# dil lean loop: K loads coalesced (8 lanes per row) and transposed through the wave's own LDS stage with an XOR swizzle
# speedup vs baseline: 1.0306x; 1.0051x over previous
; #define LAS __attribute__((address_space(3)))
; #define GAS __attribute__((address_space(1)))
; __device__ __forceinline__ void dil_unit(LAS unsigned char* lds, bf16_t* proj, int seq, int hd, int T0, int rho) {
;     int tid_ = threadIdx.x; asm volatile("" : "+v"(tid_));
;     const int tid = tid_, lane = tid & 63, r32 = lane & 31, hi = lane >> 5, wid = __builtin_amdgcn_readfirstlane(tid >> 6);
;     bf16_t* base = proj + (size_t)seq * SEQ * NIN;
;     LAS unsigned char* wbuf = lds + wid * 4096;
;     const LAS unsigned char* vp = wbuf + ((lane >> 4) & 1) * 32 + (lane & 3) * 8 + (4 * hi + ((lane & 15) >> 2)) * 64;
;     const int P0 = T0 + rho;
;     bf16x8 qr[4];
; #pragma unroll
;     for (int ks = 0; ks < 4; ++ks) qr[ks] = *(const GAS bf16x8*)(base + (size_t)(P0 + 16 * r32) * NIN + PC_LQ + hd * 64 + 16 * ks + 8 * hi);
;     f32x16 o0 = {}, o1 = {}; float l = 0.f;
;     const bool bound = (T0 < 1024) || (T0 >= 15360);
; __device__ __forceinline__ void attn_phase(unsigned char* ws, int l, LAS unsigned char* lds, int G) {
;     ...
;     for (int bu = vb; bu < 1152; bu += G) {
;         const int sh = bu >> 6, rem = bu & 63, T0 = (rem >> 1) * 512, rho = (rem & 1) * 8 + wid;
;         dil_unit(lds, proj, sh / 6, sh % 6, T0, rho);
.LBB0_554:
	s_lshr_b32 s82, s33, 8
	s_mul_i32 s82, s82, 13
	s_add_i32 s82, s82, s33
	s_ashr_i32 s2, s33, 6
	s_mul_hi_i32 s7, s2, 0x2aaaaaab
	s_lshl_b32 s3, s82, 8
	s_lshr_b32 s8, s7, 31
	s_and_b32 s6, s3, 0x3e00
	s_lshl_b32 s3, s82, 3
	s_add_i32 s7, s7, s8
	s_and_b32 s3, s3, 8
	s_mul_i32 s8, s7, 6
	s_add_i32 s3, s3, s64
	s_sub_i32 s8, s2, s8
	s_mul_hi_i32 s2, s7, 0x6000000
	s_mul_i32 s7, s7, 0x6000000
	v_mov_b32_e32 v2, v154
	s_add_u32 s56, s48, s7
	s_addc_u32 s57, s49, s2
	v_and_b32_e32 v105, 31, v2
	s_add_i32 s76, s3, s6
	v_lshl_add_u32 v3, v105, 4, s76
	v_mov_b64_e32 v[0:1], s[56:57]
	s_lshl_b32 s58, s8, 6
	v_bfe_u32 v106, v2, 5, 1
	v_mad_u64_u32 v[0:1], s[2:3], v3, s65, v[0:1]
	s_ashr_i32 s59, s58, 31
	v_lshl_add_u64 v[0:1], s[58:59], 1, v[0:1]
	v_lshlrev_b32_e32 v80, 4, v106
	v_lshl_add_u64 v[0:1], v[0:1], 0, v[80:81]
	global_load_dwordx4 v[48:51], v[0:1], off offset:1280
	global_load_dwordx4 v[52:55], v[0:1], off offset:1312
	global_load_dwordx4 v[56:59], v[0:1], off offset:1344
	global_load_dwordx4 v[60:63], v[0:1], off offset:1376
	v_readfirstlane_b32 s2, v2
	s_lshl_b32 s2, s2, 6
	s_and_b32 s2, s2, 0xfffff000
	v_lshlrev_b32_e32 v0, 1, v2
	v_lshlrev_b32_e32 v104, 3, v2
	v_lshlrev_b32_e32 v107, 2, v106
	v_lshrrev_b32_e32 v1, 2, v2
	v_and_b32_e32 v103, 63, v2
	v_and_b32_e32 v0, 32, v0
	v_and_b32_e32 v98, 24, v104
	v_and_or_b32 v1, v1, 3, v107
	s_add_i32 s77, s2, 0
	v_lshlrev_b32_e32 v108, 6, v1
	v_lshlrev_b32_e32 v1, 3, v106
	v_add3_u32 v109, s77, v0, v98
	s_addk_i32 s6, 0xc400
	v_lshrrev_b32_e32 v110, 2, v103
	v_lshlrev_b32_e32 v0, 4, v103
	s_mov_b64 s[2:3], -1
	s_cmp_gt_u32 s6, 0xffffc7ff
	v_lshlrev_b32_e32 v100, 1, v98
	s_mul_i32 s6, s8, 0x1c00
	v_lshlrev_b32_e32 v82, 1, v1
	v_or_b32_e32 v111, 16, v110
	v_add_u32_e32 v112, s77, v0
	s_cbranch_scc0 .LBB0_558
	s_movk_i32 s100, 0x1800
	s_add_i32 s101, s6, 0x15c00
	s_lshl_b32 s90, s58, 1
	s_add_u32 s82, s56, s90
	s_addc_u32 s83, s57, 0
	s_add_u32 s82, s82, 0x1200
	s_addc_u32 s83, s83, 0
	s_sub_i32 s90, s76, 64
	s_mul_i32 s90, s90, 0x1800
	s_add_u32 s84, s82, s90
	s_addc_u32 s85, s83, 0
	s_sub_i32 s90, s76, 256
	s_mul_i32 s90, s90, 0x1800
	s_add_u32 s86, s82, s90
	s_addc_u32 s87, s83, 0
	s_sub_i32 s90, s76, 1024
	s_mul_i32 s90, s90, 0x1800
	s_add_u32 s88, s82, s90
	s_addc_u32 s89, s83, 0
	v_lshlrev_b32_e32 v153, 1, v98
	v_mad_u32_u24 v80, v105, s100, v82
	v_mad_u32_u24 v100, v110, s100, v153
	v_add_u32_e32 v149, 0x18000, v100
	v_lshlrev_b32_e32 v83, 2, v105
	v_mad_u32_u24 v83, v83, s100, v82
	v_lshlrev_b32_e32 v101, 2, v110
	v_mad_u32_u24 v101, v101, s100, v153
	v_add_u32_e32 v150, 0x60000, v101
	v_lshlrev_b32_e32 v99, 4, v105
	v_mad_u32_u24 v99, v99, s100, v82
	v_lshlrev_b32_e32 v148, 4, v110
	v_mad_u32_u24 v148, v148, s100, v153
	v_add_u32_e32 v151, 0x180000, v148
	v_lshrrev_b32_e32 v249, 3, v103
	v_and_b32_e32 v250, 7, v103
	v_lshlrev_b32_e32 v250, 4, v250
	v_add_u32_e32 v235, 0, v249
	v_mad_u32_u24 v235, v235, s100, v250
	v_add_u32_e32 v236, 8, v249
	v_mad_u32_u24 v236, v236, s100, v250
	v_add_u32_e32 v237, 16, v249
	v_mad_u32_u24 v237, v237, s100, v250
	v_add_u32_e32 v238, 24, v249
	v_mad_u32_u24 v238, v238, s100, v250
	v_add_u32_e32 v239, 0, v249
	v_lshlrev_b32_e32 v239, 2, v239
	v_mad_u32_u24 v239, v239, s100, v250
	v_add_u32_e32 v240, 8, v249
	v_lshlrev_b32_e32 v240, 2, v240
	v_mad_u32_u24 v240, v240, s100, v250
	v_add_u32_e32 v241, 16, v249
	v_lshlrev_b32_e32 v241, 2, v241
	v_mad_u32_u24 v241, v241, s100, v250
	v_add_u32_e32 v242, 24, v249
	v_lshlrev_b32_e32 v242, 2, v242
	v_mad_u32_u24 v242, v242, s100, v250
	v_add_u32_e32 v243, 0, v249
	v_lshlrev_b32_e32 v243, 4, v243
	v_mad_u32_u24 v243, v243, s100, v250
	v_add_u32_e32 v244, 8, v249
	v_lshlrev_b32_e32 v244, 4, v244
	v_mad_u32_u24 v244, v244, s100, v250
	v_add_u32_e32 v245, 16, v249
	v_lshlrev_b32_e32 v245, 4, v245
	v_mad_u32_u24 v245, v245, s100, v250
	v_add_u32_e32 v246, 24, v249
	v_lshlrev_b32_e32 v246, 4, v246
	v_mad_u32_u24 v246, v246, s100, v250
	v_and_b32_e32 v247, 7, v249
	v_lshlrev_b32_e32 v247, 4, v247
	v_xor_b32_e32 v247, v247, v112
	v_and_b32_e32 v153, 7, v105
	v_or_b32_e32 v248, 0, v106
	v_xor_b32_e32 v248, v248, v153
	v_lshlrev_b32_e32 v248, 4, v248
	v_lshl_add_u32 v248, v105, 7, v248
	v_add_u32_e32 v248, s77, v248
	v_or_b32_e32 v249, 2, v106
	v_xor_b32_e32 v249, v249, v153
	v_lshlrev_b32_e32 v249, 4, v249
	v_lshl_add_u32 v249, v105, 7, v249
	v_add_u32_e32 v249, s77, v249
	v_or_b32_e32 v250, 4, v106
	v_xor_b32_e32 v250, v250, v153
	v_lshlrev_b32_e32 v250, 4, v250
	v_lshl_add_u32 v250, v105, 7, v250
	v_add_u32_e32 v250, s77, v250
	v_or_b32_e32 v251, 6, v106
	v_xor_b32_e32 v251, v251, v153
	v_lshlrev_b32_e32 v251, 4, v251
	v_lshl_add_u32 v251, v105, 7, v251
	v_add_u32_e32 v251, s77, v251
	v_lshlrev_b32_e32 v153, 1, v98
	v_mul_u32_u24_e32 v228, 17, v105
	v_sub_u32_e32 v228, v107, v228
	s_mul_i32 s90, s58, 153
	s_lshr_b32 s90, s90, 1
	s_add_i32 s90, s90, 34876
	v_lshl_add_u32 v228, v228, 2, s90
	v_lshlrev_b32_e32 v229, 2, v105
	v_sub_u32_e32 v229, v107, v229
	s_add_i32 s90, s101, 5104
	v_lshl_add_u32 v229, v229, 2, s90
	v_sub_u32_e32 v230, v107, v105
	s_add_i32 s90, s101, 6364
	v_lshl_add_u32 v230, v230, 2, s90
	v_add_u32_e32 v231, v109, v108
	v_mov_b64_e32 v[232:233], 0
	v_mov_b64_e32 v[0:1], 0
	v_mov_b64_e32 v[2:3], 0
	v_mov_b64_e32 v[4:5], 0
	v_mov_b64_e32 v[6:7], 0
	v_mov_b64_e32 v[8:9], 0
	v_mov_b64_e32 v[10:11], 0
	v_mov_b64_e32 v[12:13], 0
	v_mov_b64_e32 v[14:15], 0
	v_mov_b64_e32 v[16:17], 0
	v_mov_b64_e32 v[18:19], 0
	v_mov_b64_e32 v[20:21], 0
	v_mov_b64_e32 v[22:23], 0
	v_mov_b64_e32 v[24:25], 0
	v_mov_b64_e32 v[26:27], 0
	v_mov_b64_e32 v[28:29], 0
	v_mov_b64_e32 v[30:31], 0
	global_load_dwordx4 v[116:119], v235, s[84:85]
	global_load_dwordx4 v[120:123], v236, s[84:85]
	global_load_dwordx4 v[124:127], v237, s[84:85]
	global_load_dwordx4 v[128:131], v238, s[84:85]
	global_load_dwordx4 v[132:135], v100, s[84:85] offset:768
	global_load_dwordx4 v[136:139], v149, s[84:85] offset:768
	global_load_dwordx4 v[140:143], v100, s[84:85] offset:832
	global_load_dwordx4 v[144:147], v149, s[84:85] offset:832
	s_add_u32 s84, s84, 0x30000
	s_addc_u32 s85, s85, 0
	global_load_dwordx4 v[156:159], v235, s[84:85]
	global_load_dwordx4 v[160:163], v236, s[84:85]
	global_load_dwordx4 v[164:167], v237, s[84:85]
	global_load_dwordx4 v[168:171], v238, s[84:85]
	global_load_dwordx4 v[172:175], v100, s[84:85] offset:768
	global_load_dwordx4 v[176:179], v149, s[84:85] offset:768
	global_load_dwordx4 v[180:183], v100, s[84:85] offset:832
	global_load_dwordx4 v[184:187], v149, s[84:85] offset:832
	s_add_u32 s84, s84, 0x30000
	s_addc_u32 s85, s85, 0
	global_load_dwordx4 v[188:191], v235, s[84:85]
	global_load_dwordx4 v[192:195], v236, s[84:85]
	global_load_dwordx4 v[196:199], v237, s[84:85]
	global_load_dwordx4 v[200:203], v238, s[84:85]
	global_load_dwordx4 v[204:207], v100, s[84:85] offset:768
	global_load_dwordx4 v[208:211], v149, s[84:85] offset:768
	global_load_dwordx4 v[212:215], v100, s[84:85] offset:832
	global_load_dwordx4 v[216:219], v149, s[84:85] offset:832
	s_add_u32 s84, s84, 0x30000
	s_addc_u32 s85, s85, 0
	s_waitcnt vmcnt(16)
	ds_write_b128 v247, v[116:119]
	ds_write_b128 v247, v[120:123] offset:1024
	ds_write_b128 v247, v[124:127] offset:2048
	ds_write_b128 v247, v[128:131] offset:3072
	ds_read_b128 v[116:119], v248
	ds_read_b128 v[120:123], v249
	ds_read_b128 v[124:127], v250
	ds_read_b128 v[128:131], v251
	ds_write_b128 v112, v[132:135]
	ds_write_b128 v112, v[136:139] offset:1024
	ds_write_b128 v112, v[140:143] offset:2048
	ds_write_b128 v112, v[144:147] offset:3072
	v_mov_b32_e32 v115, v228
	ds_read2_b32 v[32:33], v115 offset0:0 offset1:1
	ds_read2_b32 v[34:35], v115 offset0:2 offset1:3
	ds_read2_b32 v[36:37], v115 offset0:8 offset1:9
	ds_read2_b32 v[38:39], v115 offset0:10 offset1:11
	ds_read2_b32 v[40:41], v115 offset0:17 offset1:18
	ds_read2_b32 v[42:43], v115 offset0:19 offset1:20
	ds_read2_b32 v[44:45], v115 offset0:25 offset1:26
	ds_read2_b32 v[46:47], v115 offset0:27 offset1:28
	s_waitcnt lgkmcnt(0)
	v_mfma_f32_32x32x16_bf16 v[32:47], v[116:119], v[48:51], v[32:47]
	ds_read_b64_tr_b16 v[72:73], v231
	ds_read_b64_tr_b16 v[74:75], v231 offset:512
	ds_read_b64_tr_b16 v[76:77], v231 offset:2048
	ds_read_b64_tr_b16 v[78:79], v231 offset:2560
	ds_read_b64_tr_b16 v[220:221], v231 offset:1024
	ds_read_b64_tr_b16 v[222:223], v231 offset:1536
	ds_read_b64_tr_b16 v[224:225], v231 offset:3072
	ds_read_b64_tr_b16 v[226:227], v231 offset:3584
	v_mfma_f32_32x32x16_bf16 v[32:47], v[120:123], v[52:55], v[32:47]
	v_mfma_f32_32x32x16_bf16 v[32:47], v[124:127], v[56:59], v[32:47]
	v_mfma_f32_32x32x16_bf16 v[32:47], v[128:131], v[60:63], v[32:47]
	s_nop 11
	v_exp_f32_e32 v32, v32
	v_exp_f32_e32 v33, v33
	v_exp_f32_e32 v34, v34
	v_exp_f32_e32 v35, v35
	v_exp_f32_e32 v36, v36
	v_exp_f32_e32 v37, v37
	v_exp_f32_e32 v38, v38
	v_exp_f32_e32 v39, v39
	v_exp_f32_e32 v40, v40
	v_exp_f32_e32 v41, v41
	v_exp_f32_e32 v42, v42
	v_exp_f32_e32 v43, v43
	v_exp_f32_e32 v44, v44
	v_exp_f32_e32 v45, v45
	v_exp_f32_e32 v46, v46
	v_exp_f32_e32 v47, v47
	v_cvt_pk_bf16_f32 v64, v32, v33
	v_cvt_pk_bf16_f32 v65, v34, v35
	v_cvt_pk_bf16_f32 v66, v36, v37
	v_cvt_pk_bf16_f32 v67, v38, v39
	v_cvt_pk_bf16_f32 v68, v40, v41
	v_cvt_pk_bf16_f32 v69, v42, v43
	v_cvt_pk_bf16_f32 v70, v44, v45
	v_cvt_pk_bf16_f32 v71, v46, v47
	v_pk_add_f32 v[232:233], v[232:233], v[32:33]
	v_pk_add_f32 v[232:233], v[232:233], v[34:35]
	v_pk_add_f32 v[232:233], v[232:233], v[36:37]
	v_pk_add_f32 v[232:233], v[232:233], v[38:39]
	v_pk_add_f32 v[232:233], v[232:233], v[40:41]
	v_pk_add_f32 v[232:233], v[232:233], v[42:43]
	v_pk_add_f32 v[232:233], v[232:233], v[44:45]
	v_pk_add_f32 v[232:233], v[232:233], v[46:47]
	s_waitcnt lgkmcnt(0)
	v_mfma_f32_32x32x16_bf16 v[0:15], v[64:67], v[72:75], v[0:15]
	v_mfma_f32_32x32x16_bf16 v[16:31], v[64:67], v[76:79], v[16:31]
	v_mfma_f32_32x32x16_bf16 v[0:15], v[68:71], v[220:223], v[0:15]
	v_mfma_f32_32x32x16_bf16 v[16:31], v[68:71], v[224:227], v[16:31]
	global_load_dwordx4 v[116:119], v235, s[84:85]
	global_load_dwordx4 v[120:123], v236, s[84:85]
	global_load_dwordx4 v[124:127], v237, s[84:85]
	global_load_dwordx4 v[128:131], v238, s[84:85]
	global_load_dwordx4 v[132:135], v100, s[84:85] offset:768
	global_load_dwordx4 v[136:139], v149, s[84:85] offset:768
	global_load_dwordx4 v[140:143], v100, s[84:85] offset:832
	global_load_dwordx4 v[144:147], v149, s[84:85] offset:832
	s_add_u32 s84, s84, 0x30000
	s_addc_u32 s85, s85, 0
	s_waitcnt vmcnt(16)
	ds_write_b128 v247, v[156:159]
	ds_write_b128 v247, v[160:163] offset:1024
	ds_write_b128 v247, v[164:167] offset:2048
	ds_write_b128 v247, v[168:171] offset:3072
	ds_read_b128 v[156:159], v248
	ds_read_b128 v[160:163], v249
	ds_read_b128 v[164:167], v250
	ds_read_b128 v[168:171], v251
	ds_write_b128 v112, v[172:175]
	ds_write_b128 v112, v[176:179] offset:1024
	ds_write_b128 v112, v[180:183] offset:2048
	ds_write_b128 v112, v[184:187] offset:3072
	ds_read2_b32 v[32:33], v115 offset0:34 offset1:35
	ds_read2_b32 v[34:35], v115 offset0:36 offset1:37
	ds_read2_b32 v[36:37], v115 offset0:42 offset1:43
	ds_read2_b32 v[38:39], v115 offset0:44 offset1:45
	ds_read2_b32 v[40:41], v115 offset0:51 offset1:52
	ds_read2_b32 v[42:43], v115 offset0:53 offset1:54
	ds_read2_b32 v[44:45], v115 offset0:59 offset1:60
	ds_read2_b32 v[46:47], v115 offset0:61 offset1:62
	s_waitcnt lgkmcnt(0)
	v_mfma_f32_32x32x16_bf16 v[32:47], v[156:159], v[48:51], v[32:47]
	ds_read_b64_tr_b16 v[72:73], v231
	ds_read_b64_tr_b16 v[74:75], v231 offset:512
	ds_read_b64_tr_b16 v[76:77], v231 offset:2048
	ds_read_b64_tr_b16 v[78:79], v231 offset:2560
	ds_read_b64_tr_b16 v[220:221], v231 offset:1024
	ds_read_b64_tr_b16 v[222:223], v231 offset:1536
	ds_read_b64_tr_b16 v[224:225], v231 offset:3072
	ds_read_b64_tr_b16 v[226:227], v231 offset:3584
	v_mfma_f32_32x32x16_bf16 v[32:47], v[160:163], v[52:55], v[32:47]
	v_mfma_f32_32x32x16_bf16 v[32:47], v[164:167], v[56:59], v[32:47]
	v_mfma_f32_32x32x16_bf16 v[32:47], v[168:171], v[60:63], v[32:47]
	s_nop 11
	v_exp_f32_e32 v32, v32
	v_exp_f32_e32 v33, v33
	v_exp_f32_e32 v34, v34
	v_exp_f32_e32 v35, v35
	v_exp_f32_e32 v36, v36
	v_exp_f32_e32 v37, v37
	v_exp_f32_e32 v38, v38
	v_exp_f32_e32 v39, v39
	v_exp_f32_e32 v40, v40
	v_exp_f32_e32 v41, v41
	v_exp_f32_e32 v42, v42
	v_exp_f32_e32 v43, v43
	v_exp_f32_e32 v44, v44
	v_exp_f32_e32 v45, v45
	v_exp_f32_e32 v46, v46
	v_exp_f32_e32 v47, v47
	v_cvt_pk_bf16_f32 v64, v32, v33
	v_cvt_pk_bf16_f32 v65, v34, v35
	v_cvt_pk_bf16_f32 v66, v36, v37
	v_cvt_pk_bf16_f32 v67, v38, v39
	v_cvt_pk_bf16_f32 v68, v40, v41
	v_cvt_pk_bf16_f32 v69, v42, v43
	v_cvt_pk_bf16_f32 v70, v44, v45
	v_cvt_pk_bf16_f32 v71, v46, v47
	v_pk_add_f32 v[232:233], v[232:233], v[32:33]
	v_pk_add_f32 v[232:233], v[232:233], v[34:35]
	v_pk_add_f32 v[232:233], v[232:233], v[36:37]
	v_pk_add_f32 v[232:233], v[232:233], v[38:39]
	v_pk_add_f32 v[232:233], v[232:233], v[40:41]
	v_pk_add_f32 v[232:233], v[232:233], v[42:43]
	v_pk_add_f32 v[232:233], v[232:233], v[44:45]
	v_pk_add_f32 v[232:233], v[232:233], v[46:47]
	s_waitcnt lgkmcnt(0)
	v_mfma_f32_32x32x16_bf16 v[0:15], v[64:67], v[72:75], v[0:15]
	v_mfma_f32_32x32x16_bf16 v[16:31], v[64:67], v[76:79], v[16:31]
	v_mfma_f32_32x32x16_bf16 v[0:15], v[68:71], v[220:223], v[0:15]
	v_mfma_f32_32x32x16_bf16 v[16:31], v[68:71], v[224:227], v[16:31]
	global_load_dwordx4 v[156:159], v235, s[84:85]
	global_load_dwordx4 v[160:163], v236, s[84:85]
	global_load_dwordx4 v[164:167], v237, s[84:85]
	global_load_dwordx4 v[168:171], v238, s[84:85]
	global_load_dwordx4 v[172:175], v100, s[84:85] offset:768
	global_load_dwordx4 v[176:179], v149, s[84:85] offset:768
	global_load_dwordx4 v[180:183], v100, s[84:85] offset:832
	global_load_dwordx4 v[184:187], v149, s[84:85] offset:832
	s_add_u32 s84, s84, 0x30000
	s_addc_u32 s85, s85, 0
	s_waitcnt vmcnt(16)
	ds_write_b128 v247, v[188:191]
	ds_write_b128 v247, v[192:195] offset:1024
	ds_write_b128 v247, v[196:199] offset:2048
	ds_write_b128 v247, v[200:203] offset:3072
	ds_read_b128 v[188:191], v248
	ds_read_b128 v[192:195], v249
	ds_read_b128 v[196:199], v250
	ds_read_b128 v[200:203], v251
	ds_write_b128 v112, v[204:207]
	ds_write_b128 v112, v[208:211] offset:1024
	ds_write_b128 v112, v[212:215] offset:2048
	ds_write_b128 v112, v[216:219] offset:3072
	ds_read2_b32 v[32:33], v115 offset0:68 offset1:69
	ds_read2_b32 v[34:35], v115 offset0:70 offset1:71
	ds_read2_b32 v[36:37], v115 offset0:76 offset1:77
	ds_read2_b32 v[38:39], v115 offset0:78 offset1:79
	ds_read2_b32 v[40:41], v115 offset0:85 offset1:86
	ds_read2_b32 v[42:43], v115 offset0:87 offset1:88
	ds_read2_b32 v[44:45], v115 offset0:93 offset1:94
	ds_read2_b32 v[46:47], v115 offset0:95 offset1:96
	s_waitcnt lgkmcnt(0)
	v_mfma_f32_32x32x16_bf16 v[32:47], v[188:191], v[48:51], v[32:47]
	ds_read_b64_tr_b16 v[72:73], v231
	ds_read_b64_tr_b16 v[74:75], v231 offset:512
	ds_read_b64_tr_b16 v[76:77], v231 offset:2048
	ds_read_b64_tr_b16 v[78:79], v231 offset:2560
	ds_read_b64_tr_b16 v[220:221], v231 offset:1024
	ds_read_b64_tr_b16 v[222:223], v231 offset:1536
	ds_read_b64_tr_b16 v[224:225], v231 offset:3072
	ds_read_b64_tr_b16 v[226:227], v231 offset:3584
	v_mfma_f32_32x32x16_bf16 v[32:47], v[192:195], v[52:55], v[32:47]
	v_mfma_f32_32x32x16_bf16 v[32:47], v[196:199], v[56:59], v[32:47]
	v_mfma_f32_32x32x16_bf16 v[32:47], v[200:203], v[60:63], v[32:47]
	s_nop 11
	v_exp_f32_e32 v32, v32
	v_exp_f32_e32 v33, v33
	v_exp_f32_e32 v34, v34
	v_exp_f32_e32 v35, v35
	v_exp_f32_e32 v36, v36
	v_exp_f32_e32 v37, v37
	v_exp_f32_e32 v38, v38
	v_exp_f32_e32 v39, v39
	v_exp_f32_e32 v40, v40
	v_exp_f32_e32 v41, v41
	v_exp_f32_e32 v42, v42
	v_exp_f32_e32 v43, v43
	v_exp_f32_e32 v44, v44
	v_exp_f32_e32 v45, v45
	v_exp_f32_e32 v46, v46
	v_exp_f32_e32 v47, v47
	v_cvt_pk_bf16_f32 v64, v32, v33
	v_cvt_pk_bf16_f32 v65, v34, v35
	v_cvt_pk_bf16_f32 v66, v36, v37
	v_cvt_pk_bf16_f32 v67, v38, v39
	v_cvt_pk_bf16_f32 v68, v40, v41
	v_cvt_pk_bf16_f32 v69, v42, v43
	v_cvt_pk_bf16_f32 v70, v44, v45
	v_cvt_pk_bf16_f32 v71, v46, v47
	v_pk_add_f32 v[232:233], v[232:233], v[32:33]
	v_pk_add_f32 v[232:233], v[232:233], v[34:35]
	v_pk_add_f32 v[232:233], v[232:233], v[36:37]
	v_pk_add_f32 v[232:233], v[232:233], v[38:39]
	v_pk_add_f32 v[232:233], v[232:233], v[40:41]
	v_pk_add_f32 v[232:233], v[232:233], v[42:43]
	v_pk_add_f32 v[232:233], v[232:233], v[44:45]
	v_pk_add_f32 v[232:233], v[232:233], v[46:47]
	s_waitcnt lgkmcnt(0)
	v_mfma_f32_32x32x16_bf16 v[0:15], v[64:67], v[72:75], v[0:15]
	v_mfma_f32_32x32x16_bf16 v[16:31], v[64:67], v[76:79], v[16:31]
	v_mfma_f32_32x32x16_bf16 v[0:15], v[68:71], v[220:223], v[0:15]
	v_mfma_f32_32x32x16_bf16 v[16:31], v[68:71], v[224:227], v[16:31]
	global_load_dwordx4 v[188:191], v235, s[84:85]
	global_load_dwordx4 v[192:195], v236, s[84:85]
	global_load_dwordx4 v[196:199], v237, s[84:85]
	global_load_dwordx4 v[200:203], v238, s[84:85]
	global_load_dwordx4 v[204:207], v100, s[84:85] offset:768
	global_load_dwordx4 v[208:211], v149, s[84:85] offset:768
	global_load_dwordx4 v[212:215], v100, s[84:85] offset:832
	global_load_dwordx4 v[216:219], v149, s[84:85] offset:832
	s_add_u32 s84, s84, 0x30000
	s_addc_u32 s85, s85, 0
	s_waitcnt vmcnt(16)
	ds_write_b128 v247, v[116:119]
	ds_write_b128 v247, v[120:123] offset:1024
	ds_write_b128 v247, v[124:127] offset:2048
	ds_write_b128 v247, v[128:131] offset:3072
	ds_read_b128 v[116:119], v248
	ds_read_b128 v[120:123], v249
	ds_read_b128 v[124:127], v250
	ds_read_b128 v[128:131], v251
	ds_write_b128 v112, v[132:135]
	ds_write_b128 v112, v[136:139] offset:1024
	ds_write_b128 v112, v[140:143] offset:2048
	ds_write_b128 v112, v[144:147] offset:3072
	ds_read2_b32 v[32:33], v115 offset0:102 offset1:103
	ds_read2_b32 v[34:35], v115 offset0:104 offset1:105
	ds_read2_b32 v[36:37], v115 offset0:110 offset1:111
	ds_read2_b32 v[38:39], v115 offset0:112 offset1:113
	ds_read2_b32 v[40:41], v115 offset0:119 offset1:120
	ds_read2_b32 v[42:43], v115 offset0:121 offset1:122
	ds_read2_b32 v[44:45], v115 offset0:127 offset1:128
	ds_read2_b32 v[46:47], v115 offset0:129 offset1:130
	s_waitcnt lgkmcnt(0)
	v_mfma_f32_32x32x16_bf16 v[32:47], v[116:119], v[48:51], v[32:47]
	ds_read_b64_tr_b16 v[72:73], v231
	ds_read_b64_tr_b16 v[74:75], v231 offset:512
	ds_read_b64_tr_b16 v[76:77], v231 offset:2048
	ds_read_b64_tr_b16 v[78:79], v231 offset:2560
	ds_read_b64_tr_b16 v[220:221], v231 offset:1024
	ds_read_b64_tr_b16 v[222:223], v231 offset:1536
	ds_read_b64_tr_b16 v[224:225], v231 offset:3072
	ds_read_b64_tr_b16 v[226:227], v231 offset:3584
	v_mfma_f32_32x32x16_bf16 v[32:47], v[120:123], v[52:55], v[32:47]
	v_mfma_f32_32x32x16_bf16 v[32:47], v[124:127], v[56:59], v[32:47]
	v_mfma_f32_32x32x16_bf16 v[32:47], v[128:131], v[60:63], v[32:47]
	s_nop 11
	v_exp_f32_e32 v32, v32
	v_exp_f32_e32 v33, v33
	v_exp_f32_e32 v34, v34
	v_exp_f32_e32 v35, v35
	v_exp_f32_e32 v36, v36
	v_exp_f32_e32 v37, v37
	v_exp_f32_e32 v38, v38
	v_exp_f32_e32 v39, v39
	v_exp_f32_e32 v40, v40
	v_exp_f32_e32 v41, v41
	v_exp_f32_e32 v42, v42
	v_exp_f32_e32 v43, v43
	v_exp_f32_e32 v44, v44
	v_exp_f32_e32 v45, v45
	v_exp_f32_e32 v46, v46
	v_exp_f32_e32 v47, v47
	v_cvt_pk_bf16_f32 v64, v32, v33
	v_cvt_pk_bf16_f32 v65, v34, v35
	v_cvt_pk_bf16_f32 v66, v36, v37
	v_cvt_pk_bf16_f32 v67, v38, v39
	v_cvt_pk_bf16_f32 v68, v40, v41
	v_cvt_pk_bf16_f32 v69, v42, v43
	v_cvt_pk_bf16_f32 v70, v44, v45
	v_cvt_pk_bf16_f32 v71, v46, v47
	v_pk_add_f32 v[232:233], v[232:233], v[32:33]
	v_pk_add_f32 v[232:233], v[232:233], v[34:35]
	v_pk_add_f32 v[232:233], v[232:233], v[36:37]
	v_pk_add_f32 v[232:233], v[232:233], v[38:39]
	v_pk_add_f32 v[232:233], v[232:233], v[40:41]
	v_pk_add_f32 v[232:233], v[232:233], v[42:43]
	v_pk_add_f32 v[232:233], v[232:233], v[44:45]
	v_pk_add_f32 v[232:233], v[232:233], v[46:47]
	s_waitcnt lgkmcnt(0)
	v_mfma_f32_32x32x16_bf16 v[0:15], v[64:67], v[72:75], v[0:15]
	v_mfma_f32_32x32x16_bf16 v[16:31], v[64:67], v[76:79], v[16:31]
	v_mfma_f32_32x32x16_bf16 v[0:15], v[68:71], v[220:223], v[0:15]
	v_mfma_f32_32x32x16_bf16 v[16:31], v[68:71], v[224:227], v[16:31]
	global_load_dwordx4 v[116:119], v235, s[84:85]
	global_load_dwordx4 v[120:123], v236, s[84:85]
	global_load_dwordx4 v[124:127], v237, s[84:85]
	global_load_dwordx4 v[128:131], v238, s[84:85]
	global_load_dwordx4 v[132:135], v100, s[84:85] offset:768
	global_load_dwordx4 v[136:139], v149, s[84:85] offset:768
	global_load_dwordx4 v[140:143], v100, s[84:85] offset:832
	global_load_dwordx4 v[144:147], v149, s[84:85] offset:832
	s_add_u32 s84, s84, 0x30000
	s_addc_u32 s85, s85, 0
	s_waitcnt vmcnt(16)
	ds_write_b128 v247, v[156:159]
	ds_write_b128 v247, v[160:163] offset:1024
	ds_write_b128 v247, v[164:167] offset:2048
	ds_write_b128 v247, v[168:171] offset:3072
	ds_read_b128 v[156:159], v248
	ds_read_b128 v[160:163], v249
	ds_read_b128 v[164:167], v250
	ds_read_b128 v[168:171], v251
	ds_write_b128 v112, v[172:175]
	ds_write_b128 v112, v[176:179] offset:1024
	ds_write_b128 v112, v[180:183] offset:2048
	ds_write_b128 v112, v[184:187] offset:3072
	ds_read2_b32 v[32:33], v115 offset0:136 offset1:137
	ds_read2_b32 v[34:35], v115 offset0:138 offset1:139
	ds_read2_b32 v[36:37], v115 offset0:144 offset1:145
	ds_read2_b32 v[38:39], v115 offset0:146 offset1:147
	ds_read2_b32 v[40:41], v115 offset0:153 offset1:154
	ds_read2_b32 v[42:43], v115 offset0:155 offset1:156
	ds_read2_b32 v[44:45], v115 offset0:161 offset1:162
	ds_read2_b32 v[46:47], v115 offset0:163 offset1:164
	s_waitcnt lgkmcnt(0)
	v_mfma_f32_32x32x16_bf16 v[32:47], v[156:159], v[48:51], v[32:47]
	ds_read_b64_tr_b16 v[72:73], v231
	ds_read_b64_tr_b16 v[74:75], v231 offset:512
	ds_read_b64_tr_b16 v[76:77], v231 offset:2048
	ds_read_b64_tr_b16 v[78:79], v231 offset:2560
	ds_read_b64_tr_b16 v[220:221], v231 offset:1024
	ds_read_b64_tr_b16 v[222:223], v231 offset:1536
	ds_read_b64_tr_b16 v[224:225], v231 offset:3072
	ds_read_b64_tr_b16 v[226:227], v231 offset:3584
	v_mfma_f32_32x32x16_bf16 v[32:47], v[160:163], v[52:55], v[32:47]
	v_mfma_f32_32x32x16_bf16 v[32:47], v[164:167], v[56:59], v[32:47]
	v_mfma_f32_32x32x16_bf16 v[32:47], v[168:171], v[60:63], v[32:47]
	s_nop 11
	v_exp_f32_e32 v32, v32
	v_exp_f32_e32 v33, v33
	v_exp_f32_e32 v34, v34
	v_exp_f32_e32 v35, v35
	v_exp_f32_e32 v36, v36
	v_exp_f32_e32 v37, v37
	v_exp_f32_e32 v38, v38
	v_exp_f32_e32 v39, v39
	v_exp_f32_e32 v40, v40
	v_exp_f32_e32 v41, v41
	v_exp_f32_e32 v42, v42
	v_exp_f32_e32 v43, v43
	v_exp_f32_e32 v44, v44
	v_exp_f32_e32 v45, v45
	v_exp_f32_e32 v46, v46
	v_exp_f32_e32 v47, v47
	v_cvt_pk_bf16_f32 v64, v32, v33
	v_cvt_pk_bf16_f32 v65, v34, v35
	v_cvt_pk_bf16_f32 v66, v36, v37
	v_cvt_pk_bf16_f32 v67, v38, v39
	v_cvt_pk_bf16_f32 v68, v40, v41
	v_cvt_pk_bf16_f32 v69, v42, v43
	v_cvt_pk_bf16_f32 v70, v44, v45
	v_cvt_pk_bf16_f32 v71, v46, v47
	v_pk_add_f32 v[232:233], v[232:233], v[32:33]
	v_pk_add_f32 v[232:233], v[232:233], v[34:35]
	v_pk_add_f32 v[232:233], v[232:233], v[36:37]
	v_pk_add_f32 v[232:233], v[232:233], v[38:39]
	v_pk_add_f32 v[232:233], v[232:233], v[40:41]
	v_pk_add_f32 v[232:233], v[232:233], v[42:43]
	v_pk_add_f32 v[232:233], v[232:233], v[44:45]
	v_pk_add_f32 v[232:233], v[232:233], v[46:47]
	s_waitcnt lgkmcnt(0)
	v_mfma_f32_32x32x16_bf16 v[0:15], v[64:67], v[72:75], v[0:15]
	v_mfma_f32_32x32x16_bf16 v[16:31], v[64:67], v[76:79], v[16:31]
	v_mfma_f32_32x32x16_bf16 v[0:15], v[68:71], v[220:223], v[0:15]
	v_mfma_f32_32x32x16_bf16 v[16:31], v[68:71], v[224:227], v[16:31]
	global_load_dwordx4 v[156:159], v235, s[84:85]
	global_load_dwordx4 v[160:163], v236, s[84:85]
	global_load_dwordx4 v[164:167], v237, s[84:85]
	global_load_dwordx4 v[168:171], v238, s[84:85]
	global_load_dwordx4 v[172:175], v100, s[84:85] offset:768
	global_load_dwordx4 v[176:179], v149, s[84:85] offset:768
	global_load_dwordx4 v[180:183], v100, s[84:85] offset:832
	global_load_dwordx4 v[184:187], v149, s[84:85] offset:832
	s_add_u32 s84, s84, 0x30000
	s_addc_u32 s85, s85, 0
	s_waitcnt vmcnt(16)
	ds_write_b128 v247, v[188:191]
	ds_write_b128 v247, v[192:195] offset:1024
	ds_write_b128 v247, v[196:199] offset:2048
	ds_write_b128 v247, v[200:203] offset:3072
	ds_read_b128 v[188:191], v248
	ds_read_b128 v[192:195], v249
	ds_read_b128 v[196:199], v250
	ds_read_b128 v[200:203], v251
	ds_write_b128 v112, v[204:207]
	ds_write_b128 v112, v[208:211] offset:1024
	ds_write_b128 v112, v[212:215] offset:2048
	ds_write_b128 v112, v[216:219] offset:3072
	ds_read2_b32 v[32:33], v115 offset0:170 offset1:171
	ds_read2_b32 v[34:35], v115 offset0:172 offset1:173
	ds_read2_b32 v[36:37], v115 offset0:178 offset1:179
	ds_read2_b32 v[38:39], v115 offset0:180 offset1:181
	ds_read2_b32 v[40:41], v115 offset0:187 offset1:188
	ds_read2_b32 v[42:43], v115 offset0:189 offset1:190
	ds_read2_b32 v[44:45], v115 offset0:195 offset1:196
	ds_read2_b32 v[46:47], v115 offset0:197 offset1:198
	s_waitcnt lgkmcnt(0)
	v_mfma_f32_32x32x16_bf16 v[32:47], v[188:191], v[48:51], v[32:47]
	ds_read_b64_tr_b16 v[72:73], v231
	ds_read_b64_tr_b16 v[74:75], v231 offset:512
	ds_read_b64_tr_b16 v[76:77], v231 offset:2048
	ds_read_b64_tr_b16 v[78:79], v231 offset:2560
	ds_read_b64_tr_b16 v[220:221], v231 offset:1024
	ds_read_b64_tr_b16 v[222:223], v231 offset:1536
	ds_read_b64_tr_b16 v[224:225], v231 offset:3072
	ds_read_b64_tr_b16 v[226:227], v231 offset:3584
	v_mfma_f32_32x32x16_bf16 v[32:47], v[192:195], v[52:55], v[32:47]
	v_mfma_f32_32x32x16_bf16 v[32:47], v[196:199], v[56:59], v[32:47]
	v_mfma_f32_32x32x16_bf16 v[32:47], v[200:203], v[60:63], v[32:47]
	s_nop 11
	v_exp_f32_e32 v32, v32
	v_exp_f32_e32 v33, v33
	v_exp_f32_e32 v34, v34
	v_exp_f32_e32 v35, v35
	v_exp_f32_e32 v36, v36
	v_exp_f32_e32 v37, v37
	v_exp_f32_e32 v38, v38
	v_exp_f32_e32 v39, v39
	v_exp_f32_e32 v40, v40
	v_exp_f32_e32 v41, v41
	v_exp_f32_e32 v42, v42
	v_exp_f32_e32 v43, v43
	v_exp_f32_e32 v44, v44
	v_exp_f32_e32 v45, v45
	v_exp_f32_e32 v46, v46
	v_exp_f32_e32 v47, v47
	v_cvt_pk_bf16_f32 v64, v32, v33
	v_cvt_pk_bf16_f32 v65, v34, v35
	v_cvt_pk_bf16_f32 v66, v36, v37
	v_cvt_pk_bf16_f32 v67, v38, v39
	v_cvt_pk_bf16_f32 v68, v40, v41
	v_cvt_pk_bf16_f32 v69, v42, v43
	v_cvt_pk_bf16_f32 v70, v44, v45
	v_cvt_pk_bf16_f32 v71, v46, v47
	v_pk_add_f32 v[232:233], v[232:233], v[32:33]
	v_pk_add_f32 v[232:233], v[232:233], v[34:35]
	v_pk_add_f32 v[232:233], v[232:233], v[36:37]
	v_pk_add_f32 v[232:233], v[232:233], v[38:39]
	v_pk_add_f32 v[232:233], v[232:233], v[40:41]
	v_pk_add_f32 v[232:233], v[232:233], v[42:43]
	v_pk_add_f32 v[232:233], v[232:233], v[44:45]
	v_pk_add_f32 v[232:233], v[232:233], v[46:47]
	s_waitcnt lgkmcnt(0)
	v_mfma_f32_32x32x16_bf16 v[0:15], v[64:67], v[72:75], v[0:15]
	v_mfma_f32_32x32x16_bf16 v[16:31], v[64:67], v[76:79], v[16:31]
	v_mfma_f32_32x32x16_bf16 v[0:15], v[68:71], v[220:223], v[0:15]
	v_mfma_f32_32x32x16_bf16 v[16:31], v[68:71], v[224:227], v[16:31]
	global_load_dwordx4 v[188:191], v235, s[84:85]
	global_load_dwordx4 v[192:195], v236, s[84:85]
	global_load_dwordx4 v[196:199], v237, s[84:85]
	global_load_dwordx4 v[200:203], v238, s[84:85]
	global_load_dwordx4 v[204:207], v100, s[84:85] offset:768
	global_load_dwordx4 v[208:211], v149, s[84:85] offset:768
	global_load_dwordx4 v[212:215], v100, s[84:85] offset:832
	global_load_dwordx4 v[216:219], v149, s[84:85] offset:832
	s_add_u32 s84, s84, 0x30000
	s_addc_u32 s85, s85, 0
	s_waitcnt vmcnt(16)
	ds_write_b128 v247, v[116:119]
	ds_write_b128 v247, v[120:123] offset:1024
	ds_write_b128 v247, v[124:127] offset:2048
	ds_write_b128 v247, v[128:131] offset:3072
	ds_read_b128 v[116:119], v248
	ds_read_b128 v[120:123], v249
	ds_read_b128 v[124:127], v250
	ds_read_b128 v[128:131], v251
	ds_write_b128 v112, v[132:135]
	ds_write_b128 v112, v[136:139] offset:1024
	ds_write_b128 v112, v[140:143] offset:2048
	ds_write_b128 v112, v[144:147] offset:3072
	ds_read2_b32 v[32:33], v115 offset0:204 offset1:205
	ds_read2_b32 v[34:35], v115 offset0:206 offset1:207
	ds_read2_b32 v[36:37], v115 offset0:212 offset1:213
	ds_read2_b32 v[38:39], v115 offset0:214 offset1:215
	ds_read2_b32 v[40:41], v115 offset0:221 offset1:222
	ds_read2_b32 v[42:43], v115 offset0:223 offset1:224
	ds_read2_b32 v[44:45], v115 offset0:229 offset1:230
	ds_read2_b32 v[46:47], v115 offset0:231 offset1:232
	s_waitcnt lgkmcnt(0)
	v_mfma_f32_32x32x16_bf16 v[32:47], v[116:119], v[48:51], v[32:47]
	ds_read_b64_tr_b16 v[72:73], v231
	ds_read_b64_tr_b16 v[74:75], v231 offset:512
	ds_read_b64_tr_b16 v[76:77], v231 offset:2048
	ds_read_b64_tr_b16 v[78:79], v231 offset:2560
	ds_read_b64_tr_b16 v[220:221], v231 offset:1024
	ds_read_b64_tr_b16 v[222:223], v231 offset:1536
	ds_read_b64_tr_b16 v[224:225], v231 offset:3072
	ds_read_b64_tr_b16 v[226:227], v231 offset:3584
	v_mfma_f32_32x32x16_bf16 v[32:47], v[120:123], v[52:55], v[32:47]
	v_mfma_f32_32x32x16_bf16 v[32:47], v[124:127], v[56:59], v[32:47]
	v_mfma_f32_32x32x16_bf16 v[32:47], v[128:131], v[60:63], v[32:47]
	s_nop 11
	v_exp_f32_e32 v32, v32
	v_exp_f32_e32 v33, v33
	v_exp_f32_e32 v34, v34
	v_exp_f32_e32 v35, v35
	v_exp_f32_e32 v36, v36
	v_exp_f32_e32 v37, v37
	v_exp_f32_e32 v38, v38
	v_exp_f32_e32 v39, v39
	v_exp_f32_e32 v40, v40
	v_exp_f32_e32 v41, v41
	v_exp_f32_e32 v42, v42
	v_exp_f32_e32 v43, v43
	v_exp_f32_e32 v44, v44
	v_exp_f32_e32 v45, v45
	v_exp_f32_e32 v46, v46
	v_exp_f32_e32 v47, v47
	v_cvt_pk_bf16_f32 v64, v32, v33
	v_cvt_pk_bf16_f32 v65, v34, v35
	v_cvt_pk_bf16_f32 v66, v36, v37
	v_cvt_pk_bf16_f32 v67, v38, v39
	v_cvt_pk_bf16_f32 v68, v40, v41
	v_cvt_pk_bf16_f32 v69, v42, v43
	v_cvt_pk_bf16_f32 v70, v44, v45
	v_cvt_pk_bf16_f32 v71, v46, v47
	v_pk_add_f32 v[232:233], v[232:233], v[32:33]
	v_pk_add_f32 v[232:233], v[232:233], v[34:35]
	v_pk_add_f32 v[232:233], v[232:233], v[36:37]
	v_pk_add_f32 v[232:233], v[232:233], v[38:39]
	v_pk_add_f32 v[232:233], v[232:233], v[40:41]
	v_pk_add_f32 v[232:233], v[232:233], v[42:43]
	v_pk_add_f32 v[232:233], v[232:233], v[44:45]
	v_pk_add_f32 v[232:233], v[232:233], v[46:47]
	s_waitcnt lgkmcnt(0)
	v_mfma_f32_32x32x16_bf16 v[0:15], v[64:67], v[72:75], v[0:15]
	v_mfma_f32_32x32x16_bf16 v[16:31], v[64:67], v[76:79], v[16:31]
	v_mfma_f32_32x32x16_bf16 v[0:15], v[68:71], v[220:223], v[0:15]
	v_mfma_f32_32x32x16_bf16 v[16:31], v[68:71], v[224:227], v[16:31]
	global_load_dwordx4 v[116:119], v235, s[84:85]
	global_load_dwordx4 v[120:123], v236, s[84:85]
	global_load_dwordx4 v[124:127], v237, s[84:85]
	global_load_dwordx4 v[128:131], v238, s[84:85]
	global_load_dwordx4 v[132:135], v100, s[84:85] offset:768
	global_load_dwordx4 v[136:139], v149, s[84:85] offset:768
	global_load_dwordx4 v[140:143], v100, s[84:85] offset:832
	global_load_dwordx4 v[144:147], v149, s[84:85] offset:832
	s_add_u32 s84, s84, 0x30000
	s_addc_u32 s85, s85, 0
	s_waitcnt vmcnt(16)
	ds_write_b128 v247, v[156:159]
	ds_write_b128 v247, v[160:163] offset:1024
	ds_write_b128 v247, v[164:167] offset:2048
	ds_write_b128 v247, v[168:171] offset:3072
	ds_read_b128 v[156:159], v248
	ds_read_b128 v[160:163], v249
	ds_read_b128 v[164:167], v250
	ds_read_b128 v[168:171], v251
	ds_write_b128 v112, v[172:175]
	ds_write_b128 v112, v[176:179] offset:1024
	ds_write_b128 v112, v[180:183] offset:2048
	ds_write_b128 v112, v[184:187] offset:3072
	v_add_u32_e32 v115, 952, v115
	ds_read2_b32 v[32:33], v115 offset0:0 offset1:1
	ds_read2_b32 v[34:35], v115 offset0:2 offset1:3
	ds_read2_b32 v[36:37], v115 offset0:8 offset1:9
	ds_read2_b32 v[38:39], v115 offset0:10 offset1:11
	ds_read2_b32 v[40:41], v115 offset0:17 offset1:18
	ds_read2_b32 v[42:43], v115 offset0:19 offset1:20
	ds_read2_b32 v[44:45], v115 offset0:25 offset1:26
	ds_read2_b32 v[46:47], v115 offset0:27 offset1:28
	s_waitcnt lgkmcnt(0)
	v_mfma_f32_32x32x16_bf16 v[32:47], v[156:159], v[48:51], v[32:47]
	ds_read_b64_tr_b16 v[72:73], v231
	ds_read_b64_tr_b16 v[74:75], v231 offset:512
	ds_read_b64_tr_b16 v[76:77], v231 offset:2048
	ds_read_b64_tr_b16 v[78:79], v231 offset:2560
	ds_read_b64_tr_b16 v[220:221], v231 offset:1024
	ds_read_b64_tr_b16 v[222:223], v231 offset:1536
	ds_read_b64_tr_b16 v[224:225], v231 offset:3072
	ds_read_b64_tr_b16 v[226:227], v231 offset:3584
	v_mfma_f32_32x32x16_bf16 v[32:47], v[160:163], v[52:55], v[32:47]
	v_mfma_f32_32x32x16_bf16 v[32:47], v[164:167], v[56:59], v[32:47]
	v_mfma_f32_32x32x16_bf16 v[32:47], v[168:171], v[60:63], v[32:47]
	s_nop 11
	v_exp_f32_e32 v32, v32
	v_exp_f32_e32 v33, v33
	v_exp_f32_e32 v34, v34
	v_exp_f32_e32 v35, v35
	v_exp_f32_e32 v36, v36
	v_exp_f32_e32 v37, v37
	v_exp_f32_e32 v38, v38
	v_exp_f32_e32 v39, v39
	v_exp_f32_e32 v40, v40
	v_exp_f32_e32 v41, v41
	v_exp_f32_e32 v42, v42
	v_exp_f32_e32 v43, v43
	v_exp_f32_e32 v44, v44
	v_exp_f32_e32 v45, v45
	v_exp_f32_e32 v46, v46
	v_exp_f32_e32 v47, v47
	v_cvt_pk_bf16_f32 v64, v32, v33
	v_cvt_pk_bf16_f32 v65, v34, v35
	v_cvt_pk_bf16_f32 v66, v36, v37
	v_cvt_pk_bf16_f32 v67, v38, v39
	v_cvt_pk_bf16_f32 v68, v40, v41
	v_cvt_pk_bf16_f32 v69, v42, v43
	v_cvt_pk_bf16_f32 v70, v44, v45
	v_cvt_pk_bf16_f32 v71, v46, v47
	v_pk_add_f32 v[232:233], v[232:233], v[32:33]
	v_pk_add_f32 v[232:233], v[232:233], v[34:35]
	v_pk_add_f32 v[232:233], v[232:233], v[36:37]
	v_pk_add_f32 v[232:233], v[232:233], v[38:39]
	v_pk_add_f32 v[232:233], v[232:233], v[40:41]
	v_pk_add_f32 v[232:233], v[232:233], v[42:43]
	v_pk_add_f32 v[232:233], v[232:233], v[44:45]
	v_pk_add_f32 v[232:233], v[232:233], v[46:47]
	s_waitcnt lgkmcnt(0)
	v_mfma_f32_32x32x16_bf16 v[0:15], v[64:67], v[72:75], v[0:15]
	v_mfma_f32_32x32x16_bf16 v[16:31], v[64:67], v[76:79], v[16:31]
	v_mfma_f32_32x32x16_bf16 v[0:15], v[68:71], v[220:223], v[0:15]
	v_mfma_f32_32x32x16_bf16 v[16:31], v[68:71], v[224:227], v[16:31]
	global_load_dwordx4 v[156:159], v235, s[84:85]
	global_load_dwordx4 v[160:163], v236, s[84:85]
	global_load_dwordx4 v[164:167], v237, s[84:85]
	global_load_dwordx4 v[168:171], v238, s[84:85]
	global_load_dwordx4 v[172:175], v100, s[84:85] offset:768
	global_load_dwordx4 v[176:179], v149, s[84:85] offset:768
	global_load_dwordx4 v[180:183], v100, s[84:85] offset:832
	global_load_dwordx4 v[184:187], v149, s[84:85] offset:832
	s_add_u32 s84, s84, 0x30000
	s_addc_u32 s85, s85, 0
	s_waitcnt vmcnt(16)
	ds_write_b128 v247, v[188:191]
	ds_write_b128 v247, v[192:195] offset:1024
	ds_write_b128 v247, v[196:199] offset:2048
	ds_write_b128 v247, v[200:203] offset:3072
	ds_read_b128 v[188:191], v248
	ds_read_b128 v[192:195], v249
	ds_read_b128 v[196:199], v250
	ds_read_b128 v[200:203], v251
	ds_write_b128 v112, v[204:207]
	ds_write_b128 v112, v[208:211] offset:1024
	ds_write_b128 v112, v[212:215] offset:2048
	ds_write_b128 v112, v[216:219] offset:3072
	ds_read2_b32 v[32:33], v115 offset0:34 offset1:35
	ds_read2_b32 v[34:35], v115 offset0:36 offset1:37
	ds_read2_b32 v[36:37], v115 offset0:42 offset1:43
	ds_read2_b32 v[38:39], v115 offset0:44 offset1:45
	ds_read2_b32 v[40:41], v115 offset0:51 offset1:52
	ds_read2_b32 v[42:43], v115 offset0:53 offset1:54
	ds_read2_b32 v[44:45], v115 offset0:59 offset1:60
	ds_read2_b32 v[46:47], v115 offset0:61 offset1:62
	s_waitcnt lgkmcnt(0)
	v_mfma_f32_32x32x16_bf16 v[32:47], v[188:191], v[48:51], v[32:47]
	ds_read_b64_tr_b16 v[72:73], v231
	ds_read_b64_tr_b16 v[74:75], v231 offset:512
	ds_read_b64_tr_b16 v[76:77], v231 offset:2048
	ds_read_b64_tr_b16 v[78:79], v231 offset:2560
	ds_read_b64_tr_b16 v[220:221], v231 offset:1024
	ds_read_b64_tr_b16 v[222:223], v231 offset:1536
	ds_read_b64_tr_b16 v[224:225], v231 offset:3072
	ds_read_b64_tr_b16 v[226:227], v231 offset:3584
	v_mfma_f32_32x32x16_bf16 v[32:47], v[192:195], v[52:55], v[32:47]
	v_mfma_f32_32x32x16_bf16 v[32:47], v[196:199], v[56:59], v[32:47]
	v_mfma_f32_32x32x16_bf16 v[32:47], v[200:203], v[60:63], v[32:47]
	s_nop 11
	v_exp_f32_e32 v32, v32
	v_exp_f32_e32 v33, v33
	v_exp_f32_e32 v34, v34
	v_exp_f32_e32 v35, v35
	v_exp_f32_e32 v36, v36
	v_exp_f32_e32 v37, v37
	v_exp_f32_e32 v38, v38
	v_exp_f32_e32 v39, v39
	v_exp_f32_e32 v40, v40
	v_exp_f32_e32 v41, v41
	v_exp_f32_e32 v42, v42
	v_exp_f32_e32 v43, v43
	v_exp_f32_e32 v44, v44
	v_exp_f32_e32 v45, v45
	v_exp_f32_e32 v46, v46
	v_exp_f32_e32 v47, v47
	v_cvt_pk_bf16_f32 v64, v32, v33
	v_cvt_pk_bf16_f32 v65, v34, v35
	v_cvt_pk_bf16_f32 v66, v36, v37
	v_cvt_pk_bf16_f32 v67, v38, v39
	v_cvt_pk_bf16_f32 v68, v40, v41
	v_cvt_pk_bf16_f32 v69, v42, v43
	v_cvt_pk_bf16_f32 v70, v44, v45
	v_cvt_pk_bf16_f32 v71, v46, v47
	v_pk_add_f32 v[232:233], v[232:233], v[32:33]
	v_pk_add_f32 v[232:233], v[232:233], v[34:35]
	v_pk_add_f32 v[232:233], v[232:233], v[36:37]
	v_pk_add_f32 v[232:233], v[232:233], v[38:39]
	v_pk_add_f32 v[232:233], v[232:233], v[40:41]
	v_pk_add_f32 v[232:233], v[232:233], v[42:43]
	v_pk_add_f32 v[232:233], v[232:233], v[44:45]
	v_pk_add_f32 v[232:233], v[232:233], v[46:47]
	s_waitcnt lgkmcnt(0)
	v_mfma_f32_32x32x16_bf16 v[0:15], v[64:67], v[72:75], v[0:15]
	v_mfma_f32_32x32x16_bf16 v[16:31], v[64:67], v[76:79], v[16:31]
	v_mfma_f32_32x32x16_bf16 v[0:15], v[68:71], v[220:223], v[0:15]
	v_mfma_f32_32x32x16_bf16 v[16:31], v[68:71], v[224:227], v[16:31]
	global_load_dwordx4 v[188:191], v235, s[84:85]
	global_load_dwordx4 v[192:195], v236, s[84:85]
	global_load_dwordx4 v[196:199], v237, s[84:85]
	global_load_dwordx4 v[200:203], v238, s[84:85]
	global_load_dwordx4 v[204:207], v100, s[84:85] offset:768
	global_load_dwordx4 v[208:211], v149, s[84:85] offset:768
	global_load_dwordx4 v[212:215], v100, s[84:85] offset:832
	global_load_dwordx4 v[216:219], v149, s[84:85] offset:832
	s_add_u32 s84, s84, 0x30000
	s_addc_u32 s85, s85, 0
	s_waitcnt vmcnt(16)
	ds_write_b128 v247, v[116:119]
	ds_write_b128 v247, v[120:123] offset:1024
	ds_write_b128 v247, v[124:127] offset:2048
	ds_write_b128 v247, v[128:131] offset:3072
	ds_read_b128 v[116:119], v248
	ds_read_b128 v[120:123], v249
	ds_read_b128 v[124:127], v250
	ds_read_b128 v[128:131], v251
	ds_write_b128 v112, v[132:135]
	ds_write_b128 v112, v[136:139] offset:1024
	ds_write_b128 v112, v[140:143] offset:2048
	ds_write_b128 v112, v[144:147] offset:3072
	ds_read2_b32 v[32:33], v115 offset0:68 offset1:69
	ds_read2_b32 v[34:35], v115 offset0:70 offset1:71
	ds_read2_b32 v[36:37], v115 offset0:76 offset1:77
	ds_read2_b32 v[38:39], v115 offset0:78 offset1:79
	ds_read2_b32 v[40:41], v115 offset0:85 offset1:86
	ds_read2_b32 v[42:43], v115 offset0:87 offset1:88
	ds_read2_b32 v[44:45], v115 offset0:93 offset1:94
	ds_read2_b32 v[46:47], v115 offset0:95 offset1:96
	s_waitcnt lgkmcnt(0)
	v_mfma_f32_32x32x16_bf16 v[32:47], v[116:119], v[48:51], v[32:47]
	ds_read_b64_tr_b16 v[72:73], v231
	ds_read_b64_tr_b16 v[74:75], v231 offset:512
	ds_read_b64_tr_b16 v[76:77], v231 offset:2048
	ds_read_b64_tr_b16 v[78:79], v231 offset:2560
	ds_read_b64_tr_b16 v[220:221], v231 offset:1024
	ds_read_b64_tr_b16 v[222:223], v231 offset:1536
	ds_read_b64_tr_b16 v[224:225], v231 offset:3072
	ds_read_b64_tr_b16 v[226:227], v231 offset:3584
	v_mfma_f32_32x32x16_bf16 v[32:47], v[120:123], v[52:55], v[32:47]
	v_mfma_f32_32x32x16_bf16 v[32:47], v[124:127], v[56:59], v[32:47]
	v_mfma_f32_32x32x16_bf16 v[32:47], v[128:131], v[60:63], v[32:47]
	s_nop 11
	v_exp_f32_e32 v32, v32
	v_exp_f32_e32 v33, v33
	v_exp_f32_e32 v34, v34
	v_exp_f32_e32 v35, v35
	v_exp_f32_e32 v36, v36
	v_exp_f32_e32 v37, v37
	v_exp_f32_e32 v38, v38
	v_exp_f32_e32 v39, v39
	v_exp_f32_e32 v40, v40
	v_exp_f32_e32 v41, v41
	v_exp_f32_e32 v42, v42
	v_exp_f32_e32 v43, v43
	v_exp_f32_e32 v44, v44
	v_exp_f32_e32 v45, v45
	v_exp_f32_e32 v46, v46
	v_exp_f32_e32 v47, v47
	v_cvt_pk_bf16_f32 v64, v32, v33
	v_cvt_pk_bf16_f32 v65, v34, v35
	v_cvt_pk_bf16_f32 v66, v36, v37
	v_cvt_pk_bf16_f32 v67, v38, v39
	v_cvt_pk_bf16_f32 v68, v40, v41
	v_cvt_pk_bf16_f32 v69, v42, v43
	v_cvt_pk_bf16_f32 v70, v44, v45
	v_cvt_pk_bf16_f32 v71, v46, v47
	v_pk_add_f32 v[232:233], v[232:233], v[32:33]
	v_pk_add_f32 v[232:233], v[232:233], v[34:35]
	v_pk_add_f32 v[232:233], v[232:233], v[36:37]
	v_pk_add_f32 v[232:233], v[232:233], v[38:39]
	v_pk_add_f32 v[232:233], v[232:233], v[40:41]
	v_pk_add_f32 v[232:233], v[232:233], v[42:43]
	v_pk_add_f32 v[232:233], v[232:233], v[44:45]
	v_pk_add_f32 v[232:233], v[232:233], v[46:47]
	s_waitcnt lgkmcnt(0)
	v_mfma_f32_32x32x16_bf16 v[0:15], v[64:67], v[72:75], v[0:15]
	v_mfma_f32_32x32x16_bf16 v[16:31], v[64:67], v[76:79], v[16:31]
	v_mfma_f32_32x32x16_bf16 v[0:15], v[68:71], v[220:223], v[0:15]
	v_mfma_f32_32x32x16_bf16 v[16:31], v[68:71], v[224:227], v[16:31]
	global_load_dwordx4 v[116:119], v235, s[84:85]
	global_load_dwordx4 v[120:123], v236, s[84:85]
	global_load_dwordx4 v[124:127], v237, s[84:85]
	global_load_dwordx4 v[128:131], v238, s[84:85]
	global_load_dwordx4 v[132:135], v100, s[84:85] offset:768
	global_load_dwordx4 v[136:139], v149, s[84:85] offset:768
	global_load_dwordx4 v[140:143], v100, s[84:85] offset:832
	global_load_dwordx4 v[144:147], v149, s[84:85] offset:832
	s_add_u32 s84, s84, 0x30000
	s_addc_u32 s85, s85, 0
	s_waitcnt vmcnt(16)
	ds_write_b128 v247, v[156:159]
	ds_write_b128 v247, v[160:163] offset:1024
	ds_write_b128 v247, v[164:167] offset:2048
	ds_write_b128 v247, v[168:171] offset:3072
	ds_read_b128 v[156:159], v248
	ds_read_b128 v[160:163], v249
	ds_read_b128 v[164:167], v250
	ds_read_b128 v[168:171], v251
	ds_write_b128 v112, v[172:175]
	ds_write_b128 v112, v[176:179] offset:1024
	ds_write_b128 v112, v[180:183] offset:2048
	ds_write_b128 v112, v[184:187] offset:3072
	ds_read2_b32 v[32:33], v115 offset0:102 offset1:103
	ds_read2_b32 v[34:35], v115 offset0:104 offset1:105
	ds_read2_b32 v[36:37], v115 offset0:110 offset1:111
	ds_read2_b32 v[38:39], v115 offset0:112 offset1:113
	ds_read2_b32 v[40:41], v115 offset0:119 offset1:120
	ds_read2_b32 v[42:43], v115 offset0:121 offset1:122
	ds_read2_b32 v[44:45], v115 offset0:127 offset1:128
	ds_read2_b32 v[46:47], v115 offset0:129 offset1:130
	s_waitcnt lgkmcnt(0)
	v_mfma_f32_32x32x16_bf16 v[32:47], v[156:159], v[48:51], v[32:47]
	ds_read_b64_tr_b16 v[72:73], v231
	ds_read_b64_tr_b16 v[74:75], v231 offset:512
	ds_read_b64_tr_b16 v[76:77], v231 offset:2048
	ds_read_b64_tr_b16 v[78:79], v231 offset:2560
	ds_read_b64_tr_b16 v[220:221], v231 offset:1024
	ds_read_b64_tr_b16 v[222:223], v231 offset:1536
	ds_read_b64_tr_b16 v[224:225], v231 offset:3072
	ds_read_b64_tr_b16 v[226:227], v231 offset:3584
	v_mfma_f32_32x32x16_bf16 v[32:47], v[160:163], v[52:55], v[32:47]
	v_mfma_f32_32x32x16_bf16 v[32:47], v[164:167], v[56:59], v[32:47]
	v_mfma_f32_32x32x16_bf16 v[32:47], v[168:171], v[60:63], v[32:47]
	s_nop 11
	v_exp_f32_e32 v32, v32
	v_exp_f32_e32 v33, v33
	v_exp_f32_e32 v34, v34
	v_exp_f32_e32 v35, v35
	v_exp_f32_e32 v36, v36
	v_exp_f32_e32 v37, v37
	v_exp_f32_e32 v38, v38
	v_exp_f32_e32 v39, v39
	v_exp_f32_e32 v40, v40
	v_exp_f32_e32 v41, v41
	v_exp_f32_e32 v42, v42
	v_exp_f32_e32 v43, v43
	v_exp_f32_e32 v44, v44
	v_exp_f32_e32 v45, v45
	v_exp_f32_e32 v46, v46
	v_exp_f32_e32 v47, v47
	v_cvt_pk_bf16_f32 v64, v32, v33
	v_cvt_pk_bf16_f32 v65, v34, v35
	v_cvt_pk_bf16_f32 v66, v36, v37
	v_cvt_pk_bf16_f32 v67, v38, v39
	v_cvt_pk_bf16_f32 v68, v40, v41
	v_cvt_pk_bf16_f32 v69, v42, v43
	v_cvt_pk_bf16_f32 v70, v44, v45
	v_cvt_pk_bf16_f32 v71, v46, v47
	v_pk_add_f32 v[232:233], v[232:233], v[32:33]
	v_pk_add_f32 v[232:233], v[232:233], v[34:35]
	v_pk_add_f32 v[232:233], v[232:233], v[36:37]
	v_pk_add_f32 v[232:233], v[232:233], v[38:39]
	v_pk_add_f32 v[232:233], v[232:233], v[40:41]
	v_pk_add_f32 v[232:233], v[232:233], v[42:43]
	v_pk_add_f32 v[232:233], v[232:233], v[44:45]
	v_pk_add_f32 v[232:233], v[232:233], v[46:47]
	s_waitcnt lgkmcnt(0)
	v_mfma_f32_32x32x16_bf16 v[0:15], v[64:67], v[72:75], v[0:15]
	v_mfma_f32_32x32x16_bf16 v[16:31], v[64:67], v[76:79], v[16:31]
	v_mfma_f32_32x32x16_bf16 v[0:15], v[68:71], v[220:223], v[0:15]
	v_mfma_f32_32x32x16_bf16 v[16:31], v[68:71], v[224:227], v[16:31]
	global_load_dwordx4 v[156:159], v235, s[84:85]
	global_load_dwordx4 v[160:163], v236, s[84:85]
	global_load_dwordx4 v[164:167], v237, s[84:85]
	global_load_dwordx4 v[168:171], v238, s[84:85]
	global_load_dwordx4 v[172:175], v100, s[84:85] offset:768
	global_load_dwordx4 v[176:179], v149, s[84:85] offset:768
	global_load_dwordx4 v[180:183], v100, s[84:85] offset:832
	global_load_dwordx4 v[184:187], v149, s[84:85] offset:832
	s_add_u32 s84, s84, 0x30000
	s_addc_u32 s85, s85, 0
	s_waitcnt vmcnt(16)
	ds_write_b128 v247, v[188:191]
	ds_write_b128 v247, v[192:195] offset:1024
	ds_write_b128 v247, v[196:199] offset:2048
	ds_write_b128 v247, v[200:203] offset:3072
	ds_read_b128 v[188:191], v248
	ds_read_b128 v[192:195], v249
	ds_read_b128 v[196:199], v250
	ds_read_b128 v[200:203], v251
	ds_write_b128 v112, v[204:207]
	ds_write_b128 v112, v[208:211] offset:1024
	ds_write_b128 v112, v[212:215] offset:2048
	ds_write_b128 v112, v[216:219] offset:3072
	ds_read2_b32 v[32:33], v115 offset0:136 offset1:137
	ds_read2_b32 v[34:35], v115 offset0:138 offset1:139
	ds_read2_b32 v[36:37], v115 offset0:144 offset1:145
	ds_read2_b32 v[38:39], v115 offset0:146 offset1:147
	ds_read2_b32 v[40:41], v115 offset0:153 offset1:154
	ds_read2_b32 v[42:43], v115 offset0:155 offset1:156
	ds_read2_b32 v[44:45], v115 offset0:161 offset1:162
	ds_read2_b32 v[46:47], v115 offset0:163 offset1:164
	s_waitcnt lgkmcnt(0)
	v_mfma_f32_32x32x16_bf16 v[32:47], v[188:191], v[48:51], v[32:47]
	ds_read_b64_tr_b16 v[72:73], v231
	ds_read_b64_tr_b16 v[74:75], v231 offset:512
	ds_read_b64_tr_b16 v[76:77], v231 offset:2048
	ds_read_b64_tr_b16 v[78:79], v231 offset:2560
	ds_read_b64_tr_b16 v[220:221], v231 offset:1024
	ds_read_b64_tr_b16 v[222:223], v231 offset:1536
	ds_read_b64_tr_b16 v[224:225], v231 offset:3072
	ds_read_b64_tr_b16 v[226:227], v231 offset:3584
	v_mfma_f32_32x32x16_bf16 v[32:47], v[192:195], v[52:55], v[32:47]
	v_mfma_f32_32x32x16_bf16 v[32:47], v[196:199], v[56:59], v[32:47]
	v_mfma_f32_32x32x16_bf16 v[32:47], v[200:203], v[60:63], v[32:47]
	s_nop 11
	v_exp_f32_e32 v32, v32
	v_exp_f32_e32 v33, v33
	v_exp_f32_e32 v34, v34
	v_exp_f32_e32 v35, v35
	v_exp_f32_e32 v36, v36
	v_exp_f32_e32 v37, v37
	v_exp_f32_e32 v38, v38
	v_exp_f32_e32 v39, v39
	v_exp_f32_e32 v40, v40
	v_exp_f32_e32 v41, v41
	v_exp_f32_e32 v42, v42
	v_exp_f32_e32 v43, v43
	v_exp_f32_e32 v44, v44
	v_exp_f32_e32 v45, v45
	v_exp_f32_e32 v46, v46
	v_exp_f32_e32 v47, v47
	v_cvt_pk_bf16_f32 v64, v32, v33
	v_cvt_pk_bf16_f32 v65, v34, v35
	v_cvt_pk_bf16_f32 v66, v36, v37
	v_cvt_pk_bf16_f32 v67, v38, v39
	v_cvt_pk_bf16_f32 v68, v40, v41
	v_cvt_pk_bf16_f32 v69, v42, v43
	v_cvt_pk_bf16_f32 v70, v44, v45
	v_cvt_pk_bf16_f32 v71, v46, v47
	v_pk_add_f32 v[232:233], v[232:233], v[32:33]
	v_pk_add_f32 v[232:233], v[232:233], v[34:35]
	v_pk_add_f32 v[232:233], v[232:233], v[36:37]
	v_pk_add_f32 v[232:233], v[232:233], v[38:39]
	v_pk_add_f32 v[232:233], v[232:233], v[40:41]
	v_pk_add_f32 v[232:233], v[232:233], v[42:43]
	v_pk_add_f32 v[232:233], v[232:233], v[44:45]
	v_pk_add_f32 v[232:233], v[232:233], v[46:47]
	s_waitcnt lgkmcnt(0)
	v_mfma_f32_32x32x16_bf16 v[0:15], v[64:67], v[72:75], v[0:15]
	v_mfma_f32_32x32x16_bf16 v[16:31], v[64:67], v[76:79], v[16:31]
	v_mfma_f32_32x32x16_bf16 v[0:15], v[68:71], v[220:223], v[0:15]
	v_mfma_f32_32x32x16_bf16 v[16:31], v[68:71], v[224:227], v[16:31]
	global_load_dwordx4 v[188:191], v235, s[84:85]
	global_load_dwordx4 v[192:195], v236, s[84:85]
	global_load_dwordx4 v[196:199], v237, s[84:85]
	global_load_dwordx4 v[200:203], v238, s[84:85]
	global_load_dwordx4 v[204:207], v100, s[84:85] offset:768
	global_load_dwordx4 v[208:211], v149, s[84:85] offset:768
	global_load_dwordx4 v[212:215], v100, s[84:85] offset:832
	global_load_dwordx4 v[216:219], v149, s[84:85] offset:832
	s_add_u32 s84, s84, 0x30000
	s_addc_u32 s85, s85, 0
	s_waitcnt vmcnt(16)
	ds_write_b128 v247, v[116:119]
	ds_write_b128 v247, v[120:123] offset:1024
	ds_write_b128 v247, v[124:127] offset:2048
	ds_write_b128 v247, v[128:131] offset:3072
	ds_read_b128 v[116:119], v248
	ds_read_b128 v[120:123], v249
	ds_read_b128 v[124:127], v250
	ds_read_b128 v[128:131], v251
	ds_write_b128 v112, v[132:135]
	ds_write_b128 v112, v[136:139] offset:1024
	ds_write_b128 v112, v[140:143] offset:2048
	ds_write_b128 v112, v[144:147] offset:3072
	ds_read2_b32 v[32:33], v115 offset0:170 offset1:171
	ds_read2_b32 v[34:35], v115 offset0:172 offset1:173
	ds_read2_b32 v[36:37], v115 offset0:178 offset1:179
	ds_read2_b32 v[38:39], v115 offset0:180 offset1:181
	ds_read2_b32 v[40:41], v115 offset0:187 offset1:188
	ds_read2_b32 v[42:43], v115 offset0:189 offset1:190
	ds_read2_b32 v[44:45], v115 offset0:195 offset1:196
	ds_read2_b32 v[46:47], v115 offset0:197 offset1:198
	s_waitcnt lgkmcnt(0)
	v_mfma_f32_32x32x16_bf16 v[32:47], v[116:119], v[48:51], v[32:47]
	ds_read_b64_tr_b16 v[72:73], v231
	ds_read_b64_tr_b16 v[74:75], v231 offset:512
	ds_read_b64_tr_b16 v[76:77], v231 offset:2048
	ds_read_b64_tr_b16 v[78:79], v231 offset:2560
	ds_read_b64_tr_b16 v[220:221], v231 offset:1024
	ds_read_b64_tr_b16 v[222:223], v231 offset:1536
	ds_read_b64_tr_b16 v[224:225], v231 offset:3072
	ds_read_b64_tr_b16 v[226:227], v231 offset:3584
	v_mfma_f32_32x32x16_bf16 v[32:47], v[120:123], v[52:55], v[32:47]
	v_mfma_f32_32x32x16_bf16 v[32:47], v[124:127], v[56:59], v[32:47]
	v_mfma_f32_32x32x16_bf16 v[32:47], v[128:131], v[60:63], v[32:47]
	s_nop 11
	v_exp_f32_e32 v32, v32
	v_exp_f32_e32 v33, v33
	v_exp_f32_e32 v34, v34
	v_exp_f32_e32 v35, v35
	v_exp_f32_e32 v36, v36
	v_exp_f32_e32 v37, v37
	v_exp_f32_e32 v38, v38
	v_exp_f32_e32 v39, v39
	v_exp_f32_e32 v40, v40
	v_exp_f32_e32 v41, v41
	v_exp_f32_e32 v42, v42
	v_exp_f32_e32 v43, v43
	v_exp_f32_e32 v44, v44
	v_exp_f32_e32 v45, v45
	v_exp_f32_e32 v46, v46
	v_exp_f32_e32 v47, v47
	v_cvt_pk_bf16_f32 v64, v32, v33
	v_cvt_pk_bf16_f32 v65, v34, v35
	v_cvt_pk_bf16_f32 v66, v36, v37
	v_cvt_pk_bf16_f32 v67, v38, v39
	v_cvt_pk_bf16_f32 v68, v40, v41
	v_cvt_pk_bf16_f32 v69, v42, v43
	v_cvt_pk_bf16_f32 v70, v44, v45
	v_cvt_pk_bf16_f32 v71, v46, v47
	v_pk_add_f32 v[232:233], v[232:233], v[32:33]
	v_pk_add_f32 v[232:233], v[232:233], v[34:35]
	v_pk_add_f32 v[232:233], v[232:233], v[36:37]
	v_pk_add_f32 v[232:233], v[232:233], v[38:39]
	v_pk_add_f32 v[232:233], v[232:233], v[40:41]
	v_pk_add_f32 v[232:233], v[232:233], v[42:43]
	v_pk_add_f32 v[232:233], v[232:233], v[44:45]
	v_pk_add_f32 v[232:233], v[232:233], v[46:47]
	s_waitcnt lgkmcnt(0)
	v_mfma_f32_32x32x16_bf16 v[0:15], v[64:67], v[72:75], v[0:15]
	v_mfma_f32_32x32x16_bf16 v[16:31], v[64:67], v[76:79], v[16:31]
	v_mfma_f32_32x32x16_bf16 v[0:15], v[68:71], v[220:223], v[0:15]
	v_mfma_f32_32x32x16_bf16 v[16:31], v[68:71], v[224:227], v[16:31]
	global_load_dwordx4 v[116:119], v235, s[84:85]
	global_load_dwordx4 v[120:123], v236, s[84:85]
	global_load_dwordx4 v[124:127], v237, s[84:85]
	global_load_dwordx4 v[128:131], v238, s[84:85]
	global_load_dwordx4 v[132:135], v100, s[84:85] offset:768
	global_load_dwordx4 v[136:139], v149, s[84:85] offset:768
	global_load_dwordx4 v[140:143], v100, s[84:85] offset:832
	global_load_dwordx4 v[144:147], v149, s[84:85] offset:832
	s_add_u32 s84, s84, 0x30000
	s_addc_u32 s85, s85, 0
	s_waitcnt vmcnt(16)
	ds_write_b128 v247, v[156:159]
	ds_write_b128 v247, v[160:163] offset:1024
	ds_write_b128 v247, v[164:167] offset:2048
	ds_write_b128 v247, v[168:171] offset:3072
	ds_read_b128 v[156:159], v248
	ds_read_b128 v[160:163], v249
	ds_read_b128 v[164:167], v250
	ds_read_b128 v[168:171], v251
	ds_write_b128 v112, v[172:175]
	ds_write_b128 v112, v[176:179] offset:1024
	ds_write_b128 v112, v[180:183] offset:2048
	ds_write_b128 v112, v[184:187] offset:3072
	ds_read2_b32 v[32:33], v115 offset0:204 offset1:205
	ds_read2_b32 v[34:35], v115 offset0:206 offset1:207
	ds_read2_b32 v[36:37], v115 offset0:212 offset1:213
	ds_read2_b32 v[38:39], v115 offset0:214 offset1:215
	ds_read2_b32 v[40:41], v115 offset0:221 offset1:222
	ds_read2_b32 v[42:43], v115 offset0:223 offset1:224
	ds_read2_b32 v[44:45], v115 offset0:229 offset1:230
	ds_read2_b32 v[46:47], v115 offset0:231 offset1:232
	s_waitcnt lgkmcnt(0)
	v_mfma_f32_32x32x16_bf16 v[32:47], v[156:159], v[48:51], v[32:47]
	ds_read_b64_tr_b16 v[72:73], v231
	ds_read_b64_tr_b16 v[74:75], v231 offset:512
	ds_read_b64_tr_b16 v[76:77], v231 offset:2048
	ds_read_b64_tr_b16 v[78:79], v231 offset:2560
	ds_read_b64_tr_b16 v[220:221], v231 offset:1024
	ds_read_b64_tr_b16 v[222:223], v231 offset:1536
	ds_read_b64_tr_b16 v[224:225], v231 offset:3072
	ds_read_b64_tr_b16 v[226:227], v231 offset:3584
	v_mfma_f32_32x32x16_bf16 v[32:47], v[160:163], v[52:55], v[32:47]
	v_mfma_f32_32x32x16_bf16 v[32:47], v[164:167], v[56:59], v[32:47]
	v_mfma_f32_32x32x16_bf16 v[32:47], v[168:171], v[60:63], v[32:47]
	s_nop 11
	v_exp_f32_e32 v32, v32
	v_exp_f32_e32 v33, v33
	v_exp_f32_e32 v34, v34
	v_exp_f32_e32 v35, v35
	v_exp_f32_e32 v36, v36
	v_exp_f32_e32 v37, v37
	v_exp_f32_e32 v38, v38
	v_exp_f32_e32 v39, v39
	v_exp_f32_e32 v40, v40
	v_exp_f32_e32 v41, v41
	v_exp_f32_e32 v42, v42
	v_exp_f32_e32 v43, v43
	v_exp_f32_e32 v44, v44
	v_exp_f32_e32 v45, v45
	v_exp_f32_e32 v46, v46
	v_exp_f32_e32 v47, v47
	v_cvt_pk_bf16_f32 v64, v32, v33
	v_cvt_pk_bf16_f32 v65, v34, v35
	v_cvt_pk_bf16_f32 v66, v36, v37
	v_cvt_pk_bf16_f32 v67, v38, v39
	v_cvt_pk_bf16_f32 v68, v40, v41
	v_cvt_pk_bf16_f32 v69, v42, v43
	v_cvt_pk_bf16_f32 v70, v44, v45
	v_cvt_pk_bf16_f32 v71, v46, v47
	v_pk_add_f32 v[232:233], v[232:233], v[32:33]
	v_pk_add_f32 v[232:233], v[232:233], v[34:35]
	v_pk_add_f32 v[232:233], v[232:233], v[36:37]
	v_pk_add_f32 v[232:233], v[232:233], v[38:39]
	v_pk_add_f32 v[232:233], v[232:233], v[40:41]
	v_pk_add_f32 v[232:233], v[232:233], v[42:43]
	v_pk_add_f32 v[232:233], v[232:233], v[44:45]
	v_pk_add_f32 v[232:233], v[232:233], v[46:47]
	s_waitcnt lgkmcnt(0)
	v_mfma_f32_32x32x16_bf16 v[0:15], v[64:67], v[72:75], v[0:15]
	v_mfma_f32_32x32x16_bf16 v[16:31], v[64:67], v[76:79], v[16:31]
	v_mfma_f32_32x32x16_bf16 v[0:15], v[68:71], v[220:223], v[0:15]
	v_mfma_f32_32x32x16_bf16 v[16:31], v[68:71], v[224:227], v[16:31]
	global_load_dwordx4 v[156:159], v235, s[84:85]
	global_load_dwordx4 v[160:163], v236, s[84:85]
	global_load_dwordx4 v[164:167], v237, s[84:85]
	global_load_dwordx4 v[168:171], v238, s[84:85]
	global_load_dwordx4 v[172:175], v100, s[84:85] offset:768
	global_load_dwordx4 v[176:179], v149, s[84:85] offset:768
	global_load_dwordx4 v[180:183], v100, s[84:85] offset:832
	global_load_dwordx4 v[184:187], v149, s[84:85] offset:832
	s_add_u32 s84, s84, 0x30000
	s_addc_u32 s85, s85, 0
	s_waitcnt vmcnt(16)
	ds_write_b128 v247, v[188:191]
	ds_write_b128 v247, v[192:195] offset:1024
	ds_write_b128 v247, v[196:199] offset:2048
	ds_write_b128 v247, v[200:203] offset:3072
	ds_read_b128 v[188:191], v248
	ds_read_b128 v[192:195], v249
	ds_read_b128 v[196:199], v250
	ds_read_b128 v[200:203], v251
	ds_write_b128 v112, v[204:207]
	ds_write_b128 v112, v[208:211] offset:1024
	ds_write_b128 v112, v[212:215] offset:2048
	ds_write_b128 v112, v[216:219] offset:3072
	v_add_u32_e32 v115, 952, v115
	ds_read2_b32 v[32:33], v115 offset0:0 offset1:1
	ds_read2_b32 v[34:35], v115 offset0:2 offset1:3
	ds_read2_b32 v[36:37], v115 offset0:8 offset1:9
	ds_read2_b32 v[38:39], v115 offset0:10 offset1:11
	ds_read2_b32 v[40:41], v115 offset0:17 offset1:18
	ds_read2_b32 v[42:43], v115 offset0:19 offset1:20
	ds_read2_b32 v[44:45], v115 offset0:25 offset1:26
	ds_read2_b32 v[46:47], v115 offset0:27 offset1:28
	s_waitcnt lgkmcnt(0)
	v_mfma_f32_32x32x16_bf16 v[32:47], v[188:191], v[48:51], v[32:47]
	ds_read_b64_tr_b16 v[72:73], v231
	ds_read_b64_tr_b16 v[74:75], v231 offset:512
	ds_read_b64_tr_b16 v[76:77], v231 offset:2048
	ds_read_b64_tr_b16 v[78:79], v231 offset:2560
	ds_read_b64_tr_b16 v[220:221], v231 offset:1024
	ds_read_b64_tr_b16 v[222:223], v231 offset:1536
	ds_read_b64_tr_b16 v[224:225], v231 offset:3072
	ds_read_b64_tr_b16 v[226:227], v231 offset:3584
	v_mfma_f32_32x32x16_bf16 v[32:47], v[192:195], v[52:55], v[32:47]
	v_mfma_f32_32x32x16_bf16 v[32:47], v[196:199], v[56:59], v[32:47]
	v_mfma_f32_32x32x16_bf16 v[32:47], v[200:203], v[60:63], v[32:47]
	s_nop 11
	v_exp_f32_e32 v32, v32
	v_exp_f32_e32 v33, v33
	v_exp_f32_e32 v34, v34
	v_exp_f32_e32 v35, v35
	v_exp_f32_e32 v36, v36
	v_exp_f32_e32 v37, v37
	v_exp_f32_e32 v38, v38
	v_exp_f32_e32 v39, v39
	v_exp_f32_e32 v40, v40
	v_exp_f32_e32 v41, v41
	v_exp_f32_e32 v42, v42
	v_exp_f32_e32 v43, v43
	v_exp_f32_e32 v44, v44
	v_exp_f32_e32 v45, v45
	v_exp_f32_e32 v46, v46
	v_exp_f32_e32 v47, v47
	v_cvt_pk_bf16_f32 v64, v32, v33
	v_cvt_pk_bf16_f32 v65, v34, v35
	v_cvt_pk_bf16_f32 v66, v36, v37
	v_cvt_pk_bf16_f32 v67, v38, v39
	v_cvt_pk_bf16_f32 v68, v40, v41
	v_cvt_pk_bf16_f32 v69, v42, v43
	v_cvt_pk_bf16_f32 v70, v44, v45
	v_cvt_pk_bf16_f32 v71, v46, v47
	v_pk_add_f32 v[232:233], v[232:233], v[32:33]
	v_pk_add_f32 v[232:233], v[232:233], v[34:35]
	v_pk_add_f32 v[232:233], v[232:233], v[36:37]
	v_pk_add_f32 v[232:233], v[232:233], v[38:39]
	v_pk_add_f32 v[232:233], v[232:233], v[40:41]
	v_pk_add_f32 v[232:233], v[232:233], v[42:43]
	v_pk_add_f32 v[232:233], v[232:233], v[44:45]
	v_pk_add_f32 v[232:233], v[232:233], v[46:47]
	s_waitcnt lgkmcnt(0)
	v_mfma_f32_32x32x16_bf16 v[0:15], v[64:67], v[72:75], v[0:15]
	v_mfma_f32_32x32x16_bf16 v[16:31], v[64:67], v[76:79], v[16:31]
	v_mfma_f32_32x32x16_bf16 v[0:15], v[68:71], v[220:223], v[0:15]
	v_mfma_f32_32x32x16_bf16 v[16:31], v[68:71], v[224:227], v[16:31]
	global_load_dwordx4 v[188:191], v235, s[84:85]
	global_load_dwordx4 v[192:195], v236, s[84:85]
	global_load_dwordx4 v[196:199], v237, s[84:85]
	global_load_dwordx4 v[200:203], v238, s[84:85]
	global_load_dwordx4 v[204:207], v100, s[84:85] offset:768
	global_load_dwordx4 v[208:211], v149, s[84:85] offset:768
	global_load_dwordx4 v[212:215], v100, s[84:85] offset:832
	global_load_dwordx4 v[216:219], v149, s[84:85] offset:832
	s_add_u32 s84, s84, 0x30000
	s_addc_u32 s85, s85, 0
	s_waitcnt vmcnt(16)
	ds_write_b128 v247, v[116:119]
	ds_write_b128 v247, v[120:123] offset:1024
	ds_write_b128 v247, v[124:127] offset:2048
	ds_write_b128 v247, v[128:131] offset:3072
	ds_read_b128 v[116:119], v248
	ds_read_b128 v[120:123], v249
	ds_read_b128 v[124:127], v250
	ds_read_b128 v[128:131], v251
	ds_write_b128 v112, v[132:135]
	ds_write_b128 v112, v[136:139] offset:1024
	ds_write_b128 v112, v[140:143] offset:2048
	ds_write_b128 v112, v[144:147] offset:3072
	ds_read2_b32 v[32:33], v115 offset0:34 offset1:35
	ds_read2_b32 v[34:35], v115 offset0:36 offset1:37
	ds_read2_b32 v[36:37], v115 offset0:42 offset1:43
	ds_read2_b32 v[38:39], v115 offset0:44 offset1:45
	ds_read2_b32 v[40:41], v115 offset0:51 offset1:52
	ds_read2_b32 v[42:43], v115 offset0:53 offset1:54
	ds_read2_b32 v[44:45], v115 offset0:59 offset1:60
	ds_read2_b32 v[46:47], v115 offset0:61 offset1:62
	s_waitcnt lgkmcnt(0)
	v_mfma_f32_32x32x16_bf16 v[32:47], v[116:119], v[48:51], v[32:47]
	ds_read_b64_tr_b16 v[72:73], v231
	ds_read_b64_tr_b16 v[74:75], v231 offset:512
	ds_read_b64_tr_b16 v[76:77], v231 offset:2048
	ds_read_b64_tr_b16 v[78:79], v231 offset:2560
	ds_read_b64_tr_b16 v[220:221], v231 offset:1024
	ds_read_b64_tr_b16 v[222:223], v231 offset:1536
	ds_read_b64_tr_b16 v[224:225], v231 offset:3072
	ds_read_b64_tr_b16 v[226:227], v231 offset:3584
	v_mfma_f32_32x32x16_bf16 v[32:47], v[120:123], v[52:55], v[32:47]
	v_mfma_f32_32x32x16_bf16 v[32:47], v[124:127], v[56:59], v[32:47]
	v_mfma_f32_32x32x16_bf16 v[32:47], v[128:131], v[60:63], v[32:47]
	s_nop 11
	v_exp_f32_e32 v32, v32
	v_exp_f32_e32 v33, v33
	v_exp_f32_e32 v34, v34
	v_exp_f32_e32 v35, v35
	v_exp_f32_e32 v36, v36
	v_exp_f32_e32 v37, v37
	v_exp_f32_e32 v38, v38
	v_exp_f32_e32 v39, v39
	v_exp_f32_e32 v40, v40
	v_exp_f32_e32 v41, v41
	v_exp_f32_e32 v42, v42
	v_exp_f32_e32 v43, v43
	v_exp_f32_e32 v44, v44
	v_exp_f32_e32 v45, v45
	v_exp_f32_e32 v46, v46
	v_exp_f32_e32 v47, v47
	v_cvt_pk_bf16_f32 v64, v32, v33
	v_cvt_pk_bf16_f32 v65, v34, v35
	v_cvt_pk_bf16_f32 v66, v36, v37
	v_cvt_pk_bf16_f32 v67, v38, v39
	v_cvt_pk_bf16_f32 v68, v40, v41
	v_cvt_pk_bf16_f32 v69, v42, v43
	v_cvt_pk_bf16_f32 v70, v44, v45
	v_cvt_pk_bf16_f32 v71, v46, v47
	v_pk_add_f32 v[232:233], v[232:233], v[32:33]
	v_pk_add_f32 v[232:233], v[232:233], v[34:35]
	v_pk_add_f32 v[232:233], v[232:233], v[36:37]
	v_pk_add_f32 v[232:233], v[232:233], v[38:39]
	v_pk_add_f32 v[232:233], v[232:233], v[40:41]
	v_pk_add_f32 v[232:233], v[232:233], v[42:43]
	v_pk_add_f32 v[232:233], v[232:233], v[44:45]
	v_pk_add_f32 v[232:233], v[232:233], v[46:47]
	s_waitcnt lgkmcnt(0)
	v_mfma_f32_32x32x16_bf16 v[0:15], v[64:67], v[72:75], v[0:15]
	v_mfma_f32_32x32x16_bf16 v[16:31], v[64:67], v[76:79], v[16:31]
	v_mfma_f32_32x32x16_bf16 v[0:15], v[68:71], v[220:223], v[0:15]
	v_mfma_f32_32x32x16_bf16 v[16:31], v[68:71], v[224:227], v[16:31]
	global_load_dwordx4 v[116:119], v235, s[84:85]
	global_load_dwordx4 v[120:123], v236, s[84:85]
	global_load_dwordx4 v[124:127], v237, s[84:85]
	global_load_dwordx4 v[128:131], v238, s[84:85]
	global_load_dwordx4 v[132:135], v100, s[84:85] offset:768
	global_load_dwordx4 v[136:139], v149, s[84:85] offset:768
	global_load_dwordx4 v[140:143], v100, s[84:85] offset:832
	global_load_dwordx4 v[144:147], v149, s[84:85] offset:832
	s_add_u32 s84, s84, 0x30000
	s_addc_u32 s85, s85, 0
	s_waitcnt vmcnt(16)
	ds_write_b128 v247, v[156:159]
	ds_write_b128 v247, v[160:163] offset:1024
	ds_write_b128 v247, v[164:167] offset:2048
	ds_write_b128 v247, v[168:171] offset:3072
	ds_read_b128 v[156:159], v248
	ds_read_b128 v[160:163], v249
	ds_read_b128 v[164:167], v250
	ds_read_b128 v[168:171], v251
	ds_write_b128 v112, v[172:175]
	ds_write_b128 v112, v[176:179] offset:1024
	ds_write_b128 v112, v[180:183] offset:2048
	ds_write_b128 v112, v[184:187] offset:3072
	ds_read2_b32 v[32:33], v115 offset0:68 offset1:69
	ds_read2_b32 v[34:35], v115 offset0:70 offset1:71
	ds_read2_b32 v[36:37], v115 offset0:76 offset1:77
	ds_read2_b32 v[38:39], v115 offset0:78 offset1:79
	ds_read2_b32 v[40:41], v115 offset0:85 offset1:86
	ds_read2_b32 v[42:43], v115 offset0:87 offset1:88
	ds_read2_b32 v[44:45], v115 offset0:93 offset1:94
	ds_read2_b32 v[46:47], v115 offset0:95 offset1:96
	s_waitcnt lgkmcnt(0)
	v_mfma_f32_32x32x16_bf16 v[32:47], v[156:159], v[48:51], v[32:47]
	ds_read_b64_tr_b16 v[72:73], v231
	ds_read_b64_tr_b16 v[74:75], v231 offset:512
	ds_read_b64_tr_b16 v[76:77], v231 offset:2048
	ds_read_b64_tr_b16 v[78:79], v231 offset:2560
	ds_read_b64_tr_b16 v[220:221], v231 offset:1024
	ds_read_b64_tr_b16 v[222:223], v231 offset:1536
	ds_read_b64_tr_b16 v[224:225], v231 offset:3072
	ds_read_b64_tr_b16 v[226:227], v231 offset:3584
	v_mfma_f32_32x32x16_bf16 v[32:47], v[160:163], v[52:55], v[32:47]
	v_mfma_f32_32x32x16_bf16 v[32:47], v[164:167], v[56:59], v[32:47]
	v_mfma_f32_32x32x16_bf16 v[32:47], v[168:171], v[60:63], v[32:47]
	s_nop 11
	v_exp_f32_e32 v32, v32
	v_exp_f32_e32 v33, v33
	v_exp_f32_e32 v34, v34
	v_exp_f32_e32 v35, v35
	v_exp_f32_e32 v36, v36
	v_exp_f32_e32 v37, v37
	v_exp_f32_e32 v38, v38
	v_exp_f32_e32 v39, v39
	v_exp_f32_e32 v40, v40
	v_exp_f32_e32 v41, v41
	v_exp_f32_e32 v42, v42
	v_exp_f32_e32 v43, v43
	v_exp_f32_e32 v44, v44
	v_exp_f32_e32 v45, v45
	v_exp_f32_e32 v46, v46
	v_exp_f32_e32 v47, v47
	v_cvt_pk_bf16_f32 v64, v32, v33
	v_cvt_pk_bf16_f32 v65, v34, v35
	v_cvt_pk_bf16_f32 v66, v36, v37
	v_cvt_pk_bf16_f32 v67, v38, v39
	v_cvt_pk_bf16_f32 v68, v40, v41
	v_cvt_pk_bf16_f32 v69, v42, v43
	v_cvt_pk_bf16_f32 v70, v44, v45
	v_cvt_pk_bf16_f32 v71, v46, v47
	v_pk_add_f32 v[232:233], v[232:233], v[32:33]
	v_pk_add_f32 v[232:233], v[232:233], v[34:35]
	v_pk_add_f32 v[232:233], v[232:233], v[36:37]
	v_pk_add_f32 v[232:233], v[232:233], v[38:39]
	v_pk_add_f32 v[232:233], v[232:233], v[40:41]
	v_pk_add_f32 v[232:233], v[232:233], v[42:43]
	v_pk_add_f32 v[232:233], v[232:233], v[44:45]
	v_pk_add_f32 v[232:233], v[232:233], v[46:47]
	s_waitcnt lgkmcnt(0)
	v_mfma_f32_32x32x16_bf16 v[0:15], v[64:67], v[72:75], v[0:15]
	v_mfma_f32_32x32x16_bf16 v[16:31], v[64:67], v[76:79], v[16:31]
	v_mfma_f32_32x32x16_bf16 v[0:15], v[68:71], v[220:223], v[0:15]
	v_mfma_f32_32x32x16_bf16 v[16:31], v[68:71], v[224:227], v[16:31]
	global_load_dwordx4 v[156:159], v235, s[84:85]
	global_load_dwordx4 v[160:163], v236, s[84:85]
	global_load_dwordx4 v[164:167], v237, s[84:85]
	global_load_dwordx4 v[168:171], v238, s[84:85]
	global_load_dwordx4 v[172:175], v100, s[84:85] offset:768
	global_load_dwordx4 v[176:179], v149, s[84:85] offset:768
	global_load_dwordx4 v[180:183], v100, s[84:85] offset:832
	global_load_dwordx4 v[184:187], v149, s[84:85] offset:832
	s_waitcnt vmcnt(16)
	ds_write_b128 v247, v[188:191]
	ds_write_b128 v247, v[192:195] offset:1024
	ds_write_b128 v247, v[196:199] offset:2048
	ds_write_b128 v247, v[200:203] offset:3072
	ds_read_b128 v[188:191], v248
	ds_read_b128 v[192:195], v249
	ds_read_b128 v[196:199], v250
	ds_read_b128 v[200:203], v251
	ds_write_b128 v112, v[204:207]
	ds_write_b128 v112, v[208:211] offset:1024
	ds_write_b128 v112, v[212:215] offset:2048
	ds_write_b128 v112, v[216:219] offset:3072
	ds_read2_b32 v[32:33], v115 offset0:102 offset1:103
	ds_read2_b32 v[34:35], v115 offset0:104 offset1:105
	ds_read2_b32 v[36:37], v115 offset0:110 offset1:111
	ds_read2_b32 v[38:39], v115 offset0:112 offset1:113
	ds_read2_b32 v[40:41], v115 offset0:119 offset1:120
	ds_read2_b32 v[42:43], v115 offset0:121 offset1:122
	ds_read2_b32 v[44:45], v115 offset0:127 offset1:128
	ds_read2_b32 v[46:47], v115 offset0:129 offset1:130
	s_waitcnt lgkmcnt(0)
	v_mfma_f32_32x32x16_bf16 v[32:47], v[188:191], v[48:51], v[32:47]
	ds_read_b64_tr_b16 v[72:73], v231
	ds_read_b64_tr_b16 v[74:75], v231 offset:512
	ds_read_b64_tr_b16 v[76:77], v231 offset:2048
	ds_read_b64_tr_b16 v[78:79], v231 offset:2560
	ds_read_b64_tr_b16 v[220:221], v231 offset:1024
	ds_read_b64_tr_b16 v[222:223], v231 offset:1536
	ds_read_b64_tr_b16 v[224:225], v231 offset:3072
	ds_read_b64_tr_b16 v[226:227], v231 offset:3584
	v_mfma_f32_32x32x16_bf16 v[32:47], v[192:195], v[52:55], v[32:47]
	v_mfma_f32_32x32x16_bf16 v[32:47], v[196:199], v[56:59], v[32:47]
	v_mfma_f32_32x32x16_bf16 v[32:47], v[200:203], v[60:63], v[32:47]
	s_nop 11
	v_exp_f32_e32 v32, v32
	v_exp_f32_e32 v33, v33
	v_exp_f32_e32 v34, v34
	v_exp_f32_e32 v35, v35
	v_exp_f32_e32 v36, v36
	v_exp_f32_e32 v37, v37
	v_exp_f32_e32 v38, v38
	v_exp_f32_e32 v39, v39
	v_exp_f32_e32 v40, v40
	v_exp_f32_e32 v41, v41
	v_exp_f32_e32 v42, v42
	v_exp_f32_e32 v43, v43
	v_exp_f32_e32 v44, v44
	v_exp_f32_e32 v45, v45
	v_exp_f32_e32 v46, v46
	v_exp_f32_e32 v47, v47
	v_cvt_pk_bf16_f32 v64, v32, v33
	v_cvt_pk_bf16_f32 v65, v34, v35
	v_cvt_pk_bf16_f32 v66, v36, v37
	v_cvt_pk_bf16_f32 v67, v38, v39
	v_cvt_pk_bf16_f32 v68, v40, v41
	v_cvt_pk_bf16_f32 v69, v42, v43
	v_cvt_pk_bf16_f32 v70, v44, v45
	v_cvt_pk_bf16_f32 v71, v46, v47
	v_pk_add_f32 v[232:233], v[232:233], v[32:33]
	v_pk_add_f32 v[232:233], v[232:233], v[34:35]
	v_pk_add_f32 v[232:233], v[232:233], v[36:37]
	v_pk_add_f32 v[232:233], v[232:233], v[38:39]
	v_pk_add_f32 v[232:233], v[232:233], v[40:41]
	v_pk_add_f32 v[232:233], v[232:233], v[42:43]
	v_pk_add_f32 v[232:233], v[232:233], v[44:45]
	v_pk_add_f32 v[232:233], v[232:233], v[46:47]
	s_waitcnt lgkmcnt(0)
	v_mfma_f32_32x32x16_bf16 v[0:15], v[64:67], v[72:75], v[0:15]
	v_mfma_f32_32x32x16_bf16 v[16:31], v[64:67], v[76:79], v[16:31]
	v_mfma_f32_32x32x16_bf16 v[0:15], v[68:71], v[220:223], v[0:15]
	v_mfma_f32_32x32x16_bf16 v[16:31], v[68:71], v[224:227], v[16:31]
	global_load_dwordx4 v[188:191], v239, s[86:87]
	global_load_dwordx4 v[192:195], v240, s[86:87]
	global_load_dwordx4 v[196:199], v241, s[86:87]
	global_load_dwordx4 v[200:203], v242, s[86:87]
	global_load_dwordx4 v[204:207], v101, s[86:87] offset:768
	global_load_dwordx4 v[208:211], v150, s[86:87] offset:768
	global_load_dwordx4 v[212:215], v101, s[86:87] offset:832
	global_load_dwordx4 v[216:219], v150, s[86:87] offset:832
	s_add_u32 s86, s86, 0xc0000
	s_addc_u32 s87, s87, 0
	s_waitcnt vmcnt(16)
	ds_write_b128 v247, v[116:119]
	ds_write_b128 v247, v[120:123] offset:1024
	ds_write_b128 v247, v[124:127] offset:2048
	ds_write_b128 v247, v[128:131] offset:3072
	ds_read_b128 v[116:119], v248
	ds_read_b128 v[120:123], v249
	ds_read_b128 v[124:127], v250
	ds_read_b128 v[128:131], v251
	ds_write_b128 v112, v[132:135]
	ds_write_b128 v112, v[136:139] offset:1024
	ds_write_b128 v112, v[140:143] offset:2048
	ds_write_b128 v112, v[144:147] offset:3072
	ds_read2_b32 v[32:33], v115 offset0:136 offset1:137
	ds_read2_b32 v[34:35], v115 offset0:138 offset1:139
	ds_read2_b32 v[36:37], v115 offset0:144 offset1:145
	ds_read2_b32 v[38:39], v115 offset0:146 offset1:147
	ds_read2_b32 v[40:41], v115 offset0:153 offset1:154
	ds_read2_b32 v[42:43], v115 offset0:155 offset1:156
	ds_read2_b32 v[44:45], v115 offset0:161 offset1:162
	ds_read2_b32 v[46:47], v115 offset0:163 offset1:164
	s_waitcnt lgkmcnt(0)
	v_mfma_f32_32x32x16_bf16 v[32:47], v[116:119], v[48:51], v[32:47]
	ds_read_b64_tr_b16 v[72:73], v231
	ds_read_b64_tr_b16 v[74:75], v231 offset:512
	ds_read_b64_tr_b16 v[76:77], v231 offset:2048
	ds_read_b64_tr_b16 v[78:79], v231 offset:2560
	ds_read_b64_tr_b16 v[220:221], v231 offset:1024
	ds_read_b64_tr_b16 v[222:223], v231 offset:1536
	ds_read_b64_tr_b16 v[224:225], v231 offset:3072
	ds_read_b64_tr_b16 v[226:227], v231 offset:3584
	v_mfma_f32_32x32x16_bf16 v[32:47], v[120:123], v[52:55], v[32:47]
	v_mfma_f32_32x32x16_bf16 v[32:47], v[124:127], v[56:59], v[32:47]
	v_mfma_f32_32x32x16_bf16 v[32:47], v[128:131], v[60:63], v[32:47]
	s_nop 11
	v_exp_f32_e32 v32, v32
	v_exp_f32_e32 v33, v33
	v_exp_f32_e32 v34, v34
	v_exp_f32_e32 v35, v35
	v_exp_f32_e32 v36, v36
	v_exp_f32_e32 v37, v37
	v_exp_f32_e32 v38, v38
	v_exp_f32_e32 v39, v39
	v_exp_f32_e32 v40, v40
	v_exp_f32_e32 v41, v41
	v_exp_f32_e32 v42, v42
	v_exp_f32_e32 v43, v43
	v_exp_f32_e32 v44, v44
	v_exp_f32_e32 v45, v45
	v_exp_f32_e32 v46, v46
	v_exp_f32_e32 v47, v47
	v_cvt_pk_bf16_f32 v64, v32, v33
	v_cvt_pk_bf16_f32 v65, v34, v35
	v_cvt_pk_bf16_f32 v66, v36, v37
	v_cvt_pk_bf16_f32 v67, v38, v39
	v_cvt_pk_bf16_f32 v68, v40, v41
	v_cvt_pk_bf16_f32 v69, v42, v43
	v_cvt_pk_bf16_f32 v70, v44, v45
	v_cvt_pk_bf16_f32 v71, v46, v47
	v_pk_add_f32 v[232:233], v[232:233], v[32:33]
	v_pk_add_f32 v[232:233], v[232:233], v[34:35]
	v_pk_add_f32 v[232:233], v[232:233], v[36:37]
	v_pk_add_f32 v[232:233], v[232:233], v[38:39]
	v_pk_add_f32 v[232:233], v[232:233], v[40:41]
	v_pk_add_f32 v[232:233], v[232:233], v[42:43]
	v_pk_add_f32 v[232:233], v[232:233], v[44:45]
	v_pk_add_f32 v[232:233], v[232:233], v[46:47]
	s_waitcnt lgkmcnt(0)
	v_mfma_f32_32x32x16_bf16 v[0:15], v[64:67], v[72:75], v[0:15]
	v_mfma_f32_32x32x16_bf16 v[16:31], v[64:67], v[76:79], v[16:31]
	v_mfma_f32_32x32x16_bf16 v[0:15], v[68:71], v[220:223], v[0:15]
	v_mfma_f32_32x32x16_bf16 v[16:31], v[68:71], v[224:227], v[16:31]
	global_load_dwordx4 v[116:119], v239, s[86:87]
	global_load_dwordx4 v[120:123], v240, s[86:87]
	global_load_dwordx4 v[124:127], v241, s[86:87]
	global_load_dwordx4 v[128:131], v242, s[86:87]
	global_load_dwordx4 v[132:135], v101, s[86:87] offset:768
	global_load_dwordx4 v[136:139], v150, s[86:87] offset:768
	global_load_dwordx4 v[140:143], v101, s[86:87] offset:832
	global_load_dwordx4 v[144:147], v150, s[86:87] offset:832
	s_add_u32 s86, s86, 0xc0000
	s_addc_u32 s87, s87, 0
	s_waitcnt vmcnt(16)
	ds_write_b128 v247, v[156:159]
	ds_write_b128 v247, v[160:163] offset:1024
	ds_write_b128 v247, v[164:167] offset:2048
	ds_write_b128 v247, v[168:171] offset:3072
	ds_read_b128 v[156:159], v248
	ds_read_b128 v[160:163], v249
	ds_read_b128 v[164:167], v250
	ds_read_b128 v[168:171], v251
	ds_write_b128 v112, v[172:175]
	ds_write_b128 v112, v[176:179] offset:1024
	ds_write_b128 v112, v[180:183] offset:2048
	ds_write_b128 v112, v[184:187] offset:3072
	ds_read2_b32 v[32:33], v115 offset0:170 offset1:171
	ds_read2_b32 v[34:35], v115 offset0:172 offset1:173
	ds_read2_b32 v[36:37], v115 offset0:178 offset1:179
	ds_read2_b32 v[38:39], v115 offset0:180 offset1:181
	ds_read2_b32 v[40:41], v115 offset0:187 offset1:188
	ds_read2_b32 v[42:43], v115 offset0:189 offset1:190
	ds_read2_b32 v[44:45], v115 offset0:195 offset1:196
	ds_read2_b32 v[46:47], v115 offset0:197 offset1:198
	s_waitcnt lgkmcnt(0)
	v_mfma_f32_32x32x16_bf16 v[32:47], v[156:159], v[48:51], v[32:47]
	ds_read_b64_tr_b16 v[72:73], v231
	ds_read_b64_tr_b16 v[74:75], v231 offset:512
	ds_read_b64_tr_b16 v[76:77], v231 offset:2048
	ds_read_b64_tr_b16 v[78:79], v231 offset:2560
	ds_read_b64_tr_b16 v[220:221], v231 offset:1024
	ds_read_b64_tr_b16 v[222:223], v231 offset:1536
	ds_read_b64_tr_b16 v[224:225], v231 offset:3072
	ds_read_b64_tr_b16 v[226:227], v231 offset:3584
	v_mfma_f32_32x32x16_bf16 v[32:47], v[160:163], v[52:55], v[32:47]
	v_mfma_f32_32x32x16_bf16 v[32:47], v[164:167], v[56:59], v[32:47]
	v_mfma_f32_32x32x16_bf16 v[32:47], v[168:171], v[60:63], v[32:47]
	s_nop 11
	v_exp_f32_e32 v32, v32
	v_exp_f32_e32 v33, v33
	v_exp_f32_e32 v34, v34
	v_exp_f32_e32 v35, v35
	v_exp_f32_e32 v36, v36
	v_exp_f32_e32 v37, v37
	v_exp_f32_e32 v38, v38
	v_exp_f32_e32 v39, v39
	v_exp_f32_e32 v40, v40
	v_exp_f32_e32 v41, v41
	v_exp_f32_e32 v42, v42
	v_exp_f32_e32 v43, v43
	v_exp_f32_e32 v44, v44
	v_exp_f32_e32 v45, v45
	v_exp_f32_e32 v46, v46
	v_exp_f32_e32 v47, v47
	v_cvt_pk_bf16_f32 v64, v32, v33
	v_cvt_pk_bf16_f32 v65, v34, v35
	v_cvt_pk_bf16_f32 v66, v36, v37
	v_cvt_pk_bf16_f32 v67, v38, v39
	v_cvt_pk_bf16_f32 v68, v40, v41
	v_cvt_pk_bf16_f32 v69, v42, v43
	v_cvt_pk_bf16_f32 v70, v44, v45
	v_cvt_pk_bf16_f32 v71, v46, v47
	v_pk_add_f32 v[232:233], v[232:233], v[32:33]
	v_pk_add_f32 v[232:233], v[232:233], v[34:35]
	v_pk_add_f32 v[232:233], v[232:233], v[36:37]
	v_pk_add_f32 v[232:233], v[232:233], v[38:39]
	v_pk_add_f32 v[232:233], v[232:233], v[40:41]
	v_pk_add_f32 v[232:233], v[232:233], v[42:43]
	v_pk_add_f32 v[232:233], v[232:233], v[44:45]
	v_pk_add_f32 v[232:233], v[232:233], v[46:47]
	s_waitcnt lgkmcnt(0)
	v_mfma_f32_32x32x16_bf16 v[0:15], v[64:67], v[72:75], v[0:15]
	v_mfma_f32_32x32x16_bf16 v[16:31], v[64:67], v[76:79], v[16:31]
	v_mfma_f32_32x32x16_bf16 v[0:15], v[68:71], v[220:223], v[0:15]
	v_mfma_f32_32x32x16_bf16 v[16:31], v[68:71], v[224:227], v[16:31]
	global_load_dwordx4 v[156:159], v239, s[86:87]
	global_load_dwordx4 v[160:163], v240, s[86:87]
	global_load_dwordx4 v[164:167], v241, s[86:87]
	global_load_dwordx4 v[168:171], v242, s[86:87]
	global_load_dwordx4 v[172:175], v101, s[86:87] offset:768
	global_load_dwordx4 v[176:179], v150, s[86:87] offset:768
	global_load_dwordx4 v[180:183], v101, s[86:87] offset:832
	global_load_dwordx4 v[184:187], v150, s[86:87] offset:832
	s_add_u32 s86, s86, 0xc0000
	s_addc_u32 s87, s87, 0
	s_waitcnt vmcnt(16)
	ds_write_b128 v247, v[188:191]
	ds_write_b128 v247, v[192:195] offset:1024
	ds_write_b128 v247, v[196:199] offset:2048
	ds_write_b128 v247, v[200:203] offset:3072
	ds_read_b128 v[188:191], v248
	ds_read_b128 v[192:195], v249
	ds_read_b128 v[196:199], v250
	ds_read_b128 v[200:203], v251
	ds_write_b128 v112, v[204:207]
	ds_write_b128 v112, v[208:211] offset:1024
	ds_write_b128 v112, v[212:215] offset:2048
	ds_write_b128 v112, v[216:219] offset:3072
	v_mov_b32_e32 v115, v229
	ds_read2_b32 v[32:33], v115 offset0:0 offset1:1
	ds_read2_b32 v[34:35], v115 offset0:2 offset1:3
	ds_read2_b32 v[36:37], v115 offset0:8 offset1:9
	ds_read2_b32 v[38:39], v115 offset0:10 offset1:11
	ds_read2_b32 v[40:41], v115 offset0:16 offset1:17
	ds_read2_b32 v[42:43], v115 offset0:18 offset1:19
	ds_read2_b32 v[44:45], v115 offset0:24 offset1:25
	ds_read2_b32 v[46:47], v115 offset0:26 offset1:27
	s_waitcnt lgkmcnt(0)
	v_mfma_f32_32x32x16_bf16 v[32:47], v[188:191], v[48:51], v[32:47]
	ds_read_b64_tr_b16 v[72:73], v231
	ds_read_b64_tr_b16 v[74:75], v231 offset:512
	ds_read_b64_tr_b16 v[76:77], v231 offset:2048
	ds_read_b64_tr_b16 v[78:79], v231 offset:2560
	ds_read_b64_tr_b16 v[220:221], v231 offset:1024
	ds_read_b64_tr_b16 v[222:223], v231 offset:1536
	ds_read_b64_tr_b16 v[224:225], v231 offset:3072
	ds_read_b64_tr_b16 v[226:227], v231 offset:3584
	v_mfma_f32_32x32x16_bf16 v[32:47], v[192:195], v[52:55], v[32:47]
	v_mfma_f32_32x32x16_bf16 v[32:47], v[196:199], v[56:59], v[32:47]
	v_mfma_f32_32x32x16_bf16 v[32:47], v[200:203], v[60:63], v[32:47]
	s_nop 11
	v_exp_f32_e32 v32, v32
	v_exp_f32_e32 v33, v33
	v_exp_f32_e32 v34, v34
	v_exp_f32_e32 v35, v35
	v_exp_f32_e32 v36, v36
	v_exp_f32_e32 v37, v37
	v_exp_f32_e32 v38, v38
	v_exp_f32_e32 v39, v39
	v_exp_f32_e32 v40, v40
	v_exp_f32_e32 v41, v41
	v_exp_f32_e32 v42, v42
	v_exp_f32_e32 v43, v43
	v_exp_f32_e32 v44, v44
	v_exp_f32_e32 v45, v45
	v_exp_f32_e32 v46, v46
	v_exp_f32_e32 v47, v47
	v_cvt_pk_bf16_f32 v64, v32, v33
	v_cvt_pk_bf16_f32 v65, v34, v35
	v_cvt_pk_bf16_f32 v66, v36, v37
	v_cvt_pk_bf16_f32 v67, v38, v39
	v_cvt_pk_bf16_f32 v68, v40, v41
	v_cvt_pk_bf16_f32 v69, v42, v43
	v_cvt_pk_bf16_f32 v70, v44, v45
	v_cvt_pk_bf16_f32 v71, v46, v47
	v_pk_add_f32 v[232:233], v[232:233], v[32:33]
	v_pk_add_f32 v[232:233], v[232:233], v[34:35]
	v_pk_add_f32 v[232:233], v[232:233], v[36:37]
	v_pk_add_f32 v[232:233], v[232:233], v[38:39]
	v_pk_add_f32 v[232:233], v[232:233], v[40:41]
	v_pk_add_f32 v[232:233], v[232:233], v[42:43]
	v_pk_add_f32 v[232:233], v[232:233], v[44:45]
	v_pk_add_f32 v[232:233], v[232:233], v[46:47]
	s_waitcnt lgkmcnt(0)
	v_mfma_f32_32x32x16_bf16 v[0:15], v[64:67], v[72:75], v[0:15]
	v_mfma_f32_32x32x16_bf16 v[16:31], v[64:67], v[76:79], v[16:31]
	v_mfma_f32_32x32x16_bf16 v[0:15], v[68:71], v[220:223], v[0:15]
	v_mfma_f32_32x32x16_bf16 v[16:31], v[68:71], v[224:227], v[16:31]
	global_load_dwordx4 v[188:191], v239, s[86:87]
	global_load_dwordx4 v[192:195], v240, s[86:87]
	global_load_dwordx4 v[196:199], v241, s[86:87]
	global_load_dwordx4 v[200:203], v242, s[86:87]
	global_load_dwordx4 v[204:207], v101, s[86:87] offset:768
	global_load_dwordx4 v[208:211], v150, s[86:87] offset:768
	global_load_dwordx4 v[212:215], v101, s[86:87] offset:832
	global_load_dwordx4 v[216:219], v150, s[86:87] offset:832
	s_add_u32 s86, s86, 0xc0000
	s_addc_u32 s87, s87, 0
	s_waitcnt vmcnt(16)
	ds_write_b128 v247, v[116:119]
	ds_write_b128 v247, v[120:123] offset:1024
	ds_write_b128 v247, v[124:127] offset:2048
	ds_write_b128 v247, v[128:131] offset:3072
	ds_read_b128 v[116:119], v248
	ds_read_b128 v[120:123], v249
	ds_read_b128 v[124:127], v250
	ds_read_b128 v[128:131], v251
	ds_write_b128 v112, v[132:135]
	ds_write_b128 v112, v[136:139] offset:1024
	ds_write_b128 v112, v[140:143] offset:2048
	ds_write_b128 v112, v[144:147] offset:3072
	ds_read2_b32 v[32:33], v115 offset0:32 offset1:33
	ds_read2_b32 v[34:35], v115 offset0:34 offset1:35
	ds_read2_b32 v[36:37], v115 offset0:40 offset1:41
	ds_read2_b32 v[38:39], v115 offset0:42 offset1:43
	ds_read2_b32 v[40:41], v115 offset0:48 offset1:49
	ds_read2_b32 v[42:43], v115 offset0:50 offset1:51
	ds_read2_b32 v[44:45], v115 offset0:56 offset1:57
	ds_read2_b32 v[46:47], v115 offset0:58 offset1:59
	s_waitcnt lgkmcnt(0)
	v_mfma_f32_32x32x16_bf16 v[32:47], v[116:119], v[48:51], v[32:47]
	ds_read_b64_tr_b16 v[72:73], v231
	ds_read_b64_tr_b16 v[74:75], v231 offset:512
	ds_read_b64_tr_b16 v[76:77], v231 offset:2048
	ds_read_b64_tr_b16 v[78:79], v231 offset:2560
	ds_read_b64_tr_b16 v[220:221], v231 offset:1024
	ds_read_b64_tr_b16 v[222:223], v231 offset:1536
	ds_read_b64_tr_b16 v[224:225], v231 offset:3072
	ds_read_b64_tr_b16 v[226:227], v231 offset:3584
	v_mfma_f32_32x32x16_bf16 v[32:47], v[120:123], v[52:55], v[32:47]
	v_mfma_f32_32x32x16_bf16 v[32:47], v[124:127], v[56:59], v[32:47]
	v_mfma_f32_32x32x16_bf16 v[32:47], v[128:131], v[60:63], v[32:47]
	s_nop 11
	v_exp_f32_e32 v32, v32
	v_exp_f32_e32 v33, v33
	v_exp_f32_e32 v34, v34
	v_exp_f32_e32 v35, v35
	v_exp_f32_e32 v36, v36
	v_exp_f32_e32 v37, v37
	v_exp_f32_e32 v38, v38
	v_exp_f32_e32 v39, v39
	v_exp_f32_e32 v40, v40
	v_exp_f32_e32 v41, v41
	v_exp_f32_e32 v42, v42
	v_exp_f32_e32 v43, v43
	v_exp_f32_e32 v44, v44
	v_exp_f32_e32 v45, v45
	v_exp_f32_e32 v46, v46
	v_exp_f32_e32 v47, v47
	v_cvt_pk_bf16_f32 v64, v32, v33
	v_cvt_pk_bf16_f32 v65, v34, v35
	v_cvt_pk_bf16_f32 v66, v36, v37
	v_cvt_pk_bf16_f32 v67, v38, v39
	v_cvt_pk_bf16_f32 v68, v40, v41
	v_cvt_pk_bf16_f32 v69, v42, v43
	v_cvt_pk_bf16_f32 v70, v44, v45
	v_cvt_pk_bf16_f32 v71, v46, v47
	v_pk_add_f32 v[232:233], v[232:233], v[32:33]
	v_pk_add_f32 v[232:233], v[232:233], v[34:35]
	v_pk_add_f32 v[232:233], v[232:233], v[36:37]
	v_pk_add_f32 v[232:233], v[232:233], v[38:39]
	v_pk_add_f32 v[232:233], v[232:233], v[40:41]
	v_pk_add_f32 v[232:233], v[232:233], v[42:43]
	v_pk_add_f32 v[232:233], v[232:233], v[44:45]
	v_pk_add_f32 v[232:233], v[232:233], v[46:47]
	s_waitcnt lgkmcnt(0)
	v_mfma_f32_32x32x16_bf16 v[0:15], v[64:67], v[72:75], v[0:15]
	v_mfma_f32_32x32x16_bf16 v[16:31], v[64:67], v[76:79], v[16:31]
	v_mfma_f32_32x32x16_bf16 v[0:15], v[68:71], v[220:223], v[0:15]
	v_mfma_f32_32x32x16_bf16 v[16:31], v[68:71], v[224:227], v[16:31]
	global_load_dwordx4 v[116:119], v239, s[86:87]
	global_load_dwordx4 v[120:123], v240, s[86:87]
	global_load_dwordx4 v[124:127], v241, s[86:87]
	global_load_dwordx4 v[128:131], v242, s[86:87]
	global_load_dwordx4 v[132:135], v101, s[86:87] offset:768
	global_load_dwordx4 v[136:139], v150, s[86:87] offset:768
	global_load_dwordx4 v[140:143], v101, s[86:87] offset:832
	global_load_dwordx4 v[144:147], v150, s[86:87] offset:832
	s_add_u32 s86, s86, 0xc0000
	s_addc_u32 s87, s87, 0
	s_waitcnt vmcnt(16)
	ds_write_b128 v247, v[156:159]
	ds_write_b128 v247, v[160:163] offset:1024
	ds_write_b128 v247, v[164:167] offset:2048
	ds_write_b128 v247, v[168:171] offset:3072
	ds_read_b128 v[156:159], v248
	ds_read_b128 v[160:163], v249
	ds_read_b128 v[164:167], v250
	ds_read_b128 v[168:171], v251
	ds_write_b128 v112, v[172:175]
	ds_write_b128 v112, v[176:179] offset:1024
	ds_write_b128 v112, v[180:183] offset:2048
	ds_write_b128 v112, v[184:187] offset:3072
	ds_read2_b32 v[32:33], v115 offset0:64 offset1:65
	ds_read2_b32 v[34:35], v115 offset0:66 offset1:67
	ds_read2_b32 v[36:37], v115 offset0:72 offset1:73
	ds_read2_b32 v[38:39], v115 offset0:74 offset1:75
	ds_read2_b32 v[40:41], v115 offset0:80 offset1:81
	ds_read2_b32 v[42:43], v115 offset0:82 offset1:83
	ds_read2_b32 v[44:45], v115 offset0:88 offset1:89
	ds_read2_b32 v[46:47], v115 offset0:90 offset1:91
	s_waitcnt lgkmcnt(0)
	v_mfma_f32_32x32x16_bf16 v[32:47], v[156:159], v[48:51], v[32:47]
	ds_read_b64_tr_b16 v[72:73], v231
	ds_read_b64_tr_b16 v[74:75], v231 offset:512
	ds_read_b64_tr_b16 v[76:77], v231 offset:2048
	ds_read_b64_tr_b16 v[78:79], v231 offset:2560
	ds_read_b64_tr_b16 v[220:221], v231 offset:1024
	ds_read_b64_tr_b16 v[222:223], v231 offset:1536
	ds_read_b64_tr_b16 v[224:225], v231 offset:3072
	ds_read_b64_tr_b16 v[226:227], v231 offset:3584
	v_mfma_f32_32x32x16_bf16 v[32:47], v[160:163], v[52:55], v[32:47]
	v_mfma_f32_32x32x16_bf16 v[32:47], v[164:167], v[56:59], v[32:47]
	v_mfma_f32_32x32x16_bf16 v[32:47], v[168:171], v[60:63], v[32:47]
	s_nop 11
	v_exp_f32_e32 v32, v32
	v_exp_f32_e32 v33, v33
	v_exp_f32_e32 v34, v34
	v_exp_f32_e32 v35, v35
	v_exp_f32_e32 v36, v36
	v_exp_f32_e32 v37, v37
	v_exp_f32_e32 v38, v38
	v_exp_f32_e32 v39, v39
	v_exp_f32_e32 v40, v40
	v_exp_f32_e32 v41, v41
	v_exp_f32_e32 v42, v42
	v_exp_f32_e32 v43, v43
	v_exp_f32_e32 v44, v44
	v_exp_f32_e32 v45, v45
	v_exp_f32_e32 v46, v46
	v_exp_f32_e32 v47, v47
	v_cvt_pk_bf16_f32 v64, v32, v33
	v_cvt_pk_bf16_f32 v65, v34, v35
	v_cvt_pk_bf16_f32 v66, v36, v37
	v_cvt_pk_bf16_f32 v67, v38, v39
	v_cvt_pk_bf16_f32 v68, v40, v41
	v_cvt_pk_bf16_f32 v69, v42, v43
	v_cvt_pk_bf16_f32 v70, v44, v45
	v_cvt_pk_bf16_f32 v71, v46, v47
	v_pk_add_f32 v[232:233], v[232:233], v[32:33]
	v_pk_add_f32 v[232:233], v[232:233], v[34:35]
	v_pk_add_f32 v[232:233], v[232:233], v[36:37]
	v_pk_add_f32 v[232:233], v[232:233], v[38:39]
	v_pk_add_f32 v[232:233], v[232:233], v[40:41]
	v_pk_add_f32 v[232:233], v[232:233], v[42:43]
	v_pk_add_f32 v[232:233], v[232:233], v[44:45]
	v_pk_add_f32 v[232:233], v[232:233], v[46:47]
	s_waitcnt lgkmcnt(0)
	v_mfma_f32_32x32x16_bf16 v[0:15], v[64:67], v[72:75], v[0:15]
	v_mfma_f32_32x32x16_bf16 v[16:31], v[64:67], v[76:79], v[16:31]
	v_mfma_f32_32x32x16_bf16 v[0:15], v[68:71], v[220:223], v[0:15]
	v_mfma_f32_32x32x16_bf16 v[16:31], v[68:71], v[224:227], v[16:31]
	global_load_dwordx4 v[156:159], v239, s[86:87]
	global_load_dwordx4 v[160:163], v240, s[86:87]
	global_load_dwordx4 v[164:167], v241, s[86:87]
	global_load_dwordx4 v[168:171], v242, s[86:87]
	global_load_dwordx4 v[172:175], v101, s[86:87] offset:768
	global_load_dwordx4 v[176:179], v150, s[86:87] offset:768
	global_load_dwordx4 v[180:183], v101, s[86:87] offset:832
	global_load_dwordx4 v[184:187], v150, s[86:87] offset:832
	s_add_u32 s86, s86, 0xc0000
	s_addc_u32 s87, s87, 0
	s_waitcnt vmcnt(16)
	ds_write_b128 v247, v[188:191]
	ds_write_b128 v247, v[192:195] offset:1024
	ds_write_b128 v247, v[196:199] offset:2048
	ds_write_b128 v247, v[200:203] offset:3072
	ds_read_b128 v[188:191], v248
	ds_read_b128 v[192:195], v249
	ds_read_b128 v[196:199], v250
	ds_read_b128 v[200:203], v251
	ds_write_b128 v112, v[204:207]
	ds_write_b128 v112, v[208:211] offset:1024
	ds_write_b128 v112, v[212:215] offset:2048
	ds_write_b128 v112, v[216:219] offset:3072
	ds_read2_b32 v[32:33], v115 offset0:96 offset1:97
	ds_read2_b32 v[34:35], v115 offset0:98 offset1:99
	ds_read2_b32 v[36:37], v115 offset0:104 offset1:105
	ds_read2_b32 v[38:39], v115 offset0:106 offset1:107
	ds_read2_b32 v[40:41], v115 offset0:112 offset1:113
	ds_read2_b32 v[42:43], v115 offset0:114 offset1:115
	ds_read2_b32 v[44:45], v115 offset0:120 offset1:121
	ds_read2_b32 v[46:47], v115 offset0:122 offset1:123
	s_waitcnt lgkmcnt(0)
	v_mfma_f32_32x32x16_bf16 v[32:47], v[188:191], v[48:51], v[32:47]
	ds_read_b64_tr_b16 v[72:73], v231
	ds_read_b64_tr_b16 v[74:75], v231 offset:512
	ds_read_b64_tr_b16 v[76:77], v231 offset:2048
	ds_read_b64_tr_b16 v[78:79], v231 offset:2560
	ds_read_b64_tr_b16 v[220:221], v231 offset:1024
	ds_read_b64_tr_b16 v[222:223], v231 offset:1536
	ds_read_b64_tr_b16 v[224:225], v231 offset:3072
	ds_read_b64_tr_b16 v[226:227], v231 offset:3584
	v_mfma_f32_32x32x16_bf16 v[32:47], v[192:195], v[52:55], v[32:47]
	v_mfma_f32_32x32x16_bf16 v[32:47], v[196:199], v[56:59], v[32:47]
	v_mfma_f32_32x32x16_bf16 v[32:47], v[200:203], v[60:63], v[32:47]
	s_nop 11
	v_exp_f32_e32 v32, v32
	v_exp_f32_e32 v33, v33
	v_exp_f32_e32 v34, v34
	v_exp_f32_e32 v35, v35
	v_exp_f32_e32 v36, v36
	v_exp_f32_e32 v37, v37
	v_exp_f32_e32 v38, v38
	v_exp_f32_e32 v39, v39
	v_exp_f32_e32 v40, v40
	v_exp_f32_e32 v41, v41
	v_exp_f32_e32 v42, v42
	v_exp_f32_e32 v43, v43
	v_exp_f32_e32 v44, v44
	v_exp_f32_e32 v45, v45
	v_exp_f32_e32 v46, v46
	v_exp_f32_e32 v47, v47
	v_cvt_pk_bf16_f32 v64, v32, v33
	v_cvt_pk_bf16_f32 v65, v34, v35
	v_cvt_pk_bf16_f32 v66, v36, v37
	v_cvt_pk_bf16_f32 v67, v38, v39
	v_cvt_pk_bf16_f32 v68, v40, v41
	v_cvt_pk_bf16_f32 v69, v42, v43
	v_cvt_pk_bf16_f32 v70, v44, v45
	v_cvt_pk_bf16_f32 v71, v46, v47
	v_pk_add_f32 v[232:233], v[232:233], v[32:33]
	v_pk_add_f32 v[232:233], v[232:233], v[34:35]
	v_pk_add_f32 v[232:233], v[232:233], v[36:37]
	v_pk_add_f32 v[232:233], v[232:233], v[38:39]
	v_pk_add_f32 v[232:233], v[232:233], v[40:41]
	v_pk_add_f32 v[232:233], v[232:233], v[42:43]
	v_pk_add_f32 v[232:233], v[232:233], v[44:45]
	v_pk_add_f32 v[232:233], v[232:233], v[46:47]
	s_waitcnt lgkmcnt(0)
	v_mfma_f32_32x32x16_bf16 v[0:15], v[64:67], v[72:75], v[0:15]
	v_mfma_f32_32x32x16_bf16 v[16:31], v[64:67], v[76:79], v[16:31]
	v_mfma_f32_32x32x16_bf16 v[0:15], v[68:71], v[220:223], v[0:15]
	v_mfma_f32_32x32x16_bf16 v[16:31], v[68:71], v[224:227], v[16:31]
	global_load_dwordx4 v[188:191], v239, s[86:87]
	global_load_dwordx4 v[192:195], v240, s[86:87]
	global_load_dwordx4 v[196:199], v241, s[86:87]
	global_load_dwordx4 v[200:203], v242, s[86:87]
	global_load_dwordx4 v[204:207], v101, s[86:87] offset:768
	global_load_dwordx4 v[208:211], v150, s[86:87] offset:768
	global_load_dwordx4 v[212:215], v101, s[86:87] offset:832
	global_load_dwordx4 v[216:219], v150, s[86:87] offset:832
	s_add_u32 s86, s86, 0xc0000
	s_addc_u32 s87, s87, 0
	s_waitcnt vmcnt(16)
	ds_write_b128 v247, v[116:119]
	ds_write_b128 v247, v[120:123] offset:1024
	ds_write_b128 v247, v[124:127] offset:2048
	ds_write_b128 v247, v[128:131] offset:3072
	ds_read_b128 v[116:119], v248
	ds_read_b128 v[120:123], v249
	ds_read_b128 v[124:127], v250
	ds_read_b128 v[128:131], v251
	ds_write_b128 v112, v[132:135]
	ds_write_b128 v112, v[136:139] offset:1024
	ds_write_b128 v112, v[140:143] offset:2048
	ds_write_b128 v112, v[144:147] offset:3072
	ds_read2_b32 v[32:33], v115 offset0:128 offset1:129
	ds_read2_b32 v[34:35], v115 offset0:130 offset1:131
	ds_read2_b32 v[36:37], v115 offset0:136 offset1:137
	ds_read2_b32 v[38:39], v115 offset0:138 offset1:139
	ds_read2_b32 v[40:41], v115 offset0:144 offset1:145
	ds_read2_b32 v[42:43], v115 offset0:146 offset1:147
	ds_read2_b32 v[44:45], v115 offset0:152 offset1:153
	ds_read2_b32 v[46:47], v115 offset0:154 offset1:155
	s_waitcnt lgkmcnt(0)
	v_mfma_f32_32x32x16_bf16 v[32:47], v[116:119], v[48:51], v[32:47]
	ds_read_b64_tr_b16 v[72:73], v231
	ds_read_b64_tr_b16 v[74:75], v231 offset:512
	ds_read_b64_tr_b16 v[76:77], v231 offset:2048
	ds_read_b64_tr_b16 v[78:79], v231 offset:2560
	ds_read_b64_tr_b16 v[220:221], v231 offset:1024
	ds_read_b64_tr_b16 v[222:223], v231 offset:1536
	ds_read_b64_tr_b16 v[224:225], v231 offset:3072
	ds_read_b64_tr_b16 v[226:227], v231 offset:3584
	v_mfma_f32_32x32x16_bf16 v[32:47], v[120:123], v[52:55], v[32:47]
	v_mfma_f32_32x32x16_bf16 v[32:47], v[124:127], v[56:59], v[32:47]
	v_mfma_f32_32x32x16_bf16 v[32:47], v[128:131], v[60:63], v[32:47]
	s_nop 11
	v_exp_f32_e32 v32, v32
	v_exp_f32_e32 v33, v33
	v_exp_f32_e32 v34, v34
	v_exp_f32_e32 v35, v35
	v_exp_f32_e32 v36, v36
	v_exp_f32_e32 v37, v37
	v_exp_f32_e32 v38, v38
	v_exp_f32_e32 v39, v39
	v_exp_f32_e32 v40, v40
	v_exp_f32_e32 v41, v41
	v_exp_f32_e32 v42, v42
	v_exp_f32_e32 v43, v43
	v_exp_f32_e32 v44, v44
	v_exp_f32_e32 v45, v45
	v_exp_f32_e32 v46, v46
	v_exp_f32_e32 v47, v47
	v_cvt_pk_bf16_f32 v64, v32, v33
	v_cvt_pk_bf16_f32 v65, v34, v35
	v_cvt_pk_bf16_f32 v66, v36, v37
	v_cvt_pk_bf16_f32 v67, v38, v39
	v_cvt_pk_bf16_f32 v68, v40, v41
	v_cvt_pk_bf16_f32 v69, v42, v43
	v_cvt_pk_bf16_f32 v70, v44, v45
	v_cvt_pk_bf16_f32 v71, v46, v47
	v_pk_add_f32 v[232:233], v[232:233], v[32:33]
	v_pk_add_f32 v[232:233], v[232:233], v[34:35]
	v_pk_add_f32 v[232:233], v[232:233], v[36:37]
	v_pk_add_f32 v[232:233], v[232:233], v[38:39]
	v_pk_add_f32 v[232:233], v[232:233], v[40:41]
	v_pk_add_f32 v[232:233], v[232:233], v[42:43]
	v_pk_add_f32 v[232:233], v[232:233], v[44:45]
	v_pk_add_f32 v[232:233], v[232:233], v[46:47]
	s_waitcnt lgkmcnt(0)
	v_mfma_f32_32x32x16_bf16 v[0:15], v[64:67], v[72:75], v[0:15]
	v_mfma_f32_32x32x16_bf16 v[16:31], v[64:67], v[76:79], v[16:31]
	v_mfma_f32_32x32x16_bf16 v[0:15], v[68:71], v[220:223], v[0:15]
	v_mfma_f32_32x32x16_bf16 v[16:31], v[68:71], v[224:227], v[16:31]
	global_load_dwordx4 v[116:119], v239, s[86:87]
	global_load_dwordx4 v[120:123], v240, s[86:87]
	global_load_dwordx4 v[124:127], v241, s[86:87]
	global_load_dwordx4 v[128:131], v242, s[86:87]
	global_load_dwordx4 v[132:135], v101, s[86:87] offset:768
	global_load_dwordx4 v[136:139], v150, s[86:87] offset:768
	global_load_dwordx4 v[140:143], v101, s[86:87] offset:832
	global_load_dwordx4 v[144:147], v150, s[86:87] offset:832
	s_waitcnt vmcnt(16)
	ds_write_b128 v247, v[156:159]
	ds_write_b128 v247, v[160:163] offset:1024
	ds_write_b128 v247, v[164:167] offset:2048
	ds_write_b128 v247, v[168:171] offset:3072
	ds_read_b128 v[156:159], v248
	ds_read_b128 v[160:163], v249
	ds_read_b128 v[164:167], v250
	ds_read_b128 v[168:171], v251
	ds_write_b128 v112, v[172:175]
	ds_write_b128 v112, v[176:179] offset:1024
	ds_write_b128 v112, v[180:183] offset:2048
	ds_write_b128 v112, v[184:187] offset:3072
	ds_read2_b32 v[32:33], v115 offset0:160 offset1:161
	ds_read2_b32 v[34:35], v115 offset0:162 offset1:163
	ds_read2_b32 v[36:37], v115 offset0:168 offset1:169
	ds_read2_b32 v[38:39], v115 offset0:170 offset1:171
	ds_read2_b32 v[40:41], v115 offset0:176 offset1:177
	ds_read2_b32 v[42:43], v115 offset0:178 offset1:179
	ds_read2_b32 v[44:45], v115 offset0:184 offset1:185
	ds_read2_b32 v[46:47], v115 offset0:186 offset1:187
	s_waitcnt lgkmcnt(0)
	v_mfma_f32_32x32x16_bf16 v[32:47], v[156:159], v[48:51], v[32:47]
	ds_read_b64_tr_b16 v[72:73], v231
	ds_read_b64_tr_b16 v[74:75], v231 offset:512
	ds_read_b64_tr_b16 v[76:77], v231 offset:2048
	ds_read_b64_tr_b16 v[78:79], v231 offset:2560
	ds_read_b64_tr_b16 v[220:221], v231 offset:1024
	ds_read_b64_tr_b16 v[222:223], v231 offset:1536
	ds_read_b64_tr_b16 v[224:225], v231 offset:3072
	ds_read_b64_tr_b16 v[226:227], v231 offset:3584
	v_mfma_f32_32x32x16_bf16 v[32:47], v[160:163], v[52:55], v[32:47]
	v_mfma_f32_32x32x16_bf16 v[32:47], v[164:167], v[56:59], v[32:47]
	v_mfma_f32_32x32x16_bf16 v[32:47], v[168:171], v[60:63], v[32:47]
	s_nop 11
	v_exp_f32_e32 v32, v32
	v_exp_f32_e32 v33, v33
	v_exp_f32_e32 v34, v34
	v_exp_f32_e32 v35, v35
	v_exp_f32_e32 v36, v36
	v_exp_f32_e32 v37, v37
	v_exp_f32_e32 v38, v38
	v_exp_f32_e32 v39, v39
	v_exp_f32_e32 v40, v40
	v_exp_f32_e32 v41, v41
	v_exp_f32_e32 v42, v42
	v_exp_f32_e32 v43, v43
	v_exp_f32_e32 v44, v44
	v_exp_f32_e32 v45, v45
	v_exp_f32_e32 v46, v46
	v_exp_f32_e32 v47, v47
	v_cvt_pk_bf16_f32 v64, v32, v33
	v_cvt_pk_bf16_f32 v65, v34, v35
	v_cvt_pk_bf16_f32 v66, v36, v37
	v_cvt_pk_bf16_f32 v67, v38, v39
	v_cvt_pk_bf16_f32 v68, v40, v41
	v_cvt_pk_bf16_f32 v69, v42, v43
	v_cvt_pk_bf16_f32 v70, v44, v45
	v_cvt_pk_bf16_f32 v71, v46, v47
	v_pk_add_f32 v[232:233], v[232:233], v[32:33]
	v_pk_add_f32 v[232:233], v[232:233], v[34:35]
	v_pk_add_f32 v[232:233], v[232:233], v[36:37]
	v_pk_add_f32 v[232:233], v[232:233], v[38:39]
	v_pk_add_f32 v[232:233], v[232:233], v[40:41]
	v_pk_add_f32 v[232:233], v[232:233], v[42:43]
	v_pk_add_f32 v[232:233], v[232:233], v[44:45]
	v_pk_add_f32 v[232:233], v[232:233], v[46:47]
	s_waitcnt lgkmcnt(0)
	v_mfma_f32_32x32x16_bf16 v[0:15], v[64:67], v[72:75], v[0:15]
	v_mfma_f32_32x32x16_bf16 v[16:31], v[64:67], v[76:79], v[16:31]
	v_mfma_f32_32x32x16_bf16 v[0:15], v[68:71], v[220:223], v[0:15]
	v_mfma_f32_32x32x16_bf16 v[16:31], v[68:71], v[224:227], v[16:31]
	global_load_dwordx4 v[156:159], v243, s[88:89]
	global_load_dwordx4 v[160:163], v244, s[88:89]
	global_load_dwordx4 v[164:167], v245, s[88:89]
	global_load_dwordx4 v[168:171], v246, s[88:89]
	global_load_dwordx4 v[172:175], v148, s[88:89] offset:768
	global_load_dwordx4 v[176:179], v151, s[88:89] offset:768
	global_load_dwordx4 v[180:183], v148, s[88:89] offset:832
	global_load_dwordx4 v[184:187], v151, s[88:89] offset:832
	s_add_u32 s88, s88, 0x300000
	s_addc_u32 s89, s89, 0
	s_waitcnt vmcnt(16)
	ds_write_b128 v247, v[188:191]
	ds_write_b128 v247, v[192:195] offset:1024
	ds_write_b128 v247, v[196:199] offset:2048
	ds_write_b128 v247, v[200:203] offset:3072
	ds_read_b128 v[188:191], v248
	ds_read_b128 v[192:195], v249
	ds_read_b128 v[196:199], v250
	ds_read_b128 v[200:203], v251
	ds_write_b128 v112, v[204:207]
	ds_write_b128 v112, v[208:211] offset:1024
	ds_write_b128 v112, v[212:215] offset:2048
	ds_write_b128 v112, v[216:219] offset:3072
	ds_read2_b32 v[32:33], v115 offset0:192 offset1:193
	ds_read2_b32 v[34:35], v115 offset0:194 offset1:195
	ds_read2_b32 v[36:37], v115 offset0:200 offset1:201
	ds_read2_b32 v[38:39], v115 offset0:202 offset1:203
	ds_read2_b32 v[40:41], v115 offset0:208 offset1:209
	ds_read2_b32 v[42:43], v115 offset0:210 offset1:211
	ds_read2_b32 v[44:45], v115 offset0:216 offset1:217
	ds_read2_b32 v[46:47], v115 offset0:218 offset1:219
	s_waitcnt lgkmcnt(0)
	v_mfma_f32_32x32x16_bf16 v[32:47], v[188:191], v[48:51], v[32:47]
	ds_read_b64_tr_b16 v[72:73], v231
	ds_read_b64_tr_b16 v[74:75], v231 offset:512
	ds_read_b64_tr_b16 v[76:77], v231 offset:2048
	ds_read_b64_tr_b16 v[78:79], v231 offset:2560
	ds_read_b64_tr_b16 v[220:221], v231 offset:1024
	ds_read_b64_tr_b16 v[222:223], v231 offset:1536
	ds_read_b64_tr_b16 v[224:225], v231 offset:3072
	ds_read_b64_tr_b16 v[226:227], v231 offset:3584
	v_mfma_f32_32x32x16_bf16 v[32:47], v[192:195], v[52:55], v[32:47]
	v_mfma_f32_32x32x16_bf16 v[32:47], v[196:199], v[56:59], v[32:47]
	v_mfma_f32_32x32x16_bf16 v[32:47], v[200:203], v[60:63], v[32:47]
	s_nop 11
	v_exp_f32_e32 v32, v32
	v_exp_f32_e32 v33, v33
	v_exp_f32_e32 v34, v34
	v_exp_f32_e32 v35, v35
	v_exp_f32_e32 v36, v36
	v_exp_f32_e32 v37, v37
	v_exp_f32_e32 v38, v38
	v_exp_f32_e32 v39, v39
	v_exp_f32_e32 v40, v40
	v_exp_f32_e32 v41, v41
	v_exp_f32_e32 v42, v42
	v_exp_f32_e32 v43, v43
	v_exp_f32_e32 v44, v44
	v_exp_f32_e32 v45, v45
	v_exp_f32_e32 v46, v46
	v_exp_f32_e32 v47, v47
	v_cvt_pk_bf16_f32 v64, v32, v33
	v_cvt_pk_bf16_f32 v65, v34, v35
	v_cvt_pk_bf16_f32 v66, v36, v37
	v_cvt_pk_bf16_f32 v67, v38, v39
	v_cvt_pk_bf16_f32 v68, v40, v41
	v_cvt_pk_bf16_f32 v69, v42, v43
	v_cvt_pk_bf16_f32 v70, v44, v45
	v_cvt_pk_bf16_f32 v71, v46, v47
	v_pk_add_f32 v[232:233], v[232:233], v[32:33]
	v_pk_add_f32 v[232:233], v[232:233], v[34:35]
	v_pk_add_f32 v[232:233], v[232:233], v[36:37]
	v_pk_add_f32 v[232:233], v[232:233], v[38:39]
	v_pk_add_f32 v[232:233], v[232:233], v[40:41]
	v_pk_add_f32 v[232:233], v[232:233], v[42:43]
	v_pk_add_f32 v[232:233], v[232:233], v[44:45]
	v_pk_add_f32 v[232:233], v[232:233], v[46:47]
	s_waitcnt lgkmcnt(0)
	v_mfma_f32_32x32x16_bf16 v[0:15], v[64:67], v[72:75], v[0:15]
	v_mfma_f32_32x32x16_bf16 v[16:31], v[64:67], v[76:79], v[16:31]
	v_mfma_f32_32x32x16_bf16 v[0:15], v[68:71], v[220:223], v[0:15]
	v_mfma_f32_32x32x16_bf16 v[16:31], v[68:71], v[224:227], v[16:31]
	global_load_dwordx4 v[188:191], v243, s[88:89]
	global_load_dwordx4 v[192:195], v244, s[88:89]
	global_load_dwordx4 v[196:199], v245, s[88:89]
	global_load_dwordx4 v[200:203], v246, s[88:89]
	global_load_dwordx4 v[204:207], v148, s[88:89] offset:768
	global_load_dwordx4 v[208:211], v151, s[88:89] offset:768
	global_load_dwordx4 v[212:215], v148, s[88:89] offset:832
	global_load_dwordx4 v[216:219], v151, s[88:89] offset:832
	s_add_u32 s88, s88, 0x300000
	s_addc_u32 s89, s89, 0
	s_waitcnt vmcnt(16)
	ds_write_b128 v247, v[116:119]
	ds_write_b128 v247, v[120:123] offset:1024
	ds_write_b128 v247, v[124:127] offset:2048
	ds_write_b128 v247, v[128:131] offset:3072
	ds_read_b128 v[116:119], v248
	ds_read_b128 v[120:123], v249
	ds_read_b128 v[124:127], v250
	ds_read_b128 v[128:131], v251
	ds_write_b128 v112, v[132:135]
	ds_write_b128 v112, v[136:139] offset:1024
	ds_write_b128 v112, v[140:143] offset:2048
	ds_write_b128 v112, v[144:147] offset:3072
	ds_read2_b32 v[32:33], v115 offset0:224 offset1:225
	ds_read2_b32 v[34:35], v115 offset0:226 offset1:227
	ds_read2_b32 v[36:37], v115 offset0:232 offset1:233
	ds_read2_b32 v[38:39], v115 offset0:234 offset1:235
	ds_read2_b32 v[40:41], v115 offset0:240 offset1:241
	ds_read2_b32 v[42:43], v115 offset0:242 offset1:243
	ds_read2_b32 v[44:45], v115 offset0:248 offset1:249
	ds_read2_b32 v[46:47], v115 offset0:250 offset1:251
	s_waitcnt lgkmcnt(0)
	v_mfma_f32_32x32x16_bf16 v[32:47], v[116:119], v[48:51], v[32:47]
	ds_read_b64_tr_b16 v[72:73], v231
	ds_read_b64_tr_b16 v[74:75], v231 offset:512
	ds_read_b64_tr_b16 v[76:77], v231 offset:2048
	ds_read_b64_tr_b16 v[78:79], v231 offset:2560
	ds_read_b64_tr_b16 v[220:221], v231 offset:1024
	ds_read_b64_tr_b16 v[222:223], v231 offset:1536
	ds_read_b64_tr_b16 v[224:225], v231 offset:3072
	ds_read_b64_tr_b16 v[226:227], v231 offset:3584
	v_mfma_f32_32x32x16_bf16 v[32:47], v[120:123], v[52:55], v[32:47]
	v_mfma_f32_32x32x16_bf16 v[32:47], v[124:127], v[56:59], v[32:47]
	v_mfma_f32_32x32x16_bf16 v[32:47], v[128:131], v[60:63], v[32:47]
	s_nop 11
	v_exp_f32_e32 v32, v32
	v_exp_f32_e32 v33, v33
	v_exp_f32_e32 v34, v34
	v_exp_f32_e32 v35, v35
	v_exp_f32_e32 v36, v36
	v_exp_f32_e32 v37, v37
	v_exp_f32_e32 v38, v38
	v_exp_f32_e32 v39, v39
	v_exp_f32_e32 v40, v40
	v_exp_f32_e32 v41, v41
	v_exp_f32_e32 v42, v42
	v_exp_f32_e32 v43, v43
	v_exp_f32_e32 v44, v44
	v_exp_f32_e32 v45, v45
	v_exp_f32_e32 v46, v46
	v_exp_f32_e32 v47, v47
	v_cvt_pk_bf16_f32 v64, v32, v33
	v_cvt_pk_bf16_f32 v65, v34, v35
	v_cvt_pk_bf16_f32 v66, v36, v37
	v_cvt_pk_bf16_f32 v67, v38, v39
	v_cvt_pk_bf16_f32 v68, v40, v41
	v_cvt_pk_bf16_f32 v69, v42, v43
	v_cvt_pk_bf16_f32 v70, v44, v45
	v_cvt_pk_bf16_f32 v71, v46, v47
	v_pk_add_f32 v[232:233], v[232:233], v[32:33]
	v_pk_add_f32 v[232:233], v[232:233], v[34:35]
	v_pk_add_f32 v[232:233], v[232:233], v[36:37]
	v_pk_add_f32 v[232:233], v[232:233], v[38:39]
	v_pk_add_f32 v[232:233], v[232:233], v[40:41]
	v_pk_add_f32 v[232:233], v[232:233], v[42:43]
	v_pk_add_f32 v[232:233], v[232:233], v[44:45]
	v_pk_add_f32 v[232:233], v[232:233], v[46:47]
	s_waitcnt lgkmcnt(0)
	v_mfma_f32_32x32x16_bf16 v[0:15], v[64:67], v[72:75], v[0:15]
	v_mfma_f32_32x32x16_bf16 v[16:31], v[64:67], v[76:79], v[16:31]
	v_mfma_f32_32x32x16_bf16 v[0:15], v[68:71], v[220:223], v[0:15]
	v_mfma_f32_32x32x16_bf16 v[16:31], v[68:71], v[224:227], v[16:31]
	global_load_dwordx4 v[116:119], v243, s[88:89]
	global_load_dwordx4 v[120:123], v244, s[88:89]
	global_load_dwordx4 v[124:127], v245, s[88:89]
	global_load_dwordx4 v[128:131], v246, s[88:89]
	global_load_dwordx4 v[132:135], v148, s[88:89] offset:768
	global_load_dwordx4 v[136:139], v151, s[88:89] offset:768
	global_load_dwordx4 v[140:143], v148, s[88:89] offset:832
	global_load_dwordx4 v[144:147], v151, s[88:89] offset:832
	s_add_u32 s88, s88, 0x300000
	s_addc_u32 s89, s89, 0
	s_waitcnt vmcnt(16)
	ds_write_b128 v247, v[156:159]
	ds_write_b128 v247, v[160:163] offset:1024
	ds_write_b128 v247, v[164:167] offset:2048
	ds_write_b128 v247, v[168:171] offset:3072
	ds_read_b128 v[156:159], v248
	ds_read_b128 v[160:163], v249
	ds_read_b128 v[164:167], v250
	ds_read_b128 v[168:171], v251
	ds_write_b128 v112, v[172:175]
	ds_write_b128 v112, v[176:179] offset:1024
	ds_write_b128 v112, v[180:183] offset:2048
	ds_write_b128 v112, v[184:187] offset:3072
	v_mov_b32_e32 v115, v230
	ds_read2_b32 v[32:33], v115 offset0:0 offset1:1
	ds_read2_b32 v[34:35], v115 offset0:2 offset1:3
	ds_read2_b32 v[36:37], v115 offset0:8 offset1:9
	ds_read2_b32 v[38:39], v115 offset0:10 offset1:11
	ds_read2_b32 v[40:41], v115 offset0:16 offset1:17
	ds_read2_b32 v[42:43], v115 offset0:18 offset1:19
	ds_read2_b32 v[44:45], v115 offset0:24 offset1:25
	ds_read2_b32 v[46:47], v115 offset0:26 offset1:27
	s_waitcnt lgkmcnt(0)
	v_mfma_f32_32x32x16_bf16 v[32:47], v[156:159], v[48:51], v[32:47]
	ds_read_b64_tr_b16 v[72:73], v231
	ds_read_b64_tr_b16 v[74:75], v231 offset:512
	ds_read_b64_tr_b16 v[76:77], v231 offset:2048
	ds_read_b64_tr_b16 v[78:79], v231 offset:2560
	ds_read_b64_tr_b16 v[220:221], v231 offset:1024
	ds_read_b64_tr_b16 v[222:223], v231 offset:1536
	ds_read_b64_tr_b16 v[224:225], v231 offset:3072
	ds_read_b64_tr_b16 v[226:227], v231 offset:3584
	v_mfma_f32_32x32x16_bf16 v[32:47], v[160:163], v[52:55], v[32:47]
	v_mfma_f32_32x32x16_bf16 v[32:47], v[164:167], v[56:59], v[32:47]
	v_mfma_f32_32x32x16_bf16 v[32:47], v[168:171], v[60:63], v[32:47]
	s_nop 11
	v_exp_f32_e32 v32, v32
	v_exp_f32_e32 v33, v33
	v_exp_f32_e32 v34, v34
	v_exp_f32_e32 v35, v35
	v_exp_f32_e32 v36, v36
	v_exp_f32_e32 v37, v37
	v_exp_f32_e32 v38, v38
	v_exp_f32_e32 v39, v39
	v_exp_f32_e32 v40, v40
	v_exp_f32_e32 v41, v41
	v_exp_f32_e32 v42, v42
	v_exp_f32_e32 v43, v43
	v_exp_f32_e32 v44, v44
	v_exp_f32_e32 v45, v45
	v_exp_f32_e32 v46, v46
	v_exp_f32_e32 v47, v47
	v_cvt_pk_bf16_f32 v64, v32, v33
	v_cvt_pk_bf16_f32 v65, v34, v35
	v_cvt_pk_bf16_f32 v66, v36, v37
	v_cvt_pk_bf16_f32 v67, v38, v39
	v_cvt_pk_bf16_f32 v68, v40, v41
	v_cvt_pk_bf16_f32 v69, v42, v43
	v_cvt_pk_bf16_f32 v70, v44, v45
	v_cvt_pk_bf16_f32 v71, v46, v47
	v_pk_add_f32 v[232:233], v[232:233], v[32:33]
	v_pk_add_f32 v[232:233], v[232:233], v[34:35]
	v_pk_add_f32 v[232:233], v[232:233], v[36:37]
	v_pk_add_f32 v[232:233], v[232:233], v[38:39]
	v_pk_add_f32 v[232:233], v[232:233], v[40:41]
	v_pk_add_f32 v[232:233], v[232:233], v[42:43]
	v_pk_add_f32 v[232:233], v[232:233], v[44:45]
	v_pk_add_f32 v[232:233], v[232:233], v[46:47]
	s_waitcnt lgkmcnt(0)
	v_mfma_f32_32x32x16_bf16 v[0:15], v[64:67], v[72:75], v[0:15]
	v_mfma_f32_32x32x16_bf16 v[16:31], v[64:67], v[76:79], v[16:31]
	v_mfma_f32_32x32x16_bf16 v[0:15], v[68:71], v[220:223], v[0:15]
	v_mfma_f32_32x32x16_bf16 v[16:31], v[68:71], v[224:227], v[16:31]
	global_load_dwordx4 v[156:159], v243, s[88:89]
	global_load_dwordx4 v[160:163], v244, s[88:89]
	global_load_dwordx4 v[164:167], v245, s[88:89]
	global_load_dwordx4 v[168:171], v246, s[88:89]
	global_load_dwordx4 v[172:175], v148, s[88:89] offset:768
	global_load_dwordx4 v[176:179], v151, s[88:89] offset:768
	global_load_dwordx4 v[180:183], v148, s[88:89] offset:832
	global_load_dwordx4 v[184:187], v151, s[88:89] offset:832
	s_add_u32 s88, s88, 0x300000
	s_addc_u32 s89, s89, 0
	s_waitcnt vmcnt(16)
	ds_write_b128 v247, v[188:191]
	ds_write_b128 v247, v[192:195] offset:1024
	ds_write_b128 v247, v[196:199] offset:2048
	ds_write_b128 v247, v[200:203] offset:3072
	ds_read_b128 v[188:191], v248
	ds_read_b128 v[192:195], v249
	ds_read_b128 v[196:199], v250
	ds_read_b128 v[200:203], v251
	ds_write_b128 v112, v[204:207]
	ds_write_b128 v112, v[208:211] offset:1024
	ds_write_b128 v112, v[212:215] offset:2048
	ds_write_b128 v112, v[216:219] offset:3072
	ds_read2_b32 v[32:33], v115 offset0:32 offset1:33
	ds_read2_b32 v[34:35], v115 offset0:34 offset1:35
	ds_read2_b32 v[36:37], v115 offset0:40 offset1:41
	ds_read2_b32 v[38:39], v115 offset0:42 offset1:43
	ds_read2_b32 v[40:41], v115 offset0:48 offset1:49
	ds_read2_b32 v[42:43], v115 offset0:50 offset1:51
	ds_read2_b32 v[44:45], v115 offset0:56 offset1:57
	ds_read2_b32 v[46:47], v115 offset0:58 offset1:59
	s_waitcnt lgkmcnt(0)
	v_mfma_f32_32x32x16_bf16 v[32:47], v[188:191], v[48:51], v[32:47]
	ds_read_b64_tr_b16 v[72:73], v231
	ds_read_b64_tr_b16 v[74:75], v231 offset:512
	ds_read_b64_tr_b16 v[76:77], v231 offset:2048
	ds_read_b64_tr_b16 v[78:79], v231 offset:2560
	ds_read_b64_tr_b16 v[220:221], v231 offset:1024
	ds_read_b64_tr_b16 v[222:223], v231 offset:1536
	ds_read_b64_tr_b16 v[224:225], v231 offset:3072
	ds_read_b64_tr_b16 v[226:227], v231 offset:3584
	v_mfma_f32_32x32x16_bf16 v[32:47], v[192:195], v[52:55], v[32:47]
	v_mfma_f32_32x32x16_bf16 v[32:47], v[196:199], v[56:59], v[32:47]
	v_mfma_f32_32x32x16_bf16 v[32:47], v[200:203], v[60:63], v[32:47]
	s_nop 11
	v_exp_f32_e32 v32, v32
	v_exp_f32_e32 v33, v33
	v_exp_f32_e32 v34, v34
	v_exp_f32_e32 v35, v35
	v_exp_f32_e32 v36, v36
	v_exp_f32_e32 v37, v37
	v_exp_f32_e32 v38, v38
	v_exp_f32_e32 v39, v39
	v_exp_f32_e32 v40, v40
	v_exp_f32_e32 v41, v41
	v_exp_f32_e32 v42, v42
	v_exp_f32_e32 v43, v43
	v_exp_f32_e32 v44, v44
	v_exp_f32_e32 v45, v45
	v_exp_f32_e32 v46, v46
	v_exp_f32_e32 v47, v47
	v_cvt_pk_bf16_f32 v64, v32, v33
	v_cvt_pk_bf16_f32 v65, v34, v35
	v_cvt_pk_bf16_f32 v66, v36, v37
	v_cvt_pk_bf16_f32 v67, v38, v39
	v_cvt_pk_bf16_f32 v68, v40, v41
	v_cvt_pk_bf16_f32 v69, v42, v43
	v_cvt_pk_bf16_f32 v70, v44, v45
	v_cvt_pk_bf16_f32 v71, v46, v47
	v_pk_add_f32 v[232:233], v[232:233], v[32:33]
	v_pk_add_f32 v[232:233], v[232:233], v[34:35]
	v_pk_add_f32 v[232:233], v[232:233], v[36:37]
	v_pk_add_f32 v[232:233], v[232:233], v[38:39]
	v_pk_add_f32 v[232:233], v[232:233], v[40:41]
	v_pk_add_f32 v[232:233], v[232:233], v[42:43]
	v_pk_add_f32 v[232:233], v[232:233], v[44:45]
	v_pk_add_f32 v[232:233], v[232:233], v[46:47]
	s_waitcnt lgkmcnt(0)
	v_mfma_f32_32x32x16_bf16 v[0:15], v[64:67], v[72:75], v[0:15]
	v_mfma_f32_32x32x16_bf16 v[16:31], v[64:67], v[76:79], v[16:31]
	v_mfma_f32_32x32x16_bf16 v[0:15], v[68:71], v[220:223], v[0:15]
	v_mfma_f32_32x32x16_bf16 v[16:31], v[68:71], v[224:227], v[16:31]
	global_load_dwordx4 v[188:191], v243, s[88:89]
	global_load_dwordx4 v[192:195], v244, s[88:89]
	global_load_dwordx4 v[196:199], v245, s[88:89]
	global_load_dwordx4 v[200:203], v246, s[88:89]
	global_load_dwordx4 v[204:207], v148, s[88:89] offset:768
	global_load_dwordx4 v[208:211], v151, s[88:89] offset:768
	global_load_dwordx4 v[212:215], v148, s[88:89] offset:832
	global_load_dwordx4 v[216:219], v151, s[88:89] offset:832
	s_waitcnt vmcnt(16)
	ds_write_b128 v247, v[116:119]
	ds_write_b128 v247, v[120:123] offset:1024
	ds_write_b128 v247, v[124:127] offset:2048
	ds_write_b128 v247, v[128:131] offset:3072
	ds_read_b128 v[116:119], v248
	ds_read_b128 v[120:123], v249
	ds_read_b128 v[124:127], v250
	ds_read_b128 v[128:131], v251
	ds_write_b128 v112, v[132:135]
	ds_write_b128 v112, v[136:139] offset:1024
	ds_write_b128 v112, v[140:143] offset:2048
	ds_write_b128 v112, v[144:147] offset:3072
	ds_read2_b32 v[32:33], v115 offset0:64 offset1:65
	ds_read2_b32 v[34:35], v115 offset0:66 offset1:67
	ds_read2_b32 v[36:37], v115 offset0:72 offset1:73
	ds_read2_b32 v[38:39], v115 offset0:74 offset1:75
	ds_read2_b32 v[40:41], v115 offset0:80 offset1:81
	ds_read2_b32 v[42:43], v115 offset0:82 offset1:83
	ds_read2_b32 v[44:45], v115 offset0:88 offset1:89
	ds_read2_b32 v[46:47], v115 offset0:90 offset1:91
	s_waitcnt lgkmcnt(0)
	v_mfma_f32_32x32x16_bf16 v[32:47], v[116:119], v[48:51], v[32:47]
	ds_read_b64_tr_b16 v[72:73], v231
	ds_read_b64_tr_b16 v[74:75], v231 offset:512
	ds_read_b64_tr_b16 v[76:77], v231 offset:2048
	ds_read_b64_tr_b16 v[78:79], v231 offset:2560
	ds_read_b64_tr_b16 v[220:221], v231 offset:1024
	ds_read_b64_tr_b16 v[222:223], v231 offset:1536
	ds_read_b64_tr_b16 v[224:225], v231 offset:3072
	ds_read_b64_tr_b16 v[226:227], v231 offset:3584
	v_mfma_f32_32x32x16_bf16 v[32:47], v[120:123], v[52:55], v[32:47]
	v_mfma_f32_32x32x16_bf16 v[32:47], v[124:127], v[56:59], v[32:47]
	v_mfma_f32_32x32x16_bf16 v[32:47], v[128:131], v[60:63], v[32:47]
	s_nop 11
	v_exp_f32_e32 v32, v32
	v_exp_f32_e32 v33, v33
	v_exp_f32_e32 v34, v34
	v_exp_f32_e32 v35, v35
	v_exp_f32_e32 v36, v36
	v_exp_f32_e32 v37, v37
	v_exp_f32_e32 v38, v38
	v_exp_f32_e32 v39, v39
	v_exp_f32_e32 v40, v40
	v_exp_f32_e32 v41, v41
	v_exp_f32_e32 v42, v42
	v_exp_f32_e32 v43, v43
	v_exp_f32_e32 v44, v44
	v_exp_f32_e32 v45, v45
	v_exp_f32_e32 v46, v46
	v_exp_f32_e32 v47, v47
	v_cvt_pk_bf16_f32 v64, v32, v33
	v_cvt_pk_bf16_f32 v65, v34, v35
	v_cvt_pk_bf16_f32 v66, v36, v37
	v_cvt_pk_bf16_f32 v67, v38, v39
	v_cvt_pk_bf16_f32 v68, v40, v41
	v_cvt_pk_bf16_f32 v69, v42, v43
	v_cvt_pk_bf16_f32 v70, v44, v45
	v_cvt_pk_bf16_f32 v71, v46, v47
	v_pk_add_f32 v[232:233], v[232:233], v[32:33]
	v_pk_add_f32 v[232:233], v[232:233], v[34:35]
	v_pk_add_f32 v[232:233], v[232:233], v[36:37]
	v_pk_add_f32 v[232:233], v[232:233], v[38:39]
	v_pk_add_f32 v[232:233], v[232:233], v[40:41]
	v_pk_add_f32 v[232:233], v[232:233], v[42:43]
	v_pk_add_f32 v[232:233], v[232:233], v[44:45]
	v_pk_add_f32 v[232:233], v[232:233], v[46:47]
	s_waitcnt lgkmcnt(0)
	v_mfma_f32_32x32x16_bf16 v[0:15], v[64:67], v[72:75], v[0:15]
	v_mfma_f32_32x32x16_bf16 v[16:31], v[64:67], v[76:79], v[16:31]
	v_mfma_f32_32x32x16_bf16 v[0:15], v[68:71], v[220:223], v[0:15]
	v_mfma_f32_32x32x16_bf16 v[16:31], v[68:71], v[224:227], v[16:31]
	s_waitcnt vmcnt(8)
	ds_write_b128 v247, v[156:159]
	ds_write_b128 v247, v[160:163] offset:1024
	ds_write_b128 v247, v[164:167] offset:2048
	ds_write_b128 v247, v[168:171] offset:3072
	ds_read_b128 v[156:159], v248
	ds_read_b128 v[160:163], v249
	ds_read_b128 v[164:167], v250
	ds_read_b128 v[168:171], v251
	ds_write_b128 v112, v[172:175]
	ds_write_b128 v112, v[176:179] offset:1024
	ds_write_b128 v112, v[180:183] offset:2048
	ds_write_b128 v112, v[184:187] offset:3072
	ds_read2_b32 v[32:33], v115 offset0:96 offset1:97
	ds_read2_b32 v[34:35], v115 offset0:98 offset1:99
	ds_read2_b32 v[36:37], v115 offset0:104 offset1:105
	ds_read2_b32 v[38:39], v115 offset0:106 offset1:107
	ds_read2_b32 v[40:41], v115 offset0:112 offset1:113
	ds_read2_b32 v[42:43], v115 offset0:114 offset1:115
	ds_read2_b32 v[44:45], v115 offset0:120 offset1:121
	ds_read2_b32 v[46:47], v115 offset0:122 offset1:123
	s_waitcnt lgkmcnt(0)
; __device__ __forceinline__ int crow(int r, int hi) { return (r & 3) + 8 * (r >> 2) + 4 * hi; }
; __device__ __forceinline__ void dil_unit(LAS unsigned char* lds, bf16_t* proj, int seq, int hd, int T0, int rho) {
;     ...
;     l += __shfl_xor(l, 32);
; #pragma unroll
;     for (int rr = 0; rr < 16; ++rr) {
;         const int j = crow(rr, hi);
;         const float il = __builtin_amdgcn_rcpf(__shfl(l, j));
	v_mfma_f32_32x32x16_bf16 v[32:47], v[156:159], v[48:51], v[32:47]
	ds_read_b64_tr_b16 v[72:73], v231
	ds_read_b64_tr_b16 v[74:75], v231 offset:512
	ds_read_b64_tr_b16 v[76:77], v231 offset:2048
	ds_read_b64_tr_b16 v[78:79], v231 offset:2560
	ds_read_b64_tr_b16 v[220:221], v231 offset:1024
	ds_read_b64_tr_b16 v[222:223], v231 offset:1536
	ds_read_b64_tr_b16 v[224:225], v231 offset:3072
	ds_read_b64_tr_b16 v[226:227], v231 offset:3584
	v_mfma_f32_32x32x16_bf16 v[32:47], v[160:163], v[52:55], v[32:47]
	v_mfma_f32_32x32x16_bf16 v[32:47], v[164:167], v[56:59], v[32:47]
	v_mfma_f32_32x32x16_bf16 v[32:47], v[168:171], v[60:63], v[32:47]
	s_nop 11
	v_exp_f32_e32 v32, v32
	v_exp_f32_e32 v33, v33
	v_exp_f32_e32 v34, v34
	v_exp_f32_e32 v35, v35
	v_exp_f32_e32 v36, v36
	v_exp_f32_e32 v37, v37
	v_exp_f32_e32 v38, v38
	v_exp_f32_e32 v39, v39
	v_exp_f32_e32 v40, v40
	v_exp_f32_e32 v41, v41
	v_exp_f32_e32 v42, v42
	v_exp_f32_e32 v43, v43
	v_exp_f32_e32 v44, v44
	v_exp_f32_e32 v45, v45
	v_exp_f32_e32 v46, v46
	v_exp_f32_e32 v47, v47
	v_cvt_pk_bf16_f32 v64, v32, v33
	v_cvt_pk_bf16_f32 v65, v34, v35
	v_cvt_pk_bf16_f32 v66, v36, v37
	v_cvt_pk_bf16_f32 v67, v38, v39
	v_cvt_pk_bf16_f32 v68, v40, v41
	v_cvt_pk_bf16_f32 v69, v42, v43
	v_cvt_pk_bf16_f32 v70, v44, v45
	v_cvt_pk_bf16_f32 v71, v46, v47
	v_pk_add_f32 v[232:233], v[232:233], v[32:33]
	v_pk_add_f32 v[232:233], v[232:233], v[34:35]
	v_pk_add_f32 v[232:233], v[232:233], v[36:37]
	v_pk_add_f32 v[232:233], v[232:233], v[38:39]
	v_pk_add_f32 v[232:233], v[232:233], v[40:41]
	v_pk_add_f32 v[232:233], v[232:233], v[42:43]
	v_pk_add_f32 v[232:233], v[232:233], v[44:45]
	v_pk_add_f32 v[232:233], v[232:233], v[46:47]
	s_waitcnt lgkmcnt(0)
	v_mfma_f32_32x32x16_bf16 v[0:15], v[64:67], v[72:75], v[0:15]
	v_mfma_f32_32x32x16_bf16 v[16:31], v[64:67], v[76:79], v[16:31]
	v_mfma_f32_32x32x16_bf16 v[0:15], v[68:71], v[220:223], v[0:15]
	v_mfma_f32_32x32x16_bf16 v[16:31], v[68:71], v[224:227], v[16:31]
	s_waitcnt vmcnt(0)
	ds_write_b128 v247, v[188:191]
	ds_write_b128 v247, v[192:195] offset:1024
	ds_write_b128 v247, v[196:199] offset:2048
	ds_write_b128 v247, v[200:203] offset:3072
	ds_read_b128 v[188:191], v248
	ds_read_b128 v[192:195], v249
	ds_read_b128 v[196:199], v250
	ds_read_b128 v[200:203], v251
	ds_write_b128 v112, v[204:207]
	ds_write_b128 v112, v[208:211] offset:1024
	ds_write_b128 v112, v[212:215] offset:2048
	ds_write_b128 v112, v[216:219] offset:3072
	ds_read2_b32 v[32:33], v115 offset0:128 offset1:129
	ds_read2_b32 v[34:35], v115 offset0:130 offset1:131
	ds_read2_b32 v[36:37], v115 offset0:136 offset1:137
	ds_read2_b32 v[38:39], v115 offset0:138 offset1:139
	ds_read2_b32 v[40:41], v115 offset0:144 offset1:145
	ds_read2_b32 v[42:43], v115 offset0:146 offset1:147
	ds_read2_b32 v[44:45], v115 offset0:152 offset1:153
	ds_read2_b32 v[46:47], v115 offset0:154 offset1:155
	s_waitcnt lgkmcnt(0)
	v_mfma_f32_32x32x16_bf16 v[32:47], v[188:191], v[48:51], v[32:47]
	ds_read_b64_tr_b16 v[72:73], v231
	ds_read_b64_tr_b16 v[74:75], v231 offset:512
	ds_read_b64_tr_b16 v[76:77], v231 offset:2048
	ds_read_b64_tr_b16 v[78:79], v231 offset:2560
	ds_read_b64_tr_b16 v[220:221], v231 offset:1024
	ds_read_b64_tr_b16 v[222:223], v231 offset:1536
	ds_read_b64_tr_b16 v[224:225], v231 offset:3072
	ds_read_b64_tr_b16 v[226:227], v231 offset:3584
	v_mfma_f32_32x32x16_bf16 v[32:47], v[192:195], v[52:55], v[32:47]
	v_mfma_f32_32x32x16_bf16 v[32:47], v[196:199], v[56:59], v[32:47]
	v_mfma_f32_32x32x16_bf16 v[32:47], v[200:203], v[60:63], v[32:47]
	s_nop 11
	v_exp_f32_e32 v32, v32
	v_exp_f32_e32 v33, v33
	v_exp_f32_e32 v34, v34
	v_exp_f32_e32 v35, v35
	v_exp_f32_e32 v36, v36
	v_exp_f32_e32 v37, v37
	v_exp_f32_e32 v38, v38
	v_exp_f32_e32 v39, v39
	v_exp_f32_e32 v40, v40
	v_exp_f32_e32 v41, v41
	v_exp_f32_e32 v42, v42
	v_exp_f32_e32 v43, v43
	v_exp_f32_e32 v44, v44
	v_exp_f32_e32 v45, v45
	v_exp_f32_e32 v46, v46
	v_exp_f32_e32 v47, v47
	v_cvt_pk_bf16_f32 v64, v32, v33
	v_cvt_pk_bf16_f32 v65, v34, v35
	v_cvt_pk_bf16_f32 v66, v36, v37
	v_cvt_pk_bf16_f32 v67, v38, v39
	v_cvt_pk_bf16_f32 v68, v40, v41
	v_cvt_pk_bf16_f32 v69, v42, v43
	v_cvt_pk_bf16_f32 v70, v44, v45
	v_cvt_pk_bf16_f32 v71, v46, v47
	v_pk_add_f32 v[232:233], v[232:233], v[32:33]
	v_pk_add_f32 v[232:233], v[232:233], v[34:35]
	v_pk_add_f32 v[232:233], v[232:233], v[36:37]
	v_pk_add_f32 v[232:233], v[232:233], v[38:39]
	v_pk_add_f32 v[232:233], v[232:233], v[40:41]
	v_pk_add_f32 v[232:233], v[232:233], v[42:43]
	v_pk_add_f32 v[232:233], v[232:233], v[44:45]
	v_pk_add_f32 v[232:233], v[232:233], v[46:47]
	s_waitcnt lgkmcnt(0)
	v_mfma_f32_32x32x16_bf16 v[0:15], v[64:67], v[72:75], v[0:15]
	v_mfma_f32_32x32x16_bf16 v[16:31], v[64:67], v[76:79], v[16:31]
	v_mfma_f32_32x32x16_bf16 v[0:15], v[68:71], v[220:223], v[0:15]
	v_mfma_f32_32x32x16_bf16 v[16:31], v[68:71], v[224:227], v[16:31]
	v_add_f32_e32 v113, v232, v233
	v_or_b32_e32 v114, 1, v107
	v_or_b32_e32 v97, 2, v107
	v_or_b32_e32 v96, 3, v107
	v_or_b32_e32 v95, 8, v107
	v_or_b32_e32 v94, 9, v107
	v_or_b32_e32 v93, 10, v107
	v_or_b32_e32 v92, 11, v107
	v_or_b32_e32 v91, 16, v107
	v_or_b32_e32 v90, 17, v107
	v_or_b32_e32 v89, 18, v107
	v_or_b32_e32 v88, 19, v107
	v_or_b32_e32 v87, 24, v107
	v_or_b32_e32 v86, 25, v107
	v_or_b32_e32 v85, 26, v107
	v_or_b32_e32 v84, 27, v107
	s_nop 11
	s_branch .LBB0_553

; #define LAS __attribute__((address_space(3)))
; #define GAS __attribute__((address_space(1)))
; __device__ __forceinline__ void dil_unit(LAS unsigned char* lds, bf16_t* proj, int seq, int hd, int T0, int rho) {
;     ...
;     const int tid = tid_, lane = tid & 63, r32 = lane & 31, hi = lane >> 5, wid = __builtin_amdgcn_readfirstlane(tid >> 6);
;     bf16_t* base = proj + (size_t)seq * SEQ * NIN;
;     LAS unsigned char* wbuf = lds + wid * 4096;
;     const LAS unsigned char* vp = wbuf + ((lane >> 4) & 1) * 32 + (lane & 3) * 8 + (4 * hi + ((lane & 15) >> 2)) * 64;
;     const int P0 = T0 + rho;
;     bf16x8 qr[4];
; #pragma unroll
;     for (int ks = 0; ks < 4; ++ks) qr[ks] = *(const GAS bf16x8*)(base + (size_t)(P0 + 16 * r32) * NIN + PC_LQ + hd * 64 + 16 * ks + 8 * hi);
;     f32x16 o0 = {}, o1 = {}; float l = 0.f;
;     const bool bound = (T0 < 1024) || (T0 >= 15360);
.LBB0_1266:
	s_lshr_b32 s82, s60, 8
	s_mul_i32 s82, s82, 13
	s_add_i32 s82, s82, s60
	s_ashr_i32 s4, s60, 6
	s_mul_hi_i32 s9, s4, 0x2aaaaaab
	s_lshl_b32 s5, s82, 8
	s_lshr_b32 s10, s9, 31
	s_and_b32 s8, s5, 0x3e00
	s_lshl_b32 s5, s82, 3
	s_add_i32 s9, s9, s10
	s_and_b32 s5, s5, 8
	s_mul_i32 s10, s9, 6
	s_add_i32 s5, s5, s61
	s_sub_i32 s10, s4, s10
	s_mul_hi_i32 s4, s9, 0x6000000
	s_mul_i32 s9, s9, 0x6000000
	v_mov_b32_e32 v2, v154
	s_add_u32 s52, s44, s9
	s_addc_u32 s53, s45, s4
	v_and_b32_e32 v105, 31, v2
	s_add_i32 s67, s5, s8
	v_lshl_add_u32 v3, v105, 4, s67
	v_mov_b64_e32 v[0:1], s[52:53]
	s_lshl_b32 s54, s10, 6
	v_bfe_u32 v106, v2, 5, 1
	v_mad_u64_u32 v[0:1], s[4:5], v3, s62, v[0:1]
	s_ashr_i32 s55, s54, 31
	v_lshl_add_u64 v[0:1], s[54:55], 1, v[0:1]
	v_lshlrev_b32_e32 v80, 4, v106
	v_lshl_add_u64 v[0:1], v[0:1], 0, v[80:81]
	global_load_dwordx4 v[48:51], v[0:1], off offset:1280
	global_load_dwordx4 v[52:55], v[0:1], off offset:1312
	global_load_dwordx4 v[56:59], v[0:1], off offset:1344
	global_load_dwordx4 v[60:63], v[0:1], off offset:1376
	v_readfirstlane_b32 s4, v2
	s_lshl_b32 s4, s4, 6
	s_and_b32 s4, s4, 0xfffff000
	v_lshlrev_b32_e32 v0, 1, v2
	v_lshlrev_b32_e32 v104, 3, v2
	v_lshlrev_b32_e32 v107, 2, v106
	v_lshrrev_b32_e32 v1, 2, v2
	v_and_b32_e32 v103, 63, v2
	v_and_b32_e32 v0, 32, v0
	v_and_b32_e32 v98, 24, v104
	v_and_or_b32 v1, v1, 3, v107
	s_add_i32 s69, s4, 0
	v_lshlrev_b32_e32 v108, 6, v1
	v_lshlrev_b32_e32 v1, 3, v106
	v_add3_u32 v109, s69, v0, v98
	s_addk_i32 s8, 0xc400
	v_lshrrev_b32_e32 v110, 2, v103
	v_lshlrev_b32_e32 v0, 4, v103
	s_mov_b64 s[4:5], -1
	s_cmp_gt_u32 s8, 0xffffc7ff
	v_lshlrev_b32_e32 v100, 1, v98
	s_mul_i32 s8, s10, 0x1c00
	v_lshlrev_b32_e32 v82, 1, v1
	v_or_b32_e32 v111, 16, v110
	v_add_u32_e32 v112, s69, v0
	s_cbranch_scc0 .LBB0_1270
	s_movk_i32 s100, 0x1800
	s_add_i32 s101, s8, 0x15c00
	s_lshl_b32 s90, s54, 1
	s_add_u32 s82, s52, s90
	s_addc_u32 s83, s53, 0
	s_add_u32 s82, s82, 0x1200
	s_addc_u32 s83, s83, 0
	s_sub_i32 s90, s67, 64
	s_mul_i32 s90, s90, 0x1800
	s_add_u32 s84, s82, s90
	s_addc_u32 s85, s83, 0
	s_sub_i32 s90, s67, 256
	s_mul_i32 s90, s90, 0x1800
	s_add_u32 s86, s82, s90
	s_addc_u32 s87, s83, 0
	s_sub_i32 s90, s67, 1024
	s_mul_i32 s90, s90, 0x1800
	s_add_u32 s88, s82, s90
	s_addc_u32 s89, s83, 0
	v_lshlrev_b32_e32 v153, 1, v98
	v_mad_u32_u24 v80, v105, s100, v82
	v_mad_u32_u24 v100, v110, s100, v153
	v_add_u32_e32 v149, 0x18000, v100
	v_lshlrev_b32_e32 v83, 2, v105
	v_mad_u32_u24 v83, v83, s100, v82
	v_lshlrev_b32_e32 v101, 2, v110
	v_mad_u32_u24 v101, v101, s100, v153
	v_add_u32_e32 v150, 0x60000, v101
	v_lshlrev_b32_e32 v99, 4, v105
	v_mad_u32_u24 v99, v99, s100, v82
	v_lshlrev_b32_e32 v148, 4, v110
	v_mad_u32_u24 v148, v148, s100, v153
	v_add_u32_e32 v151, 0x180000, v148
	v_lshrrev_b32_e32 v249, 3, v103
	v_and_b32_e32 v250, 7, v103
	v_lshlrev_b32_e32 v250, 4, v250
	v_add_u32_e32 v235, 0, v249
	v_mad_u32_u24 v235, v235, s100, v250
	v_add_u32_e32 v236, 8, v249
	v_mad_u32_u24 v236, v236, s100, v250
	v_add_u32_e32 v237, 16, v249
	v_mad_u32_u24 v237, v237, s100, v250
	v_add_u32_e32 v238, 24, v249
	v_mad_u32_u24 v238, v238, s100, v250
	v_add_u32_e32 v239, 0, v249
	v_lshlrev_b32_e32 v239, 2, v239
	v_mad_u32_u24 v239, v239, s100, v250
	v_add_u32_e32 v240, 8, v249
	v_lshlrev_b32_e32 v240, 2, v240
	v_mad_u32_u24 v240, v240, s100, v250
	v_add_u32_e32 v241, 16, v249
	v_lshlrev_b32_e32 v241, 2, v241
	v_mad_u32_u24 v241, v241, s100, v250
	v_add_u32_e32 v242, 24, v249
	v_lshlrev_b32_e32 v242, 2, v242
	v_mad_u32_u24 v242, v242, s100, v250
	v_add_u32_e32 v243, 0, v249
	v_lshlrev_b32_e32 v243, 4, v243
	v_mad_u32_u24 v243, v243, s100, v250
	v_add_u32_e32 v244, 8, v249
	v_lshlrev_b32_e32 v244, 4, v244
	v_mad_u32_u24 v244, v244, s100, v250
	v_add_u32_e32 v245, 16, v249
	v_lshlrev_b32_e32 v245, 4, v245
	v_mad_u32_u24 v245, v245, s100, v250
	v_add_u32_e32 v246, 24, v249
	v_lshlrev_b32_e32 v246, 4, v246
	v_mad_u32_u24 v246, v246, s100, v250
	v_and_b32_e32 v247, 7, v249
	v_lshlrev_b32_e32 v247, 4, v247
	v_xor_b32_e32 v247, v247, v112
	v_and_b32_e32 v153, 7, v105
	v_or_b32_e32 v248, 0, v106
	v_xor_b32_e32 v248, v248, v153
	v_lshlrev_b32_e32 v248, 4, v248
	v_lshl_add_u32 v248, v105, 7, v248
	v_add_u32_e32 v248, s69, v248
	v_or_b32_e32 v249, 2, v106
	v_xor_b32_e32 v249, v249, v153
	v_lshlrev_b32_e32 v249, 4, v249
	v_lshl_add_u32 v249, v105, 7, v249
	v_add_u32_e32 v249, s69, v249
	v_or_b32_e32 v250, 4, v106
	v_xor_b32_e32 v250, v250, v153
	v_lshlrev_b32_e32 v250, 4, v250
	v_lshl_add_u32 v250, v105, 7, v250
	v_add_u32_e32 v250, s69, v250
	v_or_b32_e32 v251, 6, v106
	v_xor_b32_e32 v251, v251, v153
	v_lshlrev_b32_e32 v251, 4, v251
	v_lshl_add_u32 v251, v105, 7, v251
	v_add_u32_e32 v251, s69, v251
	v_lshlrev_b32_e32 v153, 1, v98
	v_mul_u32_u24_e32 v228, 17, v105
	v_sub_u32_e32 v228, v107, v228
	s_mul_i32 s90, s54, 153
	s_lshr_b32 s90, s90, 1
	s_add_i32 s90, s90, 34876
	v_lshl_add_u32 v228, v228, 2, s90
	v_lshlrev_b32_e32 v229, 2, v105
	v_sub_u32_e32 v229, v107, v229
	s_add_i32 s90, s101, 5104
	v_lshl_add_u32 v229, v229, 2, s90
	v_sub_u32_e32 v230, v107, v105
	s_add_i32 s90, s101, 6364
	v_lshl_add_u32 v230, v230, 2, s90
	v_add_u32_e32 v231, v109, v108
	v_mov_b64_e32 v[232:233], 0
	v_mov_b64_e32 v[0:1], 0
	v_mov_b64_e32 v[2:3], 0
	v_mov_b64_e32 v[4:5], 0
	v_mov_b64_e32 v[6:7], 0
	v_mov_b64_e32 v[8:9], 0
	v_mov_b64_e32 v[10:11], 0
	v_mov_b64_e32 v[12:13], 0
	v_mov_b64_e32 v[14:15], 0
	v_mov_b64_e32 v[16:17], 0
	v_mov_b64_e32 v[18:19], 0
	v_mov_b64_e32 v[20:21], 0
	v_mov_b64_e32 v[22:23], 0
	v_mov_b64_e32 v[24:25], 0
	v_mov_b64_e32 v[26:27], 0
	v_mov_b64_e32 v[28:29], 0
	v_mov_b64_e32 v[30:31], 0
	global_load_dwordx4 v[116:119], v235, s[84:85]
	global_load_dwordx4 v[120:123], v236, s[84:85]
	global_load_dwordx4 v[124:127], v237, s[84:85]
	global_load_dwordx4 v[128:131], v238, s[84:85]
	global_load_dwordx4 v[132:135], v100, s[84:85] offset:768
	global_load_dwordx4 v[136:139], v149, s[84:85] offset:768
	global_load_dwordx4 v[140:143], v100, s[84:85] offset:832
	global_load_dwordx4 v[144:147], v149, s[84:85] offset:832
	s_add_u32 s84, s84, 0x30000
	s_addc_u32 s85, s85, 0
	global_load_dwordx4 v[156:159], v235, s[84:85]
	global_load_dwordx4 v[160:163], v236, s[84:85]
	global_load_dwordx4 v[164:167], v237, s[84:85]
	global_load_dwordx4 v[168:171], v238, s[84:85]
	global_load_dwordx4 v[172:175], v100, s[84:85] offset:768
	global_load_dwordx4 v[176:179], v149, s[84:85] offset:768
	global_load_dwordx4 v[180:183], v100, s[84:85] offset:832
	global_load_dwordx4 v[184:187], v149, s[84:85] offset:832
	s_add_u32 s84, s84, 0x30000
	s_addc_u32 s85, s85, 0
	global_load_dwordx4 v[188:191], v235, s[84:85]
	global_load_dwordx4 v[192:195], v236, s[84:85]
	global_load_dwordx4 v[196:199], v237, s[84:85]
	global_load_dwordx4 v[200:203], v238, s[84:85]
	global_load_dwordx4 v[204:207], v100, s[84:85] offset:768
	global_load_dwordx4 v[208:211], v149, s[84:85] offset:768
	global_load_dwordx4 v[212:215], v100, s[84:85] offset:832
	global_load_dwordx4 v[216:219], v149, s[84:85] offset:832
	s_add_u32 s84, s84, 0x30000
	s_addc_u32 s85, s85, 0
	s_waitcnt vmcnt(16)
	ds_write_b128 v247, v[116:119]
	ds_write_b128 v247, v[120:123] offset:1024
	ds_write_b128 v247, v[124:127] offset:2048
	ds_write_b128 v247, v[128:131] offset:3072
	ds_read_b128 v[116:119], v248
	ds_read_b128 v[120:123], v249
	ds_read_b128 v[124:127], v250
	ds_read_b128 v[128:131], v251
	ds_write_b128 v112, v[132:135]
	ds_write_b128 v112, v[136:139] offset:1024
	ds_write_b128 v112, v[140:143] offset:2048
	ds_write_b128 v112, v[144:147] offset:3072
	v_mov_b32_e32 v115, v228
	ds_read2_b32 v[32:33], v115 offset0:0 offset1:1
	ds_read2_b32 v[34:35], v115 offset0:2 offset1:3
	ds_read2_b32 v[36:37], v115 offset0:8 offset1:9
	ds_read2_b32 v[38:39], v115 offset0:10 offset1:11
	ds_read2_b32 v[40:41], v115 offset0:17 offset1:18
	ds_read2_b32 v[42:43], v115 offset0:19 offset1:20
	ds_read2_b32 v[44:45], v115 offset0:25 offset1:26
	ds_read2_b32 v[46:47], v115 offset0:27 offset1:28
	s_waitcnt lgkmcnt(0)
	v_mfma_f32_32x32x16_bf16 v[32:47], v[116:119], v[48:51], v[32:47]
	ds_read_b64_tr_b16 v[72:73], v231
	ds_read_b64_tr_b16 v[74:75], v231 offset:512
	ds_read_b64_tr_b16 v[76:77], v231 offset:2048
	ds_read_b64_tr_b16 v[78:79], v231 offset:2560
	ds_read_b64_tr_b16 v[220:221], v231 offset:1024
	ds_read_b64_tr_b16 v[222:223], v231 offset:1536
	ds_read_b64_tr_b16 v[224:225], v231 offset:3072
	ds_read_b64_tr_b16 v[226:227], v231 offset:3584
	v_mfma_f32_32x32x16_bf16 v[32:47], v[120:123], v[52:55], v[32:47]
	v_mfma_f32_32x32x16_bf16 v[32:47], v[124:127], v[56:59], v[32:47]
	v_mfma_f32_32x32x16_bf16 v[32:47], v[128:131], v[60:63], v[32:47]
	s_nop 11
	v_exp_f32_e32 v32, v32
	v_exp_f32_e32 v33, v33
	v_exp_f32_e32 v34, v34
	v_exp_f32_e32 v35, v35
	v_exp_f32_e32 v36, v36
	v_exp_f32_e32 v37, v37
	v_exp_f32_e32 v38, v38
	v_exp_f32_e32 v39, v39
	v_exp_f32_e32 v40, v40
	v_exp_f32_e32 v41, v41
	v_exp_f32_e32 v42, v42
	v_exp_f32_e32 v43, v43
	v_exp_f32_e32 v44, v44
	v_exp_f32_e32 v45, v45
	v_exp_f32_e32 v46, v46
	v_exp_f32_e32 v47, v47
	v_cvt_pk_bf16_f32 v64, v32, v33
	v_cvt_pk_bf16_f32 v65, v34, v35
	v_cvt_pk_bf16_f32 v66, v36, v37
	v_cvt_pk_bf16_f32 v67, v38, v39
	v_cvt_pk_bf16_f32 v68, v40, v41
	v_cvt_pk_bf16_f32 v69, v42, v43
	v_cvt_pk_bf16_f32 v70, v44, v45
	v_cvt_pk_bf16_f32 v71, v46, v47
	v_pk_add_f32 v[232:233], v[232:233], v[32:33]
	v_pk_add_f32 v[232:233], v[232:233], v[34:35]
	v_pk_add_f32 v[232:233], v[232:233], v[36:37]
	v_pk_add_f32 v[232:233], v[232:233], v[38:39]
	v_pk_add_f32 v[232:233], v[232:233], v[40:41]
	v_pk_add_f32 v[232:233], v[232:233], v[42:43]
	v_pk_add_f32 v[232:233], v[232:233], v[44:45]
	v_pk_add_f32 v[232:233], v[232:233], v[46:47]
	s_waitcnt lgkmcnt(0)
	v_mfma_f32_32x32x16_bf16 v[0:15], v[64:67], v[72:75], v[0:15]
	v_mfma_f32_32x32x16_bf16 v[16:31], v[64:67], v[76:79], v[16:31]
	v_mfma_f32_32x32x16_bf16 v[0:15], v[68:71], v[220:223], v[0:15]
	v_mfma_f32_32x32x16_bf16 v[16:31], v[68:71], v[224:227], v[16:31]
	global_load_dwordx4 v[116:119], v235, s[84:85]
	global_load_dwordx4 v[120:123], v236, s[84:85]
	global_load_dwordx4 v[124:127], v237, s[84:85]
	global_load_dwordx4 v[128:131], v238, s[84:85]
	global_load_dwordx4 v[132:135], v100, s[84:85] offset:768
	global_load_dwordx4 v[136:139], v149, s[84:85] offset:768
	global_load_dwordx4 v[140:143], v100, s[84:85] offset:832
	global_load_dwordx4 v[144:147], v149, s[84:85] offset:832
	s_add_u32 s84, s84, 0x30000
	s_addc_u32 s85, s85, 0
	s_waitcnt vmcnt(16)
	ds_write_b128 v247, v[156:159]
	ds_write_b128 v247, v[160:163] offset:1024
	ds_write_b128 v247, v[164:167] offset:2048
	ds_write_b128 v247, v[168:171] offset:3072
	ds_read_b128 v[156:159], v248
	ds_read_b128 v[160:163], v249
	ds_read_b128 v[164:167], v250
	ds_read_b128 v[168:171], v251
	ds_write_b128 v112, v[172:175]
	ds_write_b128 v112, v[176:179] offset:1024
	ds_write_b128 v112, v[180:183] offset:2048
	ds_write_b128 v112, v[184:187] offset:3072
	ds_read2_b32 v[32:33], v115 offset0:34 offset1:35
	ds_read2_b32 v[34:35], v115 offset0:36 offset1:37
	ds_read2_b32 v[36:37], v115 offset0:42 offset1:43
	ds_read2_b32 v[38:39], v115 offset0:44 offset1:45
	ds_read2_b32 v[40:41], v115 offset0:51 offset1:52
	ds_read2_b32 v[42:43], v115 offset0:53 offset1:54
	ds_read2_b32 v[44:45], v115 offset0:59 offset1:60
	ds_read2_b32 v[46:47], v115 offset0:61 offset1:62
	s_waitcnt lgkmcnt(0)
	v_mfma_f32_32x32x16_bf16 v[32:47], v[156:159], v[48:51], v[32:47]
	ds_read_b64_tr_b16 v[72:73], v231
	ds_read_b64_tr_b16 v[74:75], v231 offset:512
	ds_read_b64_tr_b16 v[76:77], v231 offset:2048
	ds_read_b64_tr_b16 v[78:79], v231 offset:2560
	ds_read_b64_tr_b16 v[220:221], v231 offset:1024
	ds_read_b64_tr_b16 v[222:223], v231 offset:1536
	ds_read_b64_tr_b16 v[224:225], v231 offset:3072
	ds_read_b64_tr_b16 v[226:227], v231 offset:3584
	v_mfma_f32_32x32x16_bf16 v[32:47], v[160:163], v[52:55], v[32:47]
	v_mfma_f32_32x32x16_bf16 v[32:47], v[164:167], v[56:59], v[32:47]
	v_mfma_f32_32x32x16_bf16 v[32:47], v[168:171], v[60:63], v[32:47]
	s_nop 11
	v_exp_f32_e32 v32, v32
	v_exp_f32_e32 v33, v33
	v_exp_f32_e32 v34, v34
	v_exp_f32_e32 v35, v35
	v_exp_f32_e32 v36, v36
	v_exp_f32_e32 v37, v37
	v_exp_f32_e32 v38, v38
	v_exp_f32_e32 v39, v39
	v_exp_f32_e32 v40, v40
	v_exp_f32_e32 v41, v41
	v_exp_f32_e32 v42, v42
	v_exp_f32_e32 v43, v43
	v_exp_f32_e32 v44, v44
	v_exp_f32_e32 v45, v45
	v_exp_f32_e32 v46, v46
	v_exp_f32_e32 v47, v47
	v_cvt_pk_bf16_f32 v64, v32, v33
	v_cvt_pk_bf16_f32 v65, v34, v35
	v_cvt_pk_bf16_f32 v66, v36, v37
	v_cvt_pk_bf16_f32 v67, v38, v39
	v_cvt_pk_bf16_f32 v68, v40, v41
	v_cvt_pk_bf16_f32 v69, v42, v43
	v_cvt_pk_bf16_f32 v70, v44, v45
	v_cvt_pk_bf16_f32 v71, v46, v47
	v_pk_add_f32 v[232:233], v[232:233], v[32:33]
	v_pk_add_f32 v[232:233], v[232:233], v[34:35]
	v_pk_add_f32 v[232:233], v[232:233], v[36:37]
	v_pk_add_f32 v[232:233], v[232:233], v[38:39]
	v_pk_add_f32 v[232:233], v[232:233], v[40:41]
	v_pk_add_f32 v[232:233], v[232:233], v[42:43]
	v_pk_add_f32 v[232:233], v[232:233], v[44:45]
	v_pk_add_f32 v[232:233], v[232:233], v[46:47]
	s_waitcnt lgkmcnt(0)
	v_mfma_f32_32x32x16_bf16 v[0:15], v[64:67], v[72:75], v[0:15]
	v_mfma_f32_32x32x16_bf16 v[16:31], v[64:67], v[76:79], v[16:31]
	v_mfma_f32_32x32x16_bf16 v[0:15], v[68:71], v[220:223], v[0:15]
	v_mfma_f32_32x32x16_bf16 v[16:31], v[68:71], v[224:227], v[16:31]
	global_load_dwordx4 v[156:159], v235, s[84:85]
	global_load_dwordx4 v[160:163], v236, s[84:85]
	global_load_dwordx4 v[164:167], v237, s[84:85]
	global_load_dwordx4 v[168:171], v238, s[84:85]
	global_load_dwordx4 v[172:175], v100, s[84:85] offset:768
	global_load_dwordx4 v[176:179], v149, s[84:85] offset:768
	global_load_dwordx4 v[180:183], v100, s[84:85] offset:832
	global_load_dwordx4 v[184:187], v149, s[84:85] offset:832
	s_add_u32 s84, s84, 0x30000
	s_addc_u32 s85, s85, 0
	s_waitcnt vmcnt(16)
	ds_write_b128 v247, v[188:191]
	ds_write_b128 v247, v[192:195] offset:1024
	ds_write_b128 v247, v[196:199] offset:2048
	ds_write_b128 v247, v[200:203] offset:3072
	ds_read_b128 v[188:191], v248
	ds_read_b128 v[192:195], v249
	ds_read_b128 v[196:199], v250
	ds_read_b128 v[200:203], v251
	ds_write_b128 v112, v[204:207]
	ds_write_b128 v112, v[208:211] offset:1024
	ds_write_b128 v112, v[212:215] offset:2048
	ds_write_b128 v112, v[216:219] offset:3072
	ds_read2_b32 v[32:33], v115 offset0:68 offset1:69
	ds_read2_b32 v[34:35], v115 offset0:70 offset1:71
	ds_read2_b32 v[36:37], v115 offset0:76 offset1:77
	ds_read2_b32 v[38:39], v115 offset0:78 offset1:79
	ds_read2_b32 v[40:41], v115 offset0:85 offset1:86
	ds_read2_b32 v[42:43], v115 offset0:87 offset1:88
	ds_read2_b32 v[44:45], v115 offset0:93 offset1:94
	ds_read2_b32 v[46:47], v115 offset0:95 offset1:96
	s_waitcnt lgkmcnt(0)
	v_mfma_f32_32x32x16_bf16 v[32:47], v[188:191], v[48:51], v[32:47]
	ds_read_b64_tr_b16 v[72:73], v231
	ds_read_b64_tr_b16 v[74:75], v231 offset:512
	ds_read_b64_tr_b16 v[76:77], v231 offset:2048
	ds_read_b64_tr_b16 v[78:79], v231 offset:2560
	ds_read_b64_tr_b16 v[220:221], v231 offset:1024
	ds_read_b64_tr_b16 v[222:223], v231 offset:1536
	ds_read_b64_tr_b16 v[224:225], v231 offset:3072
	ds_read_b64_tr_b16 v[226:227], v231 offset:3584
	v_mfma_f32_32x32x16_bf16 v[32:47], v[192:195], v[52:55], v[32:47]
	v_mfma_f32_32x32x16_bf16 v[32:47], v[196:199], v[56:59], v[32:47]
	v_mfma_f32_32x32x16_bf16 v[32:47], v[200:203], v[60:63], v[32:47]
	s_nop 11
	v_exp_f32_e32 v32, v32
	v_exp_f32_e32 v33, v33
	v_exp_f32_e32 v34, v34
	v_exp_f32_e32 v35, v35
	v_exp_f32_e32 v36, v36
	v_exp_f32_e32 v37, v37
	v_exp_f32_e32 v38, v38
	v_exp_f32_e32 v39, v39
	v_exp_f32_e32 v40, v40
	v_exp_f32_e32 v41, v41
	v_exp_f32_e32 v42, v42
	v_exp_f32_e32 v43, v43
	v_exp_f32_e32 v44, v44
	v_exp_f32_e32 v45, v45
	v_exp_f32_e32 v46, v46
	v_exp_f32_e32 v47, v47
	v_cvt_pk_bf16_f32 v64, v32, v33
	v_cvt_pk_bf16_f32 v65, v34, v35
	v_cvt_pk_bf16_f32 v66, v36, v37
	v_cvt_pk_bf16_f32 v67, v38, v39
	v_cvt_pk_bf16_f32 v68, v40, v41
	v_cvt_pk_bf16_f32 v69, v42, v43
	v_cvt_pk_bf16_f32 v70, v44, v45
	v_cvt_pk_bf16_f32 v71, v46, v47
	v_pk_add_f32 v[232:233], v[232:233], v[32:33]
	v_pk_add_f32 v[232:233], v[232:233], v[34:35]
	v_pk_add_f32 v[232:233], v[232:233], v[36:37]
	v_pk_add_f32 v[232:233], v[232:233], v[38:39]
	v_pk_add_f32 v[232:233], v[232:233], v[40:41]
	v_pk_add_f32 v[232:233], v[232:233], v[42:43]
	v_pk_add_f32 v[232:233], v[232:233], v[44:45]
	v_pk_add_f32 v[232:233], v[232:233], v[46:47]
	s_waitcnt lgkmcnt(0)
	v_mfma_f32_32x32x16_bf16 v[0:15], v[64:67], v[72:75], v[0:15]
	v_mfma_f32_32x32x16_bf16 v[16:31], v[64:67], v[76:79], v[16:31]
	v_mfma_f32_32x32x16_bf16 v[0:15], v[68:71], v[220:223], v[0:15]
	v_mfma_f32_32x32x16_bf16 v[16:31], v[68:71], v[224:227], v[16:31]
	global_load_dwordx4 v[188:191], v235, s[84:85]
	global_load_dwordx4 v[192:195], v236, s[84:85]
	global_load_dwordx4 v[196:199], v237, s[84:85]
	global_load_dwordx4 v[200:203], v238, s[84:85]
	global_load_dwordx4 v[204:207], v100, s[84:85] offset:768
	global_load_dwordx4 v[208:211], v149, s[84:85] offset:768
	global_load_dwordx4 v[212:215], v100, s[84:85] offset:832
	global_load_dwordx4 v[216:219], v149, s[84:85] offset:832
	s_add_u32 s84, s84, 0x30000
	s_addc_u32 s85, s85, 0
	s_waitcnt vmcnt(16)
	ds_write_b128 v247, v[116:119]
	ds_write_b128 v247, v[120:123] offset:1024
	ds_write_b128 v247, v[124:127] offset:2048
	ds_write_b128 v247, v[128:131] offset:3072
	ds_read_b128 v[116:119], v248
	ds_read_b128 v[120:123], v249
	ds_read_b128 v[124:127], v250
	ds_read_b128 v[128:131], v251
	ds_write_b128 v112, v[132:135]
	ds_write_b128 v112, v[136:139] offset:1024
	ds_write_b128 v112, v[140:143] offset:2048
	ds_write_b128 v112, v[144:147] offset:3072
	ds_read2_b32 v[32:33], v115 offset0:102 offset1:103
	ds_read2_b32 v[34:35], v115 offset0:104 offset1:105
	ds_read2_b32 v[36:37], v115 offset0:110 offset1:111
	ds_read2_b32 v[38:39], v115 offset0:112 offset1:113
	ds_read2_b32 v[40:41], v115 offset0:119 offset1:120
	ds_read2_b32 v[42:43], v115 offset0:121 offset1:122
	ds_read2_b32 v[44:45], v115 offset0:127 offset1:128
	ds_read2_b32 v[46:47], v115 offset0:129 offset1:130
	s_waitcnt lgkmcnt(0)
	v_mfma_f32_32x32x16_bf16 v[32:47], v[116:119], v[48:51], v[32:47]
	ds_read_b64_tr_b16 v[72:73], v231
	ds_read_b64_tr_b16 v[74:75], v231 offset:512
	ds_read_b64_tr_b16 v[76:77], v231 offset:2048
	ds_read_b64_tr_b16 v[78:79], v231 offset:2560
	ds_read_b64_tr_b16 v[220:221], v231 offset:1024
	ds_read_b64_tr_b16 v[222:223], v231 offset:1536
	ds_read_b64_tr_b16 v[224:225], v231 offset:3072
	ds_read_b64_tr_b16 v[226:227], v231 offset:3584
	v_mfma_f32_32x32x16_bf16 v[32:47], v[120:123], v[52:55], v[32:47]
	v_mfma_f32_32x32x16_bf16 v[32:47], v[124:127], v[56:59], v[32:47]
	v_mfma_f32_32x32x16_bf16 v[32:47], v[128:131], v[60:63], v[32:47]
	s_nop 11
	v_exp_f32_e32 v32, v32
	v_exp_f32_e32 v33, v33
	v_exp_f32_e32 v34, v34
	v_exp_f32_e32 v35, v35
	v_exp_f32_e32 v36, v36
	v_exp_f32_e32 v37, v37
	v_exp_f32_e32 v38, v38
	v_exp_f32_e32 v39, v39
	v_exp_f32_e32 v40, v40
	v_exp_f32_e32 v41, v41
	v_exp_f32_e32 v42, v42
	v_exp_f32_e32 v43, v43
	v_exp_f32_e32 v44, v44
	v_exp_f32_e32 v45, v45
	v_exp_f32_e32 v46, v46
	v_exp_f32_e32 v47, v47
	v_cvt_pk_bf16_f32 v64, v32, v33
	v_cvt_pk_bf16_f32 v65, v34, v35
	v_cvt_pk_bf16_f32 v66, v36, v37
	v_cvt_pk_bf16_f32 v67, v38, v39
	v_cvt_pk_bf16_f32 v68, v40, v41
	v_cvt_pk_bf16_f32 v69, v42, v43
	v_cvt_pk_bf16_f32 v70, v44, v45
	v_cvt_pk_bf16_f32 v71, v46, v47
	v_pk_add_f32 v[232:233], v[232:233], v[32:33]
	v_pk_add_f32 v[232:233], v[232:233], v[34:35]
	v_pk_add_f32 v[232:233], v[232:233], v[36:37]
	v_pk_add_f32 v[232:233], v[232:233], v[38:39]
	v_pk_add_f32 v[232:233], v[232:233], v[40:41]
	v_pk_add_f32 v[232:233], v[232:233], v[42:43]
	v_pk_add_f32 v[232:233], v[232:233], v[44:45]
	v_pk_add_f32 v[232:233], v[232:233], v[46:47]
	s_waitcnt lgkmcnt(0)
	v_mfma_f32_32x32x16_bf16 v[0:15], v[64:67], v[72:75], v[0:15]
	v_mfma_f32_32x32x16_bf16 v[16:31], v[64:67], v[76:79], v[16:31]
	v_mfma_f32_32x32x16_bf16 v[0:15], v[68:71], v[220:223], v[0:15]
	v_mfma_f32_32x32x16_bf16 v[16:31], v[68:71], v[224:227], v[16:31]
	global_load_dwordx4 v[116:119], v235, s[84:85]
	global_load_dwordx4 v[120:123], v236, s[84:85]
	global_load_dwordx4 v[124:127], v237, s[84:85]
	global_load_dwordx4 v[128:131], v238, s[84:85]
	global_load_dwordx4 v[132:135], v100, s[84:85] offset:768
	global_load_dwordx4 v[136:139], v149, s[84:85] offset:768
	global_load_dwordx4 v[140:143], v100, s[84:85] offset:832
	global_load_dwordx4 v[144:147], v149, s[84:85] offset:832
	s_add_u32 s84, s84, 0x30000
	s_addc_u32 s85, s85, 0
	s_waitcnt vmcnt(16)
	ds_write_b128 v247, v[156:159]
	ds_write_b128 v247, v[160:163] offset:1024
	ds_write_b128 v247, v[164:167] offset:2048
	ds_write_b128 v247, v[168:171] offset:3072
	ds_read_b128 v[156:159], v248
	ds_read_b128 v[160:163], v249
	ds_read_b128 v[164:167], v250
	ds_read_b128 v[168:171], v251
	ds_write_b128 v112, v[172:175]
	ds_write_b128 v112, v[176:179] offset:1024
	ds_write_b128 v112, v[180:183] offset:2048
	ds_write_b128 v112, v[184:187] offset:3072
	ds_read2_b32 v[32:33], v115 offset0:136 offset1:137
	ds_read2_b32 v[34:35], v115 offset0:138 offset1:139
	ds_read2_b32 v[36:37], v115 offset0:144 offset1:145
	ds_read2_b32 v[38:39], v115 offset0:146 offset1:147
	ds_read2_b32 v[40:41], v115 offset0:153 offset1:154
	ds_read2_b32 v[42:43], v115 offset0:155 offset1:156
	ds_read2_b32 v[44:45], v115 offset0:161 offset1:162
	ds_read2_b32 v[46:47], v115 offset0:163 offset1:164
	s_waitcnt lgkmcnt(0)
	v_mfma_f32_32x32x16_bf16 v[32:47], v[156:159], v[48:51], v[32:47]
	ds_read_b64_tr_b16 v[72:73], v231
	ds_read_b64_tr_b16 v[74:75], v231 offset:512
	ds_read_b64_tr_b16 v[76:77], v231 offset:2048
	ds_read_b64_tr_b16 v[78:79], v231 offset:2560
	ds_read_b64_tr_b16 v[220:221], v231 offset:1024
	ds_read_b64_tr_b16 v[222:223], v231 offset:1536
	ds_read_b64_tr_b16 v[224:225], v231 offset:3072
	ds_read_b64_tr_b16 v[226:227], v231 offset:3584
	v_mfma_f32_32x32x16_bf16 v[32:47], v[160:163], v[52:55], v[32:47]
	v_mfma_f32_32x32x16_bf16 v[32:47], v[164:167], v[56:59], v[32:47]
	v_mfma_f32_32x32x16_bf16 v[32:47], v[168:171], v[60:63], v[32:47]
	s_nop 11
	v_exp_f32_e32 v32, v32
	v_exp_f32_e32 v33, v33
	v_exp_f32_e32 v34, v34
	v_exp_f32_e32 v35, v35
	v_exp_f32_e32 v36, v36
	v_exp_f32_e32 v37, v37
	v_exp_f32_e32 v38, v38
	v_exp_f32_e32 v39, v39
	v_exp_f32_e32 v40, v40
	v_exp_f32_e32 v41, v41
	v_exp_f32_e32 v42, v42
	v_exp_f32_e32 v43, v43
	v_exp_f32_e32 v44, v44
	v_exp_f32_e32 v45, v45
	v_exp_f32_e32 v46, v46
	v_exp_f32_e32 v47, v47
	v_cvt_pk_bf16_f32 v64, v32, v33
	v_cvt_pk_bf16_f32 v65, v34, v35
	v_cvt_pk_bf16_f32 v66, v36, v37
	v_cvt_pk_bf16_f32 v67, v38, v39
	v_cvt_pk_bf16_f32 v68, v40, v41
	v_cvt_pk_bf16_f32 v69, v42, v43
	v_cvt_pk_bf16_f32 v70, v44, v45
	v_cvt_pk_bf16_f32 v71, v46, v47
	v_pk_add_f32 v[232:233], v[232:233], v[32:33]
	v_pk_add_f32 v[232:233], v[232:233], v[34:35]
	v_pk_add_f32 v[232:233], v[232:233], v[36:37]
	v_pk_add_f32 v[232:233], v[232:233], v[38:39]
	v_pk_add_f32 v[232:233], v[232:233], v[40:41]
	v_pk_add_f32 v[232:233], v[232:233], v[42:43]
	v_pk_add_f32 v[232:233], v[232:233], v[44:45]
	v_pk_add_f32 v[232:233], v[232:233], v[46:47]
	s_waitcnt lgkmcnt(0)
	v_mfma_f32_32x32x16_bf16 v[0:15], v[64:67], v[72:75], v[0:15]
	v_mfma_f32_32x32x16_bf16 v[16:31], v[64:67], v[76:79], v[16:31]
	v_mfma_f32_32x32x16_bf16 v[0:15], v[68:71], v[220:223], v[0:15]
	v_mfma_f32_32x32x16_bf16 v[16:31], v[68:71], v[224:227], v[16:31]
	global_load_dwordx4 v[156:159], v235, s[84:85]
	global_load_dwordx4 v[160:163], v236, s[84:85]
	global_load_dwordx4 v[164:167], v237, s[84:85]
	global_load_dwordx4 v[168:171], v238, s[84:85]
	global_load_dwordx4 v[172:175], v100, s[84:85] offset:768
	global_load_dwordx4 v[176:179], v149, s[84:85] offset:768
	global_load_dwordx4 v[180:183], v100, s[84:85] offset:832
	global_load_dwordx4 v[184:187], v149, s[84:85] offset:832
	s_add_u32 s84, s84, 0x30000
	s_addc_u32 s85, s85, 0
	s_waitcnt vmcnt(16)
	ds_write_b128 v247, v[188:191]
	ds_write_b128 v247, v[192:195] offset:1024
	ds_write_b128 v247, v[196:199] offset:2048
	ds_write_b128 v247, v[200:203] offset:3072
	ds_read_b128 v[188:191], v248
	ds_read_b128 v[192:195], v249
	ds_read_b128 v[196:199], v250
	ds_read_b128 v[200:203], v251
	ds_write_b128 v112, v[204:207]
	ds_write_b128 v112, v[208:211] offset:1024
	ds_write_b128 v112, v[212:215] offset:2048
	ds_write_b128 v112, v[216:219] offset:3072
	ds_read2_b32 v[32:33], v115 offset0:170 offset1:171
	ds_read2_b32 v[34:35], v115 offset0:172 offset1:173
	ds_read2_b32 v[36:37], v115 offset0:178 offset1:179
	ds_read2_b32 v[38:39], v115 offset0:180 offset1:181
	ds_read2_b32 v[40:41], v115 offset0:187 offset1:188
	ds_read2_b32 v[42:43], v115 offset0:189 offset1:190
	ds_read2_b32 v[44:45], v115 offset0:195 offset1:196
	ds_read2_b32 v[46:47], v115 offset0:197 offset1:198
	s_waitcnt lgkmcnt(0)
	v_mfma_f32_32x32x16_bf16 v[32:47], v[188:191], v[48:51], v[32:47]
	ds_read_b64_tr_b16 v[72:73], v231
	ds_read_b64_tr_b16 v[74:75], v231 offset:512
	ds_read_b64_tr_b16 v[76:77], v231 offset:2048
	ds_read_b64_tr_b16 v[78:79], v231 offset:2560
	ds_read_b64_tr_b16 v[220:221], v231 offset:1024
	ds_read_b64_tr_b16 v[222:223], v231 offset:1536
	ds_read_b64_tr_b16 v[224:225], v231 offset:3072
	ds_read_b64_tr_b16 v[226:227], v231 offset:3584
	v_mfma_f32_32x32x16_bf16 v[32:47], v[192:195], v[52:55], v[32:47]
	v_mfma_f32_32x32x16_bf16 v[32:47], v[196:199], v[56:59], v[32:47]
	v_mfma_f32_32x32x16_bf16 v[32:47], v[200:203], v[60:63], v[32:47]
	s_nop 11
	v_exp_f32_e32 v32, v32
	v_exp_f32_e32 v33, v33
	v_exp_f32_e32 v34, v34
	v_exp_f32_e32 v35, v35
	v_exp_f32_e32 v36, v36
	v_exp_f32_e32 v37, v37
	v_exp_f32_e32 v38, v38
	v_exp_f32_e32 v39, v39
	v_exp_f32_e32 v40, v40
	v_exp_f32_e32 v41, v41
	v_exp_f32_e32 v42, v42
	v_exp_f32_e32 v43, v43
	v_exp_f32_e32 v44, v44
	v_exp_f32_e32 v45, v45
	v_exp_f32_e32 v46, v46
	v_exp_f32_e32 v47, v47
	v_cvt_pk_bf16_f32 v64, v32, v33
	v_cvt_pk_bf16_f32 v65, v34, v35
	v_cvt_pk_bf16_f32 v66, v36, v37
	v_cvt_pk_bf16_f32 v67, v38, v39
	v_cvt_pk_bf16_f32 v68, v40, v41
	v_cvt_pk_bf16_f32 v69, v42, v43
	v_cvt_pk_bf16_f32 v70, v44, v45
	v_cvt_pk_bf16_f32 v71, v46, v47
	v_pk_add_f32 v[232:233], v[232:233], v[32:33]
	v_pk_add_f32 v[232:233], v[232:233], v[34:35]
	v_pk_add_f32 v[232:233], v[232:233], v[36:37]
	v_pk_add_f32 v[232:233], v[232:233], v[38:39]
	v_pk_add_f32 v[232:233], v[232:233], v[40:41]
	v_pk_add_f32 v[232:233], v[232:233], v[42:43]
	v_pk_add_f32 v[232:233], v[232:233], v[44:45]
	v_pk_add_f32 v[232:233], v[232:233], v[46:47]
	s_waitcnt lgkmcnt(0)
	v_mfma_f32_32x32x16_bf16 v[0:15], v[64:67], v[72:75], v[0:15]
	v_mfma_f32_32x32x16_bf16 v[16:31], v[64:67], v[76:79], v[16:31]
	v_mfma_f32_32x32x16_bf16 v[0:15], v[68:71], v[220:223], v[0:15]
	v_mfma_f32_32x32x16_bf16 v[16:31], v[68:71], v[224:227], v[16:31]
	global_load_dwordx4 v[188:191], v235, s[84:85]
	global_load_dwordx4 v[192:195], v236, s[84:85]
	global_load_dwordx4 v[196:199], v237, s[84:85]
	global_load_dwordx4 v[200:203], v238, s[84:85]
	global_load_dwordx4 v[204:207], v100, s[84:85] offset:768
	global_load_dwordx4 v[208:211], v149, s[84:85] offset:768
	global_load_dwordx4 v[212:215], v100, s[84:85] offset:832
	global_load_dwordx4 v[216:219], v149, s[84:85] offset:832
	s_add_u32 s84, s84, 0x30000
	s_addc_u32 s85, s85, 0
	s_waitcnt vmcnt(16)
	ds_write_b128 v247, v[116:119]
	ds_write_b128 v247, v[120:123] offset:1024
	ds_write_b128 v247, v[124:127] offset:2048
	ds_write_b128 v247, v[128:131] offset:3072
	ds_read_b128 v[116:119], v248
	ds_read_b128 v[120:123], v249
	ds_read_b128 v[124:127], v250
	ds_read_b128 v[128:131], v251
	ds_write_b128 v112, v[132:135]
	ds_write_b128 v112, v[136:139] offset:1024
	ds_write_b128 v112, v[140:143] offset:2048
	ds_write_b128 v112, v[144:147] offset:3072
	ds_read2_b32 v[32:33], v115 offset0:204 offset1:205
	ds_read2_b32 v[34:35], v115 offset0:206 offset1:207
	ds_read2_b32 v[36:37], v115 offset0:212 offset1:213
	ds_read2_b32 v[38:39], v115 offset0:214 offset1:215
	ds_read2_b32 v[40:41], v115 offset0:221 offset1:222
	ds_read2_b32 v[42:43], v115 offset0:223 offset1:224
	ds_read2_b32 v[44:45], v115 offset0:229 offset1:230
	ds_read2_b32 v[46:47], v115 offset0:231 offset1:232
	s_waitcnt lgkmcnt(0)
	v_mfma_f32_32x32x16_bf16 v[32:47], v[116:119], v[48:51], v[32:47]
	ds_read_b64_tr_b16 v[72:73], v231
	ds_read_b64_tr_b16 v[74:75], v231 offset:512
	ds_read_b64_tr_b16 v[76:77], v231 offset:2048
	ds_read_b64_tr_b16 v[78:79], v231 offset:2560
	ds_read_b64_tr_b16 v[220:221], v231 offset:1024
	ds_read_b64_tr_b16 v[222:223], v231 offset:1536
	ds_read_b64_tr_b16 v[224:225], v231 offset:3072
	ds_read_b64_tr_b16 v[226:227], v231 offset:3584
	v_mfma_f32_32x32x16_bf16 v[32:47], v[120:123], v[52:55], v[32:47]
	v_mfma_f32_32x32x16_bf16 v[32:47], v[124:127], v[56:59], v[32:47]
	v_mfma_f32_32x32x16_bf16 v[32:47], v[128:131], v[60:63], v[32:47]
	s_nop 11
	v_exp_f32_e32 v32, v32
	v_exp_f32_e32 v33, v33
	v_exp_f32_e32 v34, v34
	v_exp_f32_e32 v35, v35
	v_exp_f32_e32 v36, v36
	v_exp_f32_e32 v37, v37
	v_exp_f32_e32 v38, v38
	v_exp_f32_e32 v39, v39
	v_exp_f32_e32 v40, v40
	v_exp_f32_e32 v41, v41
	v_exp_f32_e32 v42, v42
	v_exp_f32_e32 v43, v43
	v_exp_f32_e32 v44, v44
	v_exp_f32_e32 v45, v45
	v_exp_f32_e32 v46, v46
	v_exp_f32_e32 v47, v47
	v_cvt_pk_bf16_f32 v64, v32, v33
	v_cvt_pk_bf16_f32 v65, v34, v35
	v_cvt_pk_bf16_f32 v66, v36, v37
	v_cvt_pk_bf16_f32 v67, v38, v39
	v_cvt_pk_bf16_f32 v68, v40, v41
	v_cvt_pk_bf16_f32 v69, v42, v43
	v_cvt_pk_bf16_f32 v70, v44, v45
	v_cvt_pk_bf16_f32 v71, v46, v47
	v_pk_add_f32 v[232:233], v[232:233], v[32:33]
	v_pk_add_f32 v[232:233], v[232:233], v[34:35]
	v_pk_add_f32 v[232:233], v[232:233], v[36:37]
	v_pk_add_f32 v[232:233], v[232:233], v[38:39]
	v_pk_add_f32 v[232:233], v[232:233], v[40:41]
	v_pk_add_f32 v[232:233], v[232:233], v[42:43]
	v_pk_add_f32 v[232:233], v[232:233], v[44:45]
	v_pk_add_f32 v[232:233], v[232:233], v[46:47]
	s_waitcnt lgkmcnt(0)
	v_mfma_f32_32x32x16_bf16 v[0:15], v[64:67], v[72:75], v[0:15]
	v_mfma_f32_32x32x16_bf16 v[16:31], v[64:67], v[76:79], v[16:31]
	v_mfma_f32_32x32x16_bf16 v[0:15], v[68:71], v[220:223], v[0:15]
	v_mfma_f32_32x32x16_bf16 v[16:31], v[68:71], v[224:227], v[16:31]
	global_load_dwordx4 v[116:119], v235, s[84:85]
	global_load_dwordx4 v[120:123], v236, s[84:85]
	global_load_dwordx4 v[124:127], v237, s[84:85]
	global_load_dwordx4 v[128:131], v238, s[84:85]
	global_load_dwordx4 v[132:135], v100, s[84:85] offset:768
	global_load_dwordx4 v[136:139], v149, s[84:85] offset:768
	global_load_dwordx4 v[140:143], v100, s[84:85] offset:832
	global_load_dwordx4 v[144:147], v149, s[84:85] offset:832
	s_add_u32 s84, s84, 0x30000
	s_addc_u32 s85, s85, 0
	s_waitcnt vmcnt(16)
	ds_write_b128 v247, v[156:159]
	ds_write_b128 v247, v[160:163] offset:1024
	ds_write_b128 v247, v[164:167] offset:2048
	ds_write_b128 v247, v[168:171] offset:3072
	ds_read_b128 v[156:159], v248
	ds_read_b128 v[160:163], v249
	ds_read_b128 v[164:167], v250
	ds_read_b128 v[168:171], v251
	ds_write_b128 v112, v[172:175]
	ds_write_b128 v112, v[176:179] offset:1024
	ds_write_b128 v112, v[180:183] offset:2048
	ds_write_b128 v112, v[184:187] offset:3072
	v_add_u32_e32 v115, 952, v115
	ds_read2_b32 v[32:33], v115 offset0:0 offset1:1
	ds_read2_b32 v[34:35], v115 offset0:2 offset1:3
	ds_read2_b32 v[36:37], v115 offset0:8 offset1:9
	ds_read2_b32 v[38:39], v115 offset0:10 offset1:11
	ds_read2_b32 v[40:41], v115 offset0:17 offset1:18
	ds_read2_b32 v[42:43], v115 offset0:19 offset1:20
	ds_read2_b32 v[44:45], v115 offset0:25 offset1:26
	ds_read2_b32 v[46:47], v115 offset0:27 offset1:28
	s_waitcnt lgkmcnt(0)
	v_mfma_f32_32x32x16_bf16 v[32:47], v[156:159], v[48:51], v[32:47]
	ds_read_b64_tr_b16 v[72:73], v231
	ds_read_b64_tr_b16 v[74:75], v231 offset:512
	ds_read_b64_tr_b16 v[76:77], v231 offset:2048
	ds_read_b64_tr_b16 v[78:79], v231 offset:2560
	ds_read_b64_tr_b16 v[220:221], v231 offset:1024
	ds_read_b64_tr_b16 v[222:223], v231 offset:1536
	ds_read_b64_tr_b16 v[224:225], v231 offset:3072
	ds_read_b64_tr_b16 v[226:227], v231 offset:3584
	v_mfma_f32_32x32x16_bf16 v[32:47], v[160:163], v[52:55], v[32:47]
	v_mfma_f32_32x32x16_bf16 v[32:47], v[164:167], v[56:59], v[32:47]
	v_mfma_f32_32x32x16_bf16 v[32:47], v[168:171], v[60:63], v[32:47]
	s_nop 11
	v_exp_f32_e32 v32, v32
	v_exp_f32_e32 v33, v33
	v_exp_f32_e32 v34, v34
	v_exp_f32_e32 v35, v35
	v_exp_f32_e32 v36, v36
	v_exp_f32_e32 v37, v37
	v_exp_f32_e32 v38, v38
	v_exp_f32_e32 v39, v39
	v_exp_f32_e32 v40, v40
	v_exp_f32_e32 v41, v41
	v_exp_f32_e32 v42, v42
	v_exp_f32_e32 v43, v43
	v_exp_f32_e32 v44, v44
	v_exp_f32_e32 v45, v45
	v_exp_f32_e32 v46, v46
	v_exp_f32_e32 v47, v47
	v_cvt_pk_bf16_f32 v64, v32, v33
	v_cvt_pk_bf16_f32 v65, v34, v35
	v_cvt_pk_bf16_f32 v66, v36, v37
	v_cvt_pk_bf16_f32 v67, v38, v39
	v_cvt_pk_bf16_f32 v68, v40, v41
	v_cvt_pk_bf16_f32 v69, v42, v43
	v_cvt_pk_bf16_f32 v70, v44, v45
	v_cvt_pk_bf16_f32 v71, v46, v47
	v_pk_add_f32 v[232:233], v[232:233], v[32:33]
	v_pk_add_f32 v[232:233], v[232:233], v[34:35]
	v_pk_add_f32 v[232:233], v[232:233], v[36:37]
	v_pk_add_f32 v[232:233], v[232:233], v[38:39]
	v_pk_add_f32 v[232:233], v[232:233], v[40:41]
	v_pk_add_f32 v[232:233], v[232:233], v[42:43]
	v_pk_add_f32 v[232:233], v[232:233], v[44:45]
	v_pk_add_f32 v[232:233], v[232:233], v[46:47]
	s_waitcnt lgkmcnt(0)
	v_mfma_f32_32x32x16_bf16 v[0:15], v[64:67], v[72:75], v[0:15]
	v_mfma_f32_32x32x16_bf16 v[16:31], v[64:67], v[76:79], v[16:31]
	v_mfma_f32_32x32x16_bf16 v[0:15], v[68:71], v[220:223], v[0:15]
	v_mfma_f32_32x32x16_bf16 v[16:31], v[68:71], v[224:227], v[16:31]
	global_load_dwordx4 v[156:159], v235, s[84:85]
	global_load_dwordx4 v[160:163], v236, s[84:85]
	global_load_dwordx4 v[164:167], v237, s[84:85]
	global_load_dwordx4 v[168:171], v238, s[84:85]
	global_load_dwordx4 v[172:175], v100, s[84:85] offset:768
	global_load_dwordx4 v[176:179], v149, s[84:85] offset:768
	global_load_dwordx4 v[180:183], v100, s[84:85] offset:832
	global_load_dwordx4 v[184:187], v149, s[84:85] offset:832
	s_add_u32 s84, s84, 0x30000
	s_addc_u32 s85, s85, 0
	s_waitcnt vmcnt(16)
	ds_write_b128 v247, v[188:191]
	ds_write_b128 v247, v[192:195] offset:1024
	ds_write_b128 v247, v[196:199] offset:2048
	ds_write_b128 v247, v[200:203] offset:3072
	ds_read_b128 v[188:191], v248
	ds_read_b128 v[192:195], v249
	ds_read_b128 v[196:199], v250
	ds_read_b128 v[200:203], v251
	ds_write_b128 v112, v[204:207]
	ds_write_b128 v112, v[208:211] offset:1024
	ds_write_b128 v112, v[212:215] offset:2048
	ds_write_b128 v112, v[216:219] offset:3072
	ds_read2_b32 v[32:33], v115 offset0:34 offset1:35
	ds_read2_b32 v[34:35], v115 offset0:36 offset1:37
	ds_read2_b32 v[36:37], v115 offset0:42 offset1:43
	ds_read2_b32 v[38:39], v115 offset0:44 offset1:45
	ds_read2_b32 v[40:41], v115 offset0:51 offset1:52
	ds_read2_b32 v[42:43], v115 offset0:53 offset1:54
	ds_read2_b32 v[44:45], v115 offset0:59 offset1:60
	ds_read2_b32 v[46:47], v115 offset0:61 offset1:62
	s_waitcnt lgkmcnt(0)
	v_mfma_f32_32x32x16_bf16 v[32:47], v[188:191], v[48:51], v[32:47]
	ds_read_b64_tr_b16 v[72:73], v231
	ds_read_b64_tr_b16 v[74:75], v231 offset:512
	ds_read_b64_tr_b16 v[76:77], v231 offset:2048
	ds_read_b64_tr_b16 v[78:79], v231 offset:2560
	ds_read_b64_tr_b16 v[220:221], v231 offset:1024
	ds_read_b64_tr_b16 v[222:223], v231 offset:1536
	ds_read_b64_tr_b16 v[224:225], v231 offset:3072
	ds_read_b64_tr_b16 v[226:227], v231 offset:3584
	v_mfma_f32_32x32x16_bf16 v[32:47], v[192:195], v[52:55], v[32:47]
	v_mfma_f32_32x32x16_bf16 v[32:47], v[196:199], v[56:59], v[32:47]
	v_mfma_f32_32x32x16_bf16 v[32:47], v[200:203], v[60:63], v[32:47]
	s_nop 11
	v_exp_f32_e32 v32, v32
	v_exp_f32_e32 v33, v33
	v_exp_f32_e32 v34, v34
	v_exp_f32_e32 v35, v35
	v_exp_f32_e32 v36, v36
	v_exp_f32_e32 v37, v37
	v_exp_f32_e32 v38, v38
	v_exp_f32_e32 v39, v39
	v_exp_f32_e32 v40, v40
	v_exp_f32_e32 v41, v41
	v_exp_f32_e32 v42, v42
	v_exp_f32_e32 v43, v43
	v_exp_f32_e32 v44, v44
	v_exp_f32_e32 v45, v45
	v_exp_f32_e32 v46, v46
	v_exp_f32_e32 v47, v47
	v_cvt_pk_bf16_f32 v64, v32, v33
	v_cvt_pk_bf16_f32 v65, v34, v35
	v_cvt_pk_bf16_f32 v66, v36, v37
	v_cvt_pk_bf16_f32 v67, v38, v39
	v_cvt_pk_bf16_f32 v68, v40, v41
	v_cvt_pk_bf16_f32 v69, v42, v43
	v_cvt_pk_bf16_f32 v70, v44, v45
	v_cvt_pk_bf16_f32 v71, v46, v47
	v_pk_add_f32 v[232:233], v[232:233], v[32:33]
	v_pk_add_f32 v[232:233], v[232:233], v[34:35]
	v_pk_add_f32 v[232:233], v[232:233], v[36:37]
	v_pk_add_f32 v[232:233], v[232:233], v[38:39]
	v_pk_add_f32 v[232:233], v[232:233], v[40:41]
	v_pk_add_f32 v[232:233], v[232:233], v[42:43]
	v_pk_add_f32 v[232:233], v[232:233], v[44:45]
	v_pk_add_f32 v[232:233], v[232:233], v[46:47]
	s_waitcnt lgkmcnt(0)
	v_mfma_f32_32x32x16_bf16 v[0:15], v[64:67], v[72:75], v[0:15]
	v_mfma_f32_32x32x16_bf16 v[16:31], v[64:67], v[76:79], v[16:31]
	v_mfma_f32_32x32x16_bf16 v[0:15], v[68:71], v[220:223], v[0:15]
	v_mfma_f32_32x32x16_bf16 v[16:31], v[68:71], v[224:227], v[16:31]
	global_load_dwordx4 v[188:191], v235, s[84:85]
	global_load_dwordx4 v[192:195], v236, s[84:85]
	global_load_dwordx4 v[196:199], v237, s[84:85]
	global_load_dwordx4 v[200:203], v238, s[84:85]
	global_load_dwordx4 v[204:207], v100, s[84:85] offset:768
	global_load_dwordx4 v[208:211], v149, s[84:85] offset:768
	global_load_dwordx4 v[212:215], v100, s[84:85] offset:832
	global_load_dwordx4 v[216:219], v149, s[84:85] offset:832
	s_add_u32 s84, s84, 0x30000
	s_addc_u32 s85, s85, 0
	s_waitcnt vmcnt(16)
	ds_write_b128 v247, v[116:119]
	ds_write_b128 v247, v[120:123] offset:1024
	ds_write_b128 v247, v[124:127] offset:2048
	ds_write_b128 v247, v[128:131] offset:3072
	ds_read_b128 v[116:119], v248
	ds_read_b128 v[120:123], v249
	ds_read_b128 v[124:127], v250
	ds_read_b128 v[128:131], v251
	ds_write_b128 v112, v[132:135]
	ds_write_b128 v112, v[136:139] offset:1024
	ds_write_b128 v112, v[140:143] offset:2048
	ds_write_b128 v112, v[144:147] offset:3072
	ds_read2_b32 v[32:33], v115 offset0:68 offset1:69
	ds_read2_b32 v[34:35], v115 offset0:70 offset1:71
	ds_read2_b32 v[36:37], v115 offset0:76 offset1:77
	ds_read2_b32 v[38:39], v115 offset0:78 offset1:79
	ds_read2_b32 v[40:41], v115 offset0:85 offset1:86
	ds_read2_b32 v[42:43], v115 offset0:87 offset1:88
	ds_read2_b32 v[44:45], v115 offset0:93 offset1:94
	ds_read2_b32 v[46:47], v115 offset0:95 offset1:96
	s_waitcnt lgkmcnt(0)
	v_mfma_f32_32x32x16_bf16 v[32:47], v[116:119], v[48:51], v[32:47]
	ds_read_b64_tr_b16 v[72:73], v231
	ds_read_b64_tr_b16 v[74:75], v231 offset:512
	ds_read_b64_tr_b16 v[76:77], v231 offset:2048
	ds_read_b64_tr_b16 v[78:79], v231 offset:2560
	ds_read_b64_tr_b16 v[220:221], v231 offset:1024
	ds_read_b64_tr_b16 v[222:223], v231 offset:1536
	ds_read_b64_tr_b16 v[224:225], v231 offset:3072
	ds_read_b64_tr_b16 v[226:227], v231 offset:3584
	v_mfma_f32_32x32x16_bf16 v[32:47], v[120:123], v[52:55], v[32:47]
	v_mfma_f32_32x32x16_bf16 v[32:47], v[124:127], v[56:59], v[32:47]
	v_mfma_f32_32x32x16_bf16 v[32:47], v[128:131], v[60:63], v[32:47]
	s_nop 11
	v_exp_f32_e32 v32, v32
	v_exp_f32_e32 v33, v33
	v_exp_f32_e32 v34, v34
	v_exp_f32_e32 v35, v35
	v_exp_f32_e32 v36, v36
	v_exp_f32_e32 v37, v37
	v_exp_f32_e32 v38, v38
	v_exp_f32_e32 v39, v39
	v_exp_f32_e32 v40, v40
	v_exp_f32_e32 v41, v41
	v_exp_f32_e32 v42, v42
	v_exp_f32_e32 v43, v43
	v_exp_f32_e32 v44, v44
	v_exp_f32_e32 v45, v45
	v_exp_f32_e32 v46, v46
	v_exp_f32_e32 v47, v47
	v_cvt_pk_bf16_f32 v64, v32, v33
	v_cvt_pk_bf16_f32 v65, v34, v35
	v_cvt_pk_bf16_f32 v66, v36, v37
	v_cvt_pk_bf16_f32 v67, v38, v39
	v_cvt_pk_bf16_f32 v68, v40, v41
	v_cvt_pk_bf16_f32 v69, v42, v43
	v_cvt_pk_bf16_f32 v70, v44, v45
	v_cvt_pk_bf16_f32 v71, v46, v47
	v_pk_add_f32 v[232:233], v[232:233], v[32:33]
	v_pk_add_f32 v[232:233], v[232:233], v[34:35]
	v_pk_add_f32 v[232:233], v[232:233], v[36:37]
	v_pk_add_f32 v[232:233], v[232:233], v[38:39]
	v_pk_add_f32 v[232:233], v[232:233], v[40:41]
	v_pk_add_f32 v[232:233], v[232:233], v[42:43]
	v_pk_add_f32 v[232:233], v[232:233], v[44:45]
	v_pk_add_f32 v[232:233], v[232:233], v[46:47]
	s_waitcnt lgkmcnt(0)
	v_mfma_f32_32x32x16_bf16 v[0:15], v[64:67], v[72:75], v[0:15]
	v_mfma_f32_32x32x16_bf16 v[16:31], v[64:67], v[76:79], v[16:31]
	v_mfma_f32_32x32x16_bf16 v[0:15], v[68:71], v[220:223], v[0:15]
	v_mfma_f32_32x32x16_bf16 v[16:31], v[68:71], v[224:227], v[16:31]
	global_load_dwordx4 v[116:119], v235, s[84:85]
	global_load_dwordx4 v[120:123], v236, s[84:85]
	global_load_dwordx4 v[124:127], v237, s[84:85]
	global_load_dwordx4 v[128:131], v238, s[84:85]
	global_load_dwordx4 v[132:135], v100, s[84:85] offset:768
	global_load_dwordx4 v[136:139], v149, s[84:85] offset:768
	global_load_dwordx4 v[140:143], v100, s[84:85] offset:832
	global_load_dwordx4 v[144:147], v149, s[84:85] offset:832
	s_add_u32 s84, s84, 0x30000
	s_addc_u32 s85, s85, 0
	s_waitcnt vmcnt(16)
	ds_write_b128 v247, v[156:159]
	ds_write_b128 v247, v[160:163] offset:1024
	ds_write_b128 v247, v[164:167] offset:2048
	ds_write_b128 v247, v[168:171] offset:3072
	ds_read_b128 v[156:159], v248
	ds_read_b128 v[160:163], v249
	ds_read_b128 v[164:167], v250
	ds_read_b128 v[168:171], v251
	ds_write_b128 v112, v[172:175]
	ds_write_b128 v112, v[176:179] offset:1024
	ds_write_b128 v112, v[180:183] offset:2048
	ds_write_b128 v112, v[184:187] offset:3072
	ds_read2_b32 v[32:33], v115 offset0:102 offset1:103
	ds_read2_b32 v[34:35], v115 offset0:104 offset1:105
	ds_read2_b32 v[36:37], v115 offset0:110 offset1:111
	ds_read2_b32 v[38:39], v115 offset0:112 offset1:113
	ds_read2_b32 v[40:41], v115 offset0:119 offset1:120
	ds_read2_b32 v[42:43], v115 offset0:121 offset1:122
	ds_read2_b32 v[44:45], v115 offset0:127 offset1:128
	ds_read2_b32 v[46:47], v115 offset0:129 offset1:130
	s_waitcnt lgkmcnt(0)
	v_mfma_f32_32x32x16_bf16 v[32:47], v[156:159], v[48:51], v[32:47]
	ds_read_b64_tr_b16 v[72:73], v231
	ds_read_b64_tr_b16 v[74:75], v231 offset:512
	ds_read_b64_tr_b16 v[76:77], v231 offset:2048
	ds_read_b64_tr_b16 v[78:79], v231 offset:2560
	ds_read_b64_tr_b16 v[220:221], v231 offset:1024
	ds_read_b64_tr_b16 v[222:223], v231 offset:1536
	ds_read_b64_tr_b16 v[224:225], v231 offset:3072
	ds_read_b64_tr_b16 v[226:227], v231 offset:3584
	v_mfma_f32_32x32x16_bf16 v[32:47], v[160:163], v[52:55], v[32:47]
	v_mfma_f32_32x32x16_bf16 v[32:47], v[164:167], v[56:59], v[32:47]
	v_mfma_f32_32x32x16_bf16 v[32:47], v[168:171], v[60:63], v[32:47]
	s_nop 11
	v_exp_f32_e32 v32, v32
	v_exp_f32_e32 v33, v33
	v_exp_f32_e32 v34, v34
	v_exp_f32_e32 v35, v35
	v_exp_f32_e32 v36, v36
	v_exp_f32_e32 v37, v37
	v_exp_f32_e32 v38, v38
	v_exp_f32_e32 v39, v39
	v_exp_f32_e32 v40, v40
	v_exp_f32_e32 v41, v41
	v_exp_f32_e32 v42, v42
	v_exp_f32_e32 v43, v43
	v_exp_f32_e32 v44, v44
	v_exp_f32_e32 v45, v45
	v_exp_f32_e32 v46, v46
	v_exp_f32_e32 v47, v47
	v_cvt_pk_bf16_f32 v64, v32, v33
	v_cvt_pk_bf16_f32 v65, v34, v35
	v_cvt_pk_bf16_f32 v66, v36, v37
	v_cvt_pk_bf16_f32 v67, v38, v39
	v_cvt_pk_bf16_f32 v68, v40, v41
	v_cvt_pk_bf16_f32 v69, v42, v43
	v_cvt_pk_bf16_f32 v70, v44, v45
	v_cvt_pk_bf16_f32 v71, v46, v47
	v_pk_add_f32 v[232:233], v[232:233], v[32:33]
	v_pk_add_f32 v[232:233], v[232:233], v[34:35]
	v_pk_add_f32 v[232:233], v[232:233], v[36:37]
	v_pk_add_f32 v[232:233], v[232:233], v[38:39]
	v_pk_add_f32 v[232:233], v[232:233], v[40:41]
	v_pk_add_f32 v[232:233], v[232:233], v[42:43]
	v_pk_add_f32 v[232:233], v[232:233], v[44:45]
	v_pk_add_f32 v[232:233], v[232:233], v[46:47]
	s_waitcnt lgkmcnt(0)
	v_mfma_f32_32x32x16_bf16 v[0:15], v[64:67], v[72:75], v[0:15]
	v_mfma_f32_32x32x16_bf16 v[16:31], v[64:67], v[76:79], v[16:31]
	v_mfma_f32_32x32x16_bf16 v[0:15], v[68:71], v[220:223], v[0:15]
	v_mfma_f32_32x32x16_bf16 v[16:31], v[68:71], v[224:227], v[16:31]
	global_load_dwordx4 v[156:159], v235, s[84:85]
	global_load_dwordx4 v[160:163], v236, s[84:85]
	global_load_dwordx4 v[164:167], v237, s[84:85]
	global_load_dwordx4 v[168:171], v238, s[84:85]
	global_load_dwordx4 v[172:175], v100, s[84:85] offset:768
	global_load_dwordx4 v[176:179], v149, s[84:85] offset:768
	global_load_dwordx4 v[180:183], v100, s[84:85] offset:832
	global_load_dwordx4 v[184:187], v149, s[84:85] offset:832
	s_add_u32 s84, s84, 0x30000
	s_addc_u32 s85, s85, 0
	s_waitcnt vmcnt(16)
	ds_write_b128 v247, v[188:191]
	ds_write_b128 v247, v[192:195] offset:1024
	ds_write_b128 v247, v[196:199] offset:2048
	ds_write_b128 v247, v[200:203] offset:3072
	ds_read_b128 v[188:191], v248
	ds_read_b128 v[192:195], v249
	ds_read_b128 v[196:199], v250
	ds_read_b128 v[200:203], v251
	ds_write_b128 v112, v[204:207]
	ds_write_b128 v112, v[208:211] offset:1024
	ds_write_b128 v112, v[212:215] offset:2048
	ds_write_b128 v112, v[216:219] offset:3072
	ds_read2_b32 v[32:33], v115 offset0:136 offset1:137
	ds_read2_b32 v[34:35], v115 offset0:138 offset1:139
	ds_read2_b32 v[36:37], v115 offset0:144 offset1:145
	ds_read2_b32 v[38:39], v115 offset0:146 offset1:147
	ds_read2_b32 v[40:41], v115 offset0:153 offset1:154
	ds_read2_b32 v[42:43], v115 offset0:155 offset1:156
	ds_read2_b32 v[44:45], v115 offset0:161 offset1:162
	ds_read2_b32 v[46:47], v115 offset0:163 offset1:164
	s_waitcnt lgkmcnt(0)
	v_mfma_f32_32x32x16_bf16 v[32:47], v[188:191], v[48:51], v[32:47]
	ds_read_b64_tr_b16 v[72:73], v231
	ds_read_b64_tr_b16 v[74:75], v231 offset:512
	ds_read_b64_tr_b16 v[76:77], v231 offset:2048
	ds_read_b64_tr_b16 v[78:79], v231 offset:2560
	ds_read_b64_tr_b16 v[220:221], v231 offset:1024
	ds_read_b64_tr_b16 v[222:223], v231 offset:1536
	ds_read_b64_tr_b16 v[224:225], v231 offset:3072
	ds_read_b64_tr_b16 v[226:227], v231 offset:3584
	v_mfma_f32_32x32x16_bf16 v[32:47], v[192:195], v[52:55], v[32:47]
	v_mfma_f32_32x32x16_bf16 v[32:47], v[196:199], v[56:59], v[32:47]
	v_mfma_f32_32x32x16_bf16 v[32:47], v[200:203], v[60:63], v[32:47]
	s_nop 11
	v_exp_f32_e32 v32, v32
	v_exp_f32_e32 v33, v33
	v_exp_f32_e32 v34, v34
	v_exp_f32_e32 v35, v35
	v_exp_f32_e32 v36, v36
	v_exp_f32_e32 v37, v37
	v_exp_f32_e32 v38, v38
	v_exp_f32_e32 v39, v39
	v_exp_f32_e32 v40, v40
	v_exp_f32_e32 v41, v41
	v_exp_f32_e32 v42, v42
	v_exp_f32_e32 v43, v43
	v_exp_f32_e32 v44, v44
	v_exp_f32_e32 v45, v45
	v_exp_f32_e32 v46, v46
	v_exp_f32_e32 v47, v47
	v_cvt_pk_bf16_f32 v64, v32, v33
	v_cvt_pk_bf16_f32 v65, v34, v35
	v_cvt_pk_bf16_f32 v66, v36, v37
	v_cvt_pk_bf16_f32 v67, v38, v39
	v_cvt_pk_bf16_f32 v68, v40, v41
	v_cvt_pk_bf16_f32 v69, v42, v43
	v_cvt_pk_bf16_f32 v70, v44, v45
	v_cvt_pk_bf16_f32 v71, v46, v47
	v_pk_add_f32 v[232:233], v[232:233], v[32:33]
	v_pk_add_f32 v[232:233], v[232:233], v[34:35]
	v_pk_add_f32 v[232:233], v[232:233], v[36:37]
	v_pk_add_f32 v[232:233], v[232:233], v[38:39]
	v_pk_add_f32 v[232:233], v[232:233], v[40:41]
	v_pk_add_f32 v[232:233], v[232:233], v[42:43]
	v_pk_add_f32 v[232:233], v[232:233], v[44:45]
	v_pk_add_f32 v[232:233], v[232:233], v[46:47]
	s_waitcnt lgkmcnt(0)
	v_mfma_f32_32x32x16_bf16 v[0:15], v[64:67], v[72:75], v[0:15]
	v_mfma_f32_32x32x16_bf16 v[16:31], v[64:67], v[76:79], v[16:31]
	v_mfma_f32_32x32x16_bf16 v[0:15], v[68:71], v[220:223], v[0:15]
	v_mfma_f32_32x32x16_bf16 v[16:31], v[68:71], v[224:227], v[16:31]
	global_load_dwordx4 v[188:191], v235, s[84:85]
	global_load_dwordx4 v[192:195], v236, s[84:85]
	global_load_dwordx4 v[196:199], v237, s[84:85]
	global_load_dwordx4 v[200:203], v238, s[84:85]
	global_load_dwordx4 v[204:207], v100, s[84:85] offset:768
	global_load_dwordx4 v[208:211], v149, s[84:85] offset:768
	global_load_dwordx4 v[212:215], v100, s[84:85] offset:832
	global_load_dwordx4 v[216:219], v149, s[84:85] offset:832
	s_add_u32 s84, s84, 0x30000
	s_addc_u32 s85, s85, 0
	s_waitcnt vmcnt(16)
	ds_write_b128 v247, v[116:119]
	ds_write_b128 v247, v[120:123] offset:1024
	ds_write_b128 v247, v[124:127] offset:2048
	ds_write_b128 v247, v[128:131] offset:3072
	ds_read_b128 v[116:119], v248
	ds_read_b128 v[120:123], v249
	ds_read_b128 v[124:127], v250
	ds_read_b128 v[128:131], v251
	ds_write_b128 v112, v[132:135]
	ds_write_b128 v112, v[136:139] offset:1024
	ds_write_b128 v112, v[140:143] offset:2048
	ds_write_b128 v112, v[144:147] offset:3072
	ds_read2_b32 v[32:33], v115 offset0:170 offset1:171
	ds_read2_b32 v[34:35], v115 offset0:172 offset1:173
	ds_read2_b32 v[36:37], v115 offset0:178 offset1:179
	ds_read2_b32 v[38:39], v115 offset0:180 offset1:181
	ds_read2_b32 v[40:41], v115 offset0:187 offset1:188
	ds_read2_b32 v[42:43], v115 offset0:189 offset1:190
	ds_read2_b32 v[44:45], v115 offset0:195 offset1:196
	ds_read2_b32 v[46:47], v115 offset0:197 offset1:198
	s_waitcnt lgkmcnt(0)
	v_mfma_f32_32x32x16_bf16 v[32:47], v[116:119], v[48:51], v[32:47]
	ds_read_b64_tr_b16 v[72:73], v231
	ds_read_b64_tr_b16 v[74:75], v231 offset:512
	ds_read_b64_tr_b16 v[76:77], v231 offset:2048
	ds_read_b64_tr_b16 v[78:79], v231 offset:2560
	ds_read_b64_tr_b16 v[220:221], v231 offset:1024
	ds_read_b64_tr_b16 v[222:223], v231 offset:1536
	ds_read_b64_tr_b16 v[224:225], v231 offset:3072
	ds_read_b64_tr_b16 v[226:227], v231 offset:3584
	v_mfma_f32_32x32x16_bf16 v[32:47], v[120:123], v[52:55], v[32:47]
	v_mfma_f32_32x32x16_bf16 v[32:47], v[124:127], v[56:59], v[32:47]
	v_mfma_f32_32x32x16_bf16 v[32:47], v[128:131], v[60:63], v[32:47]
	s_nop 11
	v_exp_f32_e32 v32, v32
	v_exp_f32_e32 v33, v33
	v_exp_f32_e32 v34, v34
	v_exp_f32_e32 v35, v35
	v_exp_f32_e32 v36, v36
	v_exp_f32_e32 v37, v37
	v_exp_f32_e32 v38, v38
	v_exp_f32_e32 v39, v39
	v_exp_f32_e32 v40, v40
	v_exp_f32_e32 v41, v41
	v_exp_f32_e32 v42, v42
	v_exp_f32_e32 v43, v43
	v_exp_f32_e32 v44, v44
	v_exp_f32_e32 v45, v45
	v_exp_f32_e32 v46, v46
	v_exp_f32_e32 v47, v47
	v_cvt_pk_bf16_f32 v64, v32, v33
	v_cvt_pk_bf16_f32 v65, v34, v35
	v_cvt_pk_bf16_f32 v66, v36, v37
	v_cvt_pk_bf16_f32 v67, v38, v39
	v_cvt_pk_bf16_f32 v68, v40, v41
	v_cvt_pk_bf16_f32 v69, v42, v43
	v_cvt_pk_bf16_f32 v70, v44, v45
	v_cvt_pk_bf16_f32 v71, v46, v47
	v_pk_add_f32 v[232:233], v[232:233], v[32:33]
	v_pk_add_f32 v[232:233], v[232:233], v[34:35]
	v_pk_add_f32 v[232:233], v[232:233], v[36:37]
	v_pk_add_f32 v[232:233], v[232:233], v[38:39]
	v_pk_add_f32 v[232:233], v[232:233], v[40:41]
	v_pk_add_f32 v[232:233], v[232:233], v[42:43]
	v_pk_add_f32 v[232:233], v[232:233], v[44:45]
	v_pk_add_f32 v[232:233], v[232:233], v[46:47]
	s_waitcnt lgkmcnt(0)
	v_mfma_f32_32x32x16_bf16 v[0:15], v[64:67], v[72:75], v[0:15]
	v_mfma_f32_32x32x16_bf16 v[16:31], v[64:67], v[76:79], v[16:31]
	v_mfma_f32_32x32x16_bf16 v[0:15], v[68:71], v[220:223], v[0:15]
	v_mfma_f32_32x32x16_bf16 v[16:31], v[68:71], v[224:227], v[16:31]
	global_load_dwordx4 v[116:119], v235, s[84:85]
	global_load_dwordx4 v[120:123], v236, s[84:85]
	global_load_dwordx4 v[124:127], v237, s[84:85]
	global_load_dwordx4 v[128:131], v238, s[84:85]
	global_load_dwordx4 v[132:135], v100, s[84:85] offset:768
	global_load_dwordx4 v[136:139], v149, s[84:85] offset:768
	global_load_dwordx4 v[140:143], v100, s[84:85] offset:832
	global_load_dwordx4 v[144:147], v149, s[84:85] offset:832
	s_add_u32 s84, s84, 0x30000
	s_addc_u32 s85, s85, 0
	s_waitcnt vmcnt(16)
	ds_write_b128 v247, v[156:159]
	ds_write_b128 v247, v[160:163] offset:1024
	ds_write_b128 v247, v[164:167] offset:2048
	ds_write_b128 v247, v[168:171] offset:3072
	ds_read_b128 v[156:159], v248
	ds_read_b128 v[160:163], v249
	ds_read_b128 v[164:167], v250
	ds_read_b128 v[168:171], v251
	ds_write_b128 v112, v[172:175]
	ds_write_b128 v112, v[176:179] offset:1024
	ds_write_b128 v112, v[180:183] offset:2048
	ds_write_b128 v112, v[184:187] offset:3072
	ds_read2_b32 v[32:33], v115 offset0:204 offset1:205
	ds_read2_b32 v[34:35], v115 offset0:206 offset1:207
	ds_read2_b32 v[36:37], v115 offset0:212 offset1:213
	ds_read2_b32 v[38:39], v115 offset0:214 offset1:215
	ds_read2_b32 v[40:41], v115 offset0:221 offset1:222
	ds_read2_b32 v[42:43], v115 offset0:223 offset1:224
	ds_read2_b32 v[44:45], v115 offset0:229 offset1:230
	ds_read2_b32 v[46:47], v115 offset0:231 offset1:232
	s_waitcnt lgkmcnt(0)
	v_mfma_f32_32x32x16_bf16 v[32:47], v[156:159], v[48:51], v[32:47]
	ds_read_b64_tr_b16 v[72:73], v231
	ds_read_b64_tr_b16 v[74:75], v231 offset:512
	ds_read_b64_tr_b16 v[76:77], v231 offset:2048
	ds_read_b64_tr_b16 v[78:79], v231 offset:2560
	ds_read_b64_tr_b16 v[220:221], v231 offset:1024
	ds_read_b64_tr_b16 v[222:223], v231 offset:1536
	ds_read_b64_tr_b16 v[224:225], v231 offset:3072
	ds_read_b64_tr_b16 v[226:227], v231 offset:3584
	v_mfma_f32_32x32x16_bf16 v[32:47], v[160:163], v[52:55], v[32:47]
	v_mfma_f32_32x32x16_bf16 v[32:47], v[164:167], v[56:59], v[32:47]
	v_mfma_f32_32x32x16_bf16 v[32:47], v[168:171], v[60:63], v[32:47]
	s_nop 11
	v_exp_f32_e32 v32, v32
	v_exp_f32_e32 v33, v33
	v_exp_f32_e32 v34, v34
	v_exp_f32_e32 v35, v35
	v_exp_f32_e32 v36, v36
	v_exp_f32_e32 v37, v37
	v_exp_f32_e32 v38, v38
	v_exp_f32_e32 v39, v39
	v_exp_f32_e32 v40, v40
	v_exp_f32_e32 v41, v41
	v_exp_f32_e32 v42, v42
	v_exp_f32_e32 v43, v43
	v_exp_f32_e32 v44, v44
	v_exp_f32_e32 v45, v45
	v_exp_f32_e32 v46, v46
	v_exp_f32_e32 v47, v47
	v_cvt_pk_bf16_f32 v64, v32, v33
	v_cvt_pk_bf16_f32 v65, v34, v35
	v_cvt_pk_bf16_f32 v66, v36, v37
	v_cvt_pk_bf16_f32 v67, v38, v39
	v_cvt_pk_bf16_f32 v68, v40, v41
	v_cvt_pk_bf16_f32 v69, v42, v43
	v_cvt_pk_bf16_f32 v70, v44, v45
	v_cvt_pk_bf16_f32 v71, v46, v47
	v_pk_add_f32 v[232:233], v[232:233], v[32:33]
	v_pk_add_f32 v[232:233], v[232:233], v[34:35]
	v_pk_add_f32 v[232:233], v[232:233], v[36:37]
	v_pk_add_f32 v[232:233], v[232:233], v[38:39]
	v_pk_add_f32 v[232:233], v[232:233], v[40:41]
	v_pk_add_f32 v[232:233], v[232:233], v[42:43]
	v_pk_add_f32 v[232:233], v[232:233], v[44:45]
	v_pk_add_f32 v[232:233], v[232:233], v[46:47]
	s_waitcnt lgkmcnt(0)
	v_mfma_f32_32x32x16_bf16 v[0:15], v[64:67], v[72:75], v[0:15]
	v_mfma_f32_32x32x16_bf16 v[16:31], v[64:67], v[76:79], v[16:31]
	v_mfma_f32_32x32x16_bf16 v[0:15], v[68:71], v[220:223], v[0:15]
	v_mfma_f32_32x32x16_bf16 v[16:31], v[68:71], v[224:227], v[16:31]
	global_load_dwordx4 v[156:159], v235, s[84:85]
	global_load_dwordx4 v[160:163], v236, s[84:85]
	global_load_dwordx4 v[164:167], v237, s[84:85]
	global_load_dwordx4 v[168:171], v238, s[84:85]
	global_load_dwordx4 v[172:175], v100, s[84:85] offset:768
	global_load_dwordx4 v[176:179], v149, s[84:85] offset:768
	global_load_dwordx4 v[180:183], v100, s[84:85] offset:832
	global_load_dwordx4 v[184:187], v149, s[84:85] offset:832
	s_add_u32 s84, s84, 0x30000
	s_addc_u32 s85, s85, 0
	s_waitcnt vmcnt(16)
	ds_write_b128 v247, v[188:191]
	ds_write_b128 v247, v[192:195] offset:1024
	ds_write_b128 v247, v[196:199] offset:2048
	ds_write_b128 v247, v[200:203] offset:3072
	ds_read_b128 v[188:191], v248
	ds_read_b128 v[192:195], v249
	ds_read_b128 v[196:199], v250
	ds_read_b128 v[200:203], v251
	ds_write_b128 v112, v[204:207]
	ds_write_b128 v112, v[208:211] offset:1024
	ds_write_b128 v112, v[212:215] offset:2048
	ds_write_b128 v112, v[216:219] offset:3072
	v_add_u32_e32 v115, 952, v115
	ds_read2_b32 v[32:33], v115 offset0:0 offset1:1
	ds_read2_b32 v[34:35], v115 offset0:2 offset1:3
	ds_read2_b32 v[36:37], v115 offset0:8 offset1:9
	ds_read2_b32 v[38:39], v115 offset0:10 offset1:11
	ds_read2_b32 v[40:41], v115 offset0:17 offset1:18
	ds_read2_b32 v[42:43], v115 offset0:19 offset1:20
	ds_read2_b32 v[44:45], v115 offset0:25 offset1:26
	ds_read2_b32 v[46:47], v115 offset0:27 offset1:28
	s_waitcnt lgkmcnt(0)
	v_mfma_f32_32x32x16_bf16 v[32:47], v[188:191], v[48:51], v[32:47]
	ds_read_b64_tr_b16 v[72:73], v231
	ds_read_b64_tr_b16 v[74:75], v231 offset:512
	ds_read_b64_tr_b16 v[76:77], v231 offset:2048
	ds_read_b64_tr_b16 v[78:79], v231 offset:2560
	ds_read_b64_tr_b16 v[220:221], v231 offset:1024
	ds_read_b64_tr_b16 v[222:223], v231 offset:1536
	ds_read_b64_tr_b16 v[224:225], v231 offset:3072
	ds_read_b64_tr_b16 v[226:227], v231 offset:3584
	v_mfma_f32_32x32x16_bf16 v[32:47], v[192:195], v[52:55], v[32:47]
	v_mfma_f32_32x32x16_bf16 v[32:47], v[196:199], v[56:59], v[32:47]
	v_mfma_f32_32x32x16_bf16 v[32:47], v[200:203], v[60:63], v[32:47]
	s_nop 11
	v_exp_f32_e32 v32, v32
	v_exp_f32_e32 v33, v33
	v_exp_f32_e32 v34, v34
	v_exp_f32_e32 v35, v35
	v_exp_f32_e32 v36, v36
	v_exp_f32_e32 v37, v37
	v_exp_f32_e32 v38, v38
	v_exp_f32_e32 v39, v39
	v_exp_f32_e32 v40, v40
	v_exp_f32_e32 v41, v41
	v_exp_f32_e32 v42, v42
	v_exp_f32_e32 v43, v43
	v_exp_f32_e32 v44, v44
	v_exp_f32_e32 v45, v45
	v_exp_f32_e32 v46, v46
	v_exp_f32_e32 v47, v47
	v_cvt_pk_bf16_f32 v64, v32, v33
	v_cvt_pk_bf16_f32 v65, v34, v35
	v_cvt_pk_bf16_f32 v66, v36, v37
	v_cvt_pk_bf16_f32 v67, v38, v39
	v_cvt_pk_bf16_f32 v68, v40, v41
	v_cvt_pk_bf16_f32 v69, v42, v43
	v_cvt_pk_bf16_f32 v70, v44, v45
	v_cvt_pk_bf16_f32 v71, v46, v47
	v_pk_add_f32 v[232:233], v[232:233], v[32:33]
	v_pk_add_f32 v[232:233], v[232:233], v[34:35]
	v_pk_add_f32 v[232:233], v[232:233], v[36:37]
	v_pk_add_f32 v[232:233], v[232:233], v[38:39]
	v_pk_add_f32 v[232:233], v[232:233], v[40:41]
	v_pk_add_f32 v[232:233], v[232:233], v[42:43]
	v_pk_add_f32 v[232:233], v[232:233], v[44:45]
	v_pk_add_f32 v[232:233], v[232:233], v[46:47]
	s_waitcnt lgkmcnt(0)
	v_mfma_f32_32x32x16_bf16 v[0:15], v[64:67], v[72:75], v[0:15]
	v_mfma_f32_32x32x16_bf16 v[16:31], v[64:67], v[76:79], v[16:31]
	v_mfma_f32_32x32x16_bf16 v[0:15], v[68:71], v[220:223], v[0:15]
	v_mfma_f32_32x32x16_bf16 v[16:31], v[68:71], v[224:227], v[16:31]
	global_load_dwordx4 v[188:191], v235, s[84:85]
	global_load_dwordx4 v[192:195], v236, s[84:85]
	global_load_dwordx4 v[196:199], v237, s[84:85]
	global_load_dwordx4 v[200:203], v238, s[84:85]
	global_load_dwordx4 v[204:207], v100, s[84:85] offset:768
	global_load_dwordx4 v[208:211], v149, s[84:85] offset:768
	global_load_dwordx4 v[212:215], v100, s[84:85] offset:832
	global_load_dwordx4 v[216:219], v149, s[84:85] offset:832
	s_add_u32 s84, s84, 0x30000
	s_addc_u32 s85, s85, 0
	s_waitcnt vmcnt(16)
	ds_write_b128 v247, v[116:119]
	ds_write_b128 v247, v[120:123] offset:1024
	ds_write_b128 v247, v[124:127] offset:2048
	ds_write_b128 v247, v[128:131] offset:3072
	ds_read_b128 v[116:119], v248
	ds_read_b128 v[120:123], v249
	ds_read_b128 v[124:127], v250
	ds_read_b128 v[128:131], v251
	ds_write_b128 v112, v[132:135]
	ds_write_b128 v112, v[136:139] offset:1024
	ds_write_b128 v112, v[140:143] offset:2048
	ds_write_b128 v112, v[144:147] offset:3072
	ds_read2_b32 v[32:33], v115 offset0:34 offset1:35
	ds_read2_b32 v[34:35], v115 offset0:36 offset1:37
	ds_read2_b32 v[36:37], v115 offset0:42 offset1:43
	ds_read2_b32 v[38:39], v115 offset0:44 offset1:45
	ds_read2_b32 v[40:41], v115 offset0:51 offset1:52
	ds_read2_b32 v[42:43], v115 offset0:53 offset1:54
	ds_read2_b32 v[44:45], v115 offset0:59 offset1:60
	ds_read2_b32 v[46:47], v115 offset0:61 offset1:62
	s_waitcnt lgkmcnt(0)
	v_mfma_f32_32x32x16_bf16 v[32:47], v[116:119], v[48:51], v[32:47]
	ds_read_b64_tr_b16 v[72:73], v231
	ds_read_b64_tr_b16 v[74:75], v231 offset:512
	ds_read_b64_tr_b16 v[76:77], v231 offset:2048
	ds_read_b64_tr_b16 v[78:79], v231 offset:2560
	ds_read_b64_tr_b16 v[220:221], v231 offset:1024
	ds_read_b64_tr_b16 v[222:223], v231 offset:1536
	ds_read_b64_tr_b16 v[224:225], v231 offset:3072
	ds_read_b64_tr_b16 v[226:227], v231 offset:3584
	v_mfma_f32_32x32x16_bf16 v[32:47], v[120:123], v[52:55], v[32:47]
	v_mfma_f32_32x32x16_bf16 v[32:47], v[124:127], v[56:59], v[32:47]
	v_mfma_f32_32x32x16_bf16 v[32:47], v[128:131], v[60:63], v[32:47]
	s_nop 11
	v_exp_f32_e32 v32, v32
	v_exp_f32_e32 v33, v33
	v_exp_f32_e32 v34, v34
	v_exp_f32_e32 v35, v35
	v_exp_f32_e32 v36, v36
	v_exp_f32_e32 v37, v37
	v_exp_f32_e32 v38, v38
	v_exp_f32_e32 v39, v39
	v_exp_f32_e32 v40, v40
	v_exp_f32_e32 v41, v41
	v_exp_f32_e32 v42, v42
	v_exp_f32_e32 v43, v43
	v_exp_f32_e32 v44, v44
	v_exp_f32_e32 v45, v45
	v_exp_f32_e32 v46, v46
	v_exp_f32_e32 v47, v47
	v_cvt_pk_bf16_f32 v64, v32, v33
	v_cvt_pk_bf16_f32 v65, v34, v35
	v_cvt_pk_bf16_f32 v66, v36, v37
	v_cvt_pk_bf16_f32 v67, v38, v39
	v_cvt_pk_bf16_f32 v68, v40, v41
	v_cvt_pk_bf16_f32 v69, v42, v43
	v_cvt_pk_bf16_f32 v70, v44, v45
	v_cvt_pk_bf16_f32 v71, v46, v47
	v_pk_add_f32 v[232:233], v[232:233], v[32:33]
	v_pk_add_f32 v[232:233], v[232:233], v[34:35]
	v_pk_add_f32 v[232:233], v[232:233], v[36:37]
	v_pk_add_f32 v[232:233], v[232:233], v[38:39]
	v_pk_add_f32 v[232:233], v[232:233], v[40:41]
	v_pk_add_f32 v[232:233], v[232:233], v[42:43]
	v_pk_add_f32 v[232:233], v[232:233], v[44:45]
	v_pk_add_f32 v[232:233], v[232:233], v[46:47]
	s_waitcnt lgkmcnt(0)
	v_mfma_f32_32x32x16_bf16 v[0:15], v[64:67], v[72:75], v[0:15]
	v_mfma_f32_32x32x16_bf16 v[16:31], v[64:67], v[76:79], v[16:31]
	v_mfma_f32_32x32x16_bf16 v[0:15], v[68:71], v[220:223], v[0:15]
	v_mfma_f32_32x32x16_bf16 v[16:31], v[68:71], v[224:227], v[16:31]
	global_load_dwordx4 v[116:119], v235, s[84:85]
	global_load_dwordx4 v[120:123], v236, s[84:85]
	global_load_dwordx4 v[124:127], v237, s[84:85]
	global_load_dwordx4 v[128:131], v238, s[84:85]
	global_load_dwordx4 v[132:135], v100, s[84:85] offset:768
	global_load_dwordx4 v[136:139], v149, s[84:85] offset:768
	global_load_dwordx4 v[140:143], v100, s[84:85] offset:832
	global_load_dwordx4 v[144:147], v149, s[84:85] offset:832
	s_add_u32 s84, s84, 0x30000
	s_addc_u32 s85, s85, 0
	s_waitcnt vmcnt(16)
	ds_write_b128 v247, v[156:159]
	ds_write_b128 v247, v[160:163] offset:1024
	ds_write_b128 v247, v[164:167] offset:2048
	ds_write_b128 v247, v[168:171] offset:3072
	ds_read_b128 v[156:159], v248
	ds_read_b128 v[160:163], v249
	ds_read_b128 v[164:167], v250
	ds_read_b128 v[168:171], v251
	ds_write_b128 v112, v[172:175]
	ds_write_b128 v112, v[176:179] offset:1024
	ds_write_b128 v112, v[180:183] offset:2048
	ds_write_b128 v112, v[184:187] offset:3072
	ds_read2_b32 v[32:33], v115 offset0:68 offset1:69
	ds_read2_b32 v[34:35], v115 offset0:70 offset1:71
	ds_read2_b32 v[36:37], v115 offset0:76 offset1:77
	ds_read2_b32 v[38:39], v115 offset0:78 offset1:79
	ds_read2_b32 v[40:41], v115 offset0:85 offset1:86
	ds_read2_b32 v[42:43], v115 offset0:87 offset1:88
	ds_read2_b32 v[44:45], v115 offset0:93 offset1:94
	ds_read2_b32 v[46:47], v115 offset0:95 offset1:96
	s_waitcnt lgkmcnt(0)
	v_mfma_f32_32x32x16_bf16 v[32:47], v[156:159], v[48:51], v[32:47]
	ds_read_b64_tr_b16 v[72:73], v231
	ds_read_b64_tr_b16 v[74:75], v231 offset:512
	ds_read_b64_tr_b16 v[76:77], v231 offset:2048
	ds_read_b64_tr_b16 v[78:79], v231 offset:2560
	ds_read_b64_tr_b16 v[220:221], v231 offset:1024
	ds_read_b64_tr_b16 v[222:223], v231 offset:1536
	ds_read_b64_tr_b16 v[224:225], v231 offset:3072
	ds_read_b64_tr_b16 v[226:227], v231 offset:3584
	v_mfma_f32_32x32x16_bf16 v[32:47], v[160:163], v[52:55], v[32:47]
	v_mfma_f32_32x32x16_bf16 v[32:47], v[164:167], v[56:59], v[32:47]
	v_mfma_f32_32x32x16_bf16 v[32:47], v[168:171], v[60:63], v[32:47]
	s_nop 11
	v_exp_f32_e32 v32, v32
	v_exp_f32_e32 v33, v33
	v_exp_f32_e32 v34, v34
	v_exp_f32_e32 v35, v35
	v_exp_f32_e32 v36, v36
	v_exp_f32_e32 v37, v37
	v_exp_f32_e32 v38, v38
	v_exp_f32_e32 v39, v39
	v_exp_f32_e32 v40, v40
	v_exp_f32_e32 v41, v41
	v_exp_f32_e32 v42, v42
	v_exp_f32_e32 v43, v43
	v_exp_f32_e32 v44, v44
	v_exp_f32_e32 v45, v45
	v_exp_f32_e32 v46, v46
	v_exp_f32_e32 v47, v47
	v_cvt_pk_bf16_f32 v64, v32, v33
	v_cvt_pk_bf16_f32 v65, v34, v35
	v_cvt_pk_bf16_f32 v66, v36, v37
	v_cvt_pk_bf16_f32 v67, v38, v39
	v_cvt_pk_bf16_f32 v68, v40, v41
	v_cvt_pk_bf16_f32 v69, v42, v43
	v_cvt_pk_bf16_f32 v70, v44, v45
	v_cvt_pk_bf16_f32 v71, v46, v47
	v_pk_add_f32 v[232:233], v[232:233], v[32:33]
	v_pk_add_f32 v[232:233], v[232:233], v[34:35]
	v_pk_add_f32 v[232:233], v[232:233], v[36:37]
	v_pk_add_f32 v[232:233], v[232:233], v[38:39]
	v_pk_add_f32 v[232:233], v[232:233], v[40:41]
	v_pk_add_f32 v[232:233], v[232:233], v[42:43]
	v_pk_add_f32 v[232:233], v[232:233], v[44:45]
	v_pk_add_f32 v[232:233], v[232:233], v[46:47]
	s_waitcnt lgkmcnt(0)
	v_mfma_f32_32x32x16_bf16 v[0:15], v[64:67], v[72:75], v[0:15]
	v_mfma_f32_32x32x16_bf16 v[16:31], v[64:67], v[76:79], v[16:31]
	v_mfma_f32_32x32x16_bf16 v[0:15], v[68:71], v[220:223], v[0:15]
	v_mfma_f32_32x32x16_bf16 v[16:31], v[68:71], v[224:227], v[16:31]
	global_load_dwordx4 v[156:159], v235, s[84:85]
	global_load_dwordx4 v[160:163], v236, s[84:85]
	global_load_dwordx4 v[164:167], v237, s[84:85]
	global_load_dwordx4 v[168:171], v238, s[84:85]
	global_load_dwordx4 v[172:175], v100, s[84:85] offset:768
	global_load_dwordx4 v[176:179], v149, s[84:85] offset:768
	global_load_dwordx4 v[180:183], v100, s[84:85] offset:832
	global_load_dwordx4 v[184:187], v149, s[84:85] offset:832
	s_waitcnt vmcnt(16)
	ds_write_b128 v247, v[188:191]
	ds_write_b128 v247, v[192:195] offset:1024
	ds_write_b128 v247, v[196:199] offset:2048
	ds_write_b128 v247, v[200:203] offset:3072
	ds_read_b128 v[188:191], v248
	ds_read_b128 v[192:195], v249
	ds_read_b128 v[196:199], v250
	ds_read_b128 v[200:203], v251
	ds_write_b128 v112, v[204:207]
	ds_write_b128 v112, v[208:211] offset:1024
	ds_write_b128 v112, v[212:215] offset:2048
	ds_write_b128 v112, v[216:219] offset:3072
	ds_read2_b32 v[32:33], v115 offset0:102 offset1:103
	ds_read2_b32 v[34:35], v115 offset0:104 offset1:105
	ds_read2_b32 v[36:37], v115 offset0:110 offset1:111
	ds_read2_b32 v[38:39], v115 offset0:112 offset1:113
	ds_read2_b32 v[40:41], v115 offset0:119 offset1:120
	ds_read2_b32 v[42:43], v115 offset0:121 offset1:122
	ds_read2_b32 v[44:45], v115 offset0:127 offset1:128
	ds_read2_b32 v[46:47], v115 offset0:129 offset1:130
	s_waitcnt lgkmcnt(0)
	v_mfma_f32_32x32x16_bf16 v[32:47], v[188:191], v[48:51], v[32:47]
	ds_read_b64_tr_b16 v[72:73], v231
	ds_read_b64_tr_b16 v[74:75], v231 offset:512
	ds_read_b64_tr_b16 v[76:77], v231 offset:2048
	ds_read_b64_tr_b16 v[78:79], v231 offset:2560
	ds_read_b64_tr_b16 v[220:221], v231 offset:1024
	ds_read_b64_tr_b16 v[222:223], v231 offset:1536
	ds_read_b64_tr_b16 v[224:225], v231 offset:3072
	ds_read_b64_tr_b16 v[226:227], v231 offset:3584
	v_mfma_f32_32x32x16_bf16 v[32:47], v[192:195], v[52:55], v[32:47]
	v_mfma_f32_32x32x16_bf16 v[32:47], v[196:199], v[56:59], v[32:47]
	v_mfma_f32_32x32x16_bf16 v[32:47], v[200:203], v[60:63], v[32:47]
	s_nop 11
	v_exp_f32_e32 v32, v32
	v_exp_f32_e32 v33, v33
	v_exp_f32_e32 v34, v34
	v_exp_f32_e32 v35, v35
	v_exp_f32_e32 v36, v36
	v_exp_f32_e32 v37, v37
	v_exp_f32_e32 v38, v38
	v_exp_f32_e32 v39, v39
	v_exp_f32_e32 v40, v40
	v_exp_f32_e32 v41, v41
	v_exp_f32_e32 v42, v42
	v_exp_f32_e32 v43, v43
	v_exp_f32_e32 v44, v44
	v_exp_f32_e32 v45, v45
	v_exp_f32_e32 v46, v46
	v_exp_f32_e32 v47, v47
	v_cvt_pk_bf16_f32 v64, v32, v33
	v_cvt_pk_bf16_f32 v65, v34, v35
	v_cvt_pk_bf16_f32 v66, v36, v37
	v_cvt_pk_bf16_f32 v67, v38, v39
	v_cvt_pk_bf16_f32 v68, v40, v41
	v_cvt_pk_bf16_f32 v69, v42, v43
	v_cvt_pk_bf16_f32 v70, v44, v45
	v_cvt_pk_bf16_f32 v71, v46, v47
	v_pk_add_f32 v[232:233], v[232:233], v[32:33]
	v_pk_add_f32 v[232:233], v[232:233], v[34:35]
	v_pk_add_f32 v[232:233], v[232:233], v[36:37]
	v_pk_add_f32 v[232:233], v[232:233], v[38:39]
	v_pk_add_f32 v[232:233], v[232:233], v[40:41]
	v_pk_add_f32 v[232:233], v[232:233], v[42:43]
	v_pk_add_f32 v[232:233], v[232:233], v[44:45]
	v_pk_add_f32 v[232:233], v[232:233], v[46:47]
	s_waitcnt lgkmcnt(0)
	v_mfma_f32_32x32x16_bf16 v[0:15], v[64:67], v[72:75], v[0:15]
	v_mfma_f32_32x32x16_bf16 v[16:31], v[64:67], v[76:79], v[16:31]
	v_mfma_f32_32x32x16_bf16 v[0:15], v[68:71], v[220:223], v[0:15]
	v_mfma_f32_32x32x16_bf16 v[16:31], v[68:71], v[224:227], v[16:31]
	global_load_dwordx4 v[188:191], v239, s[86:87]
	global_load_dwordx4 v[192:195], v240, s[86:87]
	global_load_dwordx4 v[196:199], v241, s[86:87]
	global_load_dwordx4 v[200:203], v242, s[86:87]
	global_load_dwordx4 v[204:207], v101, s[86:87] offset:768
	global_load_dwordx4 v[208:211], v150, s[86:87] offset:768
	global_load_dwordx4 v[212:215], v101, s[86:87] offset:832
	global_load_dwordx4 v[216:219], v150, s[86:87] offset:832
	s_add_u32 s86, s86, 0xc0000
	s_addc_u32 s87, s87, 0
	s_waitcnt vmcnt(16)
	ds_write_b128 v247, v[116:119]
	ds_write_b128 v247, v[120:123] offset:1024
	ds_write_b128 v247, v[124:127] offset:2048
	ds_write_b128 v247, v[128:131] offset:3072
	ds_read_b128 v[116:119], v248
	ds_read_b128 v[120:123], v249
	ds_read_b128 v[124:127], v250
	ds_read_b128 v[128:131], v251
	ds_write_b128 v112, v[132:135]
	ds_write_b128 v112, v[136:139] offset:1024
	ds_write_b128 v112, v[140:143] offset:2048
	ds_write_b128 v112, v[144:147] offset:3072
	ds_read2_b32 v[32:33], v115 offset0:136 offset1:137
	ds_read2_b32 v[34:35], v115 offset0:138 offset1:139
	ds_read2_b32 v[36:37], v115 offset0:144 offset1:145
	ds_read2_b32 v[38:39], v115 offset0:146 offset1:147
	ds_read2_b32 v[40:41], v115 offset0:153 offset1:154
	ds_read2_b32 v[42:43], v115 offset0:155 offset1:156
	ds_read2_b32 v[44:45], v115 offset0:161 offset1:162
	ds_read2_b32 v[46:47], v115 offset0:163 offset1:164
	s_waitcnt lgkmcnt(0)
	v_mfma_f32_32x32x16_bf16 v[32:47], v[116:119], v[48:51], v[32:47]
	ds_read_b64_tr_b16 v[72:73], v231
	ds_read_b64_tr_b16 v[74:75], v231 offset:512
	ds_read_b64_tr_b16 v[76:77], v231 offset:2048
	ds_read_b64_tr_b16 v[78:79], v231 offset:2560
	ds_read_b64_tr_b16 v[220:221], v231 offset:1024
	ds_read_b64_tr_b16 v[222:223], v231 offset:1536
	ds_read_b64_tr_b16 v[224:225], v231 offset:3072
	ds_read_b64_tr_b16 v[226:227], v231 offset:3584
	v_mfma_f32_32x32x16_bf16 v[32:47], v[120:123], v[52:55], v[32:47]
	v_mfma_f32_32x32x16_bf16 v[32:47], v[124:127], v[56:59], v[32:47]
	v_mfma_f32_32x32x16_bf16 v[32:47], v[128:131], v[60:63], v[32:47]
	s_nop 11
	v_exp_f32_e32 v32, v32
	v_exp_f32_e32 v33, v33
	v_exp_f32_e32 v34, v34
	v_exp_f32_e32 v35, v35
	v_exp_f32_e32 v36, v36
	v_exp_f32_e32 v37, v37
	v_exp_f32_e32 v38, v38
	v_exp_f32_e32 v39, v39
	v_exp_f32_e32 v40, v40
	v_exp_f32_e32 v41, v41
	v_exp_f32_e32 v42, v42
	v_exp_f32_e32 v43, v43
	v_exp_f32_e32 v44, v44
	v_exp_f32_e32 v45, v45
	v_exp_f32_e32 v46, v46
	v_exp_f32_e32 v47, v47
	v_cvt_pk_bf16_f32 v64, v32, v33
	v_cvt_pk_bf16_f32 v65, v34, v35
	v_cvt_pk_bf16_f32 v66, v36, v37
	v_cvt_pk_bf16_f32 v67, v38, v39
	v_cvt_pk_bf16_f32 v68, v40, v41
	v_cvt_pk_bf16_f32 v69, v42, v43
	v_cvt_pk_bf16_f32 v70, v44, v45
	v_cvt_pk_bf16_f32 v71, v46, v47
	v_pk_add_f32 v[232:233], v[232:233], v[32:33]
	v_pk_add_f32 v[232:233], v[232:233], v[34:35]
	v_pk_add_f32 v[232:233], v[232:233], v[36:37]
	v_pk_add_f32 v[232:233], v[232:233], v[38:39]
	v_pk_add_f32 v[232:233], v[232:233], v[40:41]
	v_pk_add_f32 v[232:233], v[232:233], v[42:43]
	v_pk_add_f32 v[232:233], v[232:233], v[44:45]
	v_pk_add_f32 v[232:233], v[232:233], v[46:47]
	s_waitcnt lgkmcnt(0)
	v_mfma_f32_32x32x16_bf16 v[0:15], v[64:67], v[72:75], v[0:15]
	v_mfma_f32_32x32x16_bf16 v[16:31], v[64:67], v[76:79], v[16:31]
	v_mfma_f32_32x32x16_bf16 v[0:15], v[68:71], v[220:223], v[0:15]
	v_mfma_f32_32x32x16_bf16 v[16:31], v[68:71], v[224:227], v[16:31]
	global_load_dwordx4 v[116:119], v239, s[86:87]
	global_load_dwordx4 v[120:123], v240, s[86:87]
	global_load_dwordx4 v[124:127], v241, s[86:87]
	global_load_dwordx4 v[128:131], v242, s[86:87]
	global_load_dwordx4 v[132:135], v101, s[86:87] offset:768
	global_load_dwordx4 v[136:139], v150, s[86:87] offset:768
	global_load_dwordx4 v[140:143], v101, s[86:87] offset:832
	global_load_dwordx4 v[144:147], v150, s[86:87] offset:832
	s_add_u32 s86, s86, 0xc0000
	s_addc_u32 s87, s87, 0
	s_waitcnt vmcnt(16)
	ds_write_b128 v247, v[156:159]
	ds_write_b128 v247, v[160:163] offset:1024
	ds_write_b128 v247, v[164:167] offset:2048
	ds_write_b128 v247, v[168:171] offset:3072
	ds_read_b128 v[156:159], v248
	ds_read_b128 v[160:163], v249
	ds_read_b128 v[164:167], v250
	ds_read_b128 v[168:171], v251
	ds_write_b128 v112, v[172:175]
	ds_write_b128 v112, v[176:179] offset:1024
	ds_write_b128 v112, v[180:183] offset:2048
	ds_write_b128 v112, v[184:187] offset:3072
	ds_read2_b32 v[32:33], v115 offset0:170 offset1:171
	ds_read2_b32 v[34:35], v115 offset0:172 offset1:173
	ds_read2_b32 v[36:37], v115 offset0:178 offset1:179
	ds_read2_b32 v[38:39], v115 offset0:180 offset1:181
	ds_read2_b32 v[40:41], v115 offset0:187 offset1:188
	ds_read2_b32 v[42:43], v115 offset0:189 offset1:190
	ds_read2_b32 v[44:45], v115 offset0:195 offset1:196
	ds_read2_b32 v[46:47], v115 offset0:197 offset1:198
	s_waitcnt lgkmcnt(0)
	v_mfma_f32_32x32x16_bf16 v[32:47], v[156:159], v[48:51], v[32:47]
	ds_read_b64_tr_b16 v[72:73], v231
	ds_read_b64_tr_b16 v[74:75], v231 offset:512
	ds_read_b64_tr_b16 v[76:77], v231 offset:2048
	ds_read_b64_tr_b16 v[78:79], v231 offset:2560
	ds_read_b64_tr_b16 v[220:221], v231 offset:1024
	ds_read_b64_tr_b16 v[222:223], v231 offset:1536
	ds_read_b64_tr_b16 v[224:225], v231 offset:3072
	ds_read_b64_tr_b16 v[226:227], v231 offset:3584
	v_mfma_f32_32x32x16_bf16 v[32:47], v[160:163], v[52:55], v[32:47]
	v_mfma_f32_32x32x16_bf16 v[32:47], v[164:167], v[56:59], v[32:47]
	v_mfma_f32_32x32x16_bf16 v[32:47], v[168:171], v[60:63], v[32:47]
	s_nop 11
	v_exp_f32_e32 v32, v32
	v_exp_f32_e32 v33, v33
	v_exp_f32_e32 v34, v34
	v_exp_f32_e32 v35, v35
	v_exp_f32_e32 v36, v36
	v_exp_f32_e32 v37, v37
	v_exp_f32_e32 v38, v38
	v_exp_f32_e32 v39, v39
	v_exp_f32_e32 v40, v40
	v_exp_f32_e32 v41, v41
	v_exp_f32_e32 v42, v42
	v_exp_f32_e32 v43, v43
	v_exp_f32_e32 v44, v44
	v_exp_f32_e32 v45, v45
	v_exp_f32_e32 v46, v46
	v_exp_f32_e32 v47, v47
	v_cvt_pk_bf16_f32 v64, v32, v33
	v_cvt_pk_bf16_f32 v65, v34, v35
	v_cvt_pk_bf16_f32 v66, v36, v37
	v_cvt_pk_bf16_f32 v67, v38, v39
	v_cvt_pk_bf16_f32 v68, v40, v41
	v_cvt_pk_bf16_f32 v69, v42, v43
	v_cvt_pk_bf16_f32 v70, v44, v45
	v_cvt_pk_bf16_f32 v71, v46, v47
	v_pk_add_f32 v[232:233], v[232:233], v[32:33]
	v_pk_add_f32 v[232:233], v[232:233], v[34:35]
	v_pk_add_f32 v[232:233], v[232:233], v[36:37]
	v_pk_add_f32 v[232:233], v[232:233], v[38:39]
	v_pk_add_f32 v[232:233], v[232:233], v[40:41]
	v_pk_add_f32 v[232:233], v[232:233], v[42:43]
	v_pk_add_f32 v[232:233], v[232:233], v[44:45]
	v_pk_add_f32 v[232:233], v[232:233], v[46:47]
	s_waitcnt lgkmcnt(0)
	v_mfma_f32_32x32x16_bf16 v[0:15], v[64:67], v[72:75], v[0:15]
	v_mfma_f32_32x32x16_bf16 v[16:31], v[64:67], v[76:79], v[16:31]
	v_mfma_f32_32x32x16_bf16 v[0:15], v[68:71], v[220:223], v[0:15]
	v_mfma_f32_32x32x16_bf16 v[16:31], v[68:71], v[224:227], v[16:31]
	global_load_dwordx4 v[156:159], v239, s[86:87]
	global_load_dwordx4 v[160:163], v240, s[86:87]
	global_load_dwordx4 v[164:167], v241, s[86:87]
	global_load_dwordx4 v[168:171], v242, s[86:87]
	global_load_dwordx4 v[172:175], v101, s[86:87] offset:768
	global_load_dwordx4 v[176:179], v150, s[86:87] offset:768
	global_load_dwordx4 v[180:183], v101, s[86:87] offset:832
	global_load_dwordx4 v[184:187], v150, s[86:87] offset:832
	s_add_u32 s86, s86, 0xc0000
	s_addc_u32 s87, s87, 0
	s_waitcnt vmcnt(16)
	ds_write_b128 v247, v[188:191]
	ds_write_b128 v247, v[192:195] offset:1024
	ds_write_b128 v247, v[196:199] offset:2048
	ds_write_b128 v247, v[200:203] offset:3072
	ds_read_b128 v[188:191], v248
	ds_read_b128 v[192:195], v249
	ds_read_b128 v[196:199], v250
	ds_read_b128 v[200:203], v251
	ds_write_b128 v112, v[204:207]
	ds_write_b128 v112, v[208:211] offset:1024
	ds_write_b128 v112, v[212:215] offset:2048
	ds_write_b128 v112, v[216:219] offset:3072
	v_mov_b32_e32 v115, v229
	ds_read2_b32 v[32:33], v115 offset0:0 offset1:1
	ds_read2_b32 v[34:35], v115 offset0:2 offset1:3
	ds_read2_b32 v[36:37], v115 offset0:8 offset1:9
	ds_read2_b32 v[38:39], v115 offset0:10 offset1:11
	ds_read2_b32 v[40:41], v115 offset0:16 offset1:17
	ds_read2_b32 v[42:43], v115 offset0:18 offset1:19
	ds_read2_b32 v[44:45], v115 offset0:24 offset1:25
	ds_read2_b32 v[46:47], v115 offset0:26 offset1:27
	s_waitcnt lgkmcnt(0)
	v_mfma_f32_32x32x16_bf16 v[32:47], v[188:191], v[48:51], v[32:47]
	ds_read_b64_tr_b16 v[72:73], v231
	ds_read_b64_tr_b16 v[74:75], v231 offset:512
	ds_read_b64_tr_b16 v[76:77], v231 offset:2048
	ds_read_b64_tr_b16 v[78:79], v231 offset:2560
	ds_read_b64_tr_b16 v[220:221], v231 offset:1024
	ds_read_b64_tr_b16 v[222:223], v231 offset:1536
	ds_read_b64_tr_b16 v[224:225], v231 offset:3072
	ds_read_b64_tr_b16 v[226:227], v231 offset:3584
	v_mfma_f32_32x32x16_bf16 v[32:47], v[192:195], v[52:55], v[32:47]
	v_mfma_f32_32x32x16_bf16 v[32:47], v[196:199], v[56:59], v[32:47]
	v_mfma_f32_32x32x16_bf16 v[32:47], v[200:203], v[60:63], v[32:47]
	s_nop 11
	v_exp_f32_e32 v32, v32
	v_exp_f32_e32 v33, v33
	v_exp_f32_e32 v34, v34
	v_exp_f32_e32 v35, v35
	v_exp_f32_e32 v36, v36
	v_exp_f32_e32 v37, v37
	v_exp_f32_e32 v38, v38
	v_exp_f32_e32 v39, v39
	v_exp_f32_e32 v40, v40
	v_exp_f32_e32 v41, v41
	v_exp_f32_e32 v42, v42
	v_exp_f32_e32 v43, v43
	v_exp_f32_e32 v44, v44
	v_exp_f32_e32 v45, v45
	v_exp_f32_e32 v46, v46
	v_exp_f32_e32 v47, v47
	v_cvt_pk_bf16_f32 v64, v32, v33
	v_cvt_pk_bf16_f32 v65, v34, v35
	v_cvt_pk_bf16_f32 v66, v36, v37
	v_cvt_pk_bf16_f32 v67, v38, v39
	v_cvt_pk_bf16_f32 v68, v40, v41
	v_cvt_pk_bf16_f32 v69, v42, v43
	v_cvt_pk_bf16_f32 v70, v44, v45
	v_cvt_pk_bf16_f32 v71, v46, v47
	v_pk_add_f32 v[232:233], v[232:233], v[32:33]
	v_pk_add_f32 v[232:233], v[232:233], v[34:35]
	v_pk_add_f32 v[232:233], v[232:233], v[36:37]
	v_pk_add_f32 v[232:233], v[232:233], v[38:39]
	v_pk_add_f32 v[232:233], v[232:233], v[40:41]
	v_pk_add_f32 v[232:233], v[232:233], v[42:43]
	v_pk_add_f32 v[232:233], v[232:233], v[44:45]
	v_pk_add_f32 v[232:233], v[232:233], v[46:47]
	s_waitcnt lgkmcnt(0)
	v_mfma_f32_32x32x16_bf16 v[0:15], v[64:67], v[72:75], v[0:15]
	v_mfma_f32_32x32x16_bf16 v[16:31], v[64:67], v[76:79], v[16:31]
	v_mfma_f32_32x32x16_bf16 v[0:15], v[68:71], v[220:223], v[0:15]
	v_mfma_f32_32x32x16_bf16 v[16:31], v[68:71], v[224:227], v[16:31]
	global_load_dwordx4 v[188:191], v239, s[86:87]
	global_load_dwordx4 v[192:195], v240, s[86:87]
	global_load_dwordx4 v[196:199], v241, s[86:87]
	global_load_dwordx4 v[200:203], v242, s[86:87]
	global_load_dwordx4 v[204:207], v101, s[86:87] offset:768
	global_load_dwordx4 v[208:211], v150, s[86:87] offset:768
	global_load_dwordx4 v[212:215], v101, s[86:87] offset:832
	global_load_dwordx4 v[216:219], v150, s[86:87] offset:832
	s_add_u32 s86, s86, 0xc0000
	s_addc_u32 s87, s87, 0
	s_waitcnt vmcnt(16)
	ds_write_b128 v247, v[116:119]
	ds_write_b128 v247, v[120:123] offset:1024
	ds_write_b128 v247, v[124:127] offset:2048
	ds_write_b128 v247, v[128:131] offset:3072
	ds_read_b128 v[116:119], v248
	ds_read_b128 v[120:123], v249
	ds_read_b128 v[124:127], v250
	ds_read_b128 v[128:131], v251
	ds_write_b128 v112, v[132:135]
	ds_write_b128 v112, v[136:139] offset:1024
	ds_write_b128 v112, v[140:143] offset:2048
	ds_write_b128 v112, v[144:147] offset:3072
	ds_read2_b32 v[32:33], v115 offset0:32 offset1:33
	ds_read2_b32 v[34:35], v115 offset0:34 offset1:35
	ds_read2_b32 v[36:37], v115 offset0:40 offset1:41
	ds_read2_b32 v[38:39], v115 offset0:42 offset1:43
	ds_read2_b32 v[40:41], v115 offset0:48 offset1:49
	ds_read2_b32 v[42:43], v115 offset0:50 offset1:51
	ds_read2_b32 v[44:45], v115 offset0:56 offset1:57
	ds_read2_b32 v[46:47], v115 offset0:58 offset1:59
	s_waitcnt lgkmcnt(0)
	v_mfma_f32_32x32x16_bf16 v[32:47], v[116:119], v[48:51], v[32:47]
	ds_read_b64_tr_b16 v[72:73], v231
	ds_read_b64_tr_b16 v[74:75], v231 offset:512
	ds_read_b64_tr_b16 v[76:77], v231 offset:2048
	ds_read_b64_tr_b16 v[78:79], v231 offset:2560
	ds_read_b64_tr_b16 v[220:221], v231 offset:1024
	ds_read_b64_tr_b16 v[222:223], v231 offset:1536
	ds_read_b64_tr_b16 v[224:225], v231 offset:3072
	ds_read_b64_tr_b16 v[226:227], v231 offset:3584
	v_mfma_f32_32x32x16_bf16 v[32:47], v[120:123], v[52:55], v[32:47]
	v_mfma_f32_32x32x16_bf16 v[32:47], v[124:127], v[56:59], v[32:47]
	v_mfma_f32_32x32x16_bf16 v[32:47], v[128:131], v[60:63], v[32:47]
	s_nop 11
	v_exp_f32_e32 v32, v32
	v_exp_f32_e32 v33, v33
	v_exp_f32_e32 v34, v34
	v_exp_f32_e32 v35, v35
	v_exp_f32_e32 v36, v36
	v_exp_f32_e32 v37, v37
	v_exp_f32_e32 v38, v38
	v_exp_f32_e32 v39, v39
	v_exp_f32_e32 v40, v40
	v_exp_f32_e32 v41, v41
	v_exp_f32_e32 v42, v42
	v_exp_f32_e32 v43, v43
	v_exp_f32_e32 v44, v44
	v_exp_f32_e32 v45, v45
	v_exp_f32_e32 v46, v46
	v_exp_f32_e32 v47, v47
	v_cvt_pk_bf16_f32 v64, v32, v33
	v_cvt_pk_bf16_f32 v65, v34, v35
	v_cvt_pk_bf16_f32 v66, v36, v37
	v_cvt_pk_bf16_f32 v67, v38, v39
	v_cvt_pk_bf16_f32 v68, v40, v41
	v_cvt_pk_bf16_f32 v69, v42, v43
	v_cvt_pk_bf16_f32 v70, v44, v45
	v_cvt_pk_bf16_f32 v71, v46, v47
	v_pk_add_f32 v[232:233], v[232:233], v[32:33]
	v_pk_add_f32 v[232:233], v[232:233], v[34:35]
	v_pk_add_f32 v[232:233], v[232:233], v[36:37]
	v_pk_add_f32 v[232:233], v[232:233], v[38:39]
	v_pk_add_f32 v[232:233], v[232:233], v[40:41]
	v_pk_add_f32 v[232:233], v[232:233], v[42:43]
	v_pk_add_f32 v[232:233], v[232:233], v[44:45]
	v_pk_add_f32 v[232:233], v[232:233], v[46:47]
	s_waitcnt lgkmcnt(0)
	v_mfma_f32_32x32x16_bf16 v[0:15], v[64:67], v[72:75], v[0:15]
	v_mfma_f32_32x32x16_bf16 v[16:31], v[64:67], v[76:79], v[16:31]
	v_mfma_f32_32x32x16_bf16 v[0:15], v[68:71], v[220:223], v[0:15]
	v_mfma_f32_32x32x16_bf16 v[16:31], v[68:71], v[224:227], v[16:31]
	global_load_dwordx4 v[116:119], v239, s[86:87]
	global_load_dwordx4 v[120:123], v240, s[86:87]
	global_load_dwordx4 v[124:127], v241, s[86:87]
	global_load_dwordx4 v[128:131], v242, s[86:87]
	global_load_dwordx4 v[132:135], v101, s[86:87] offset:768
	global_load_dwordx4 v[136:139], v150, s[86:87] offset:768
	global_load_dwordx4 v[140:143], v101, s[86:87] offset:832
	global_load_dwordx4 v[144:147], v150, s[86:87] offset:832
	s_add_u32 s86, s86, 0xc0000
	s_addc_u32 s87, s87, 0
	s_waitcnt vmcnt(16)
	ds_write_b128 v247, v[156:159]
	ds_write_b128 v247, v[160:163] offset:1024
	ds_write_b128 v247, v[164:167] offset:2048
	ds_write_b128 v247, v[168:171] offset:3072
	ds_read_b128 v[156:159], v248
	ds_read_b128 v[160:163], v249
	ds_read_b128 v[164:167], v250
	ds_read_b128 v[168:171], v251
	ds_write_b128 v112, v[172:175]
	ds_write_b128 v112, v[176:179] offset:1024
	ds_write_b128 v112, v[180:183] offset:2048
	ds_write_b128 v112, v[184:187] offset:3072
	ds_read2_b32 v[32:33], v115 offset0:64 offset1:65
	ds_read2_b32 v[34:35], v115 offset0:66 offset1:67
	ds_read2_b32 v[36:37], v115 offset0:72 offset1:73
	ds_read2_b32 v[38:39], v115 offset0:74 offset1:75
	ds_read2_b32 v[40:41], v115 offset0:80 offset1:81
	ds_read2_b32 v[42:43], v115 offset0:82 offset1:83
	ds_read2_b32 v[44:45], v115 offset0:88 offset1:89
	ds_read2_b32 v[46:47], v115 offset0:90 offset1:91
	s_waitcnt lgkmcnt(0)
	v_mfma_f32_32x32x16_bf16 v[32:47], v[156:159], v[48:51], v[32:47]
	ds_read_b64_tr_b16 v[72:73], v231
	ds_read_b64_tr_b16 v[74:75], v231 offset:512
	ds_read_b64_tr_b16 v[76:77], v231 offset:2048
	ds_read_b64_tr_b16 v[78:79], v231 offset:2560
	ds_read_b64_tr_b16 v[220:221], v231 offset:1024
	ds_read_b64_tr_b16 v[222:223], v231 offset:1536
	ds_read_b64_tr_b16 v[224:225], v231 offset:3072
	ds_read_b64_tr_b16 v[226:227], v231 offset:3584
	v_mfma_f32_32x32x16_bf16 v[32:47], v[160:163], v[52:55], v[32:47]
	v_mfma_f32_32x32x16_bf16 v[32:47], v[164:167], v[56:59], v[32:47]
	v_mfma_f32_32x32x16_bf16 v[32:47], v[168:171], v[60:63], v[32:47]
	s_nop 11
	v_exp_f32_e32 v32, v32
	v_exp_f32_e32 v33, v33
	v_exp_f32_e32 v34, v34
	v_exp_f32_e32 v35, v35
	v_exp_f32_e32 v36, v36
	v_exp_f32_e32 v37, v37
	v_exp_f32_e32 v38, v38
	v_exp_f32_e32 v39, v39
	v_exp_f32_e32 v40, v40
	v_exp_f32_e32 v41, v41
	v_exp_f32_e32 v42, v42
	v_exp_f32_e32 v43, v43
	v_exp_f32_e32 v44, v44
	v_exp_f32_e32 v45, v45
	v_exp_f32_e32 v46, v46
	v_exp_f32_e32 v47, v47
	v_cvt_pk_bf16_f32 v64, v32, v33
	v_cvt_pk_bf16_f32 v65, v34, v35
	v_cvt_pk_bf16_f32 v66, v36, v37
	v_cvt_pk_bf16_f32 v67, v38, v39
	v_cvt_pk_bf16_f32 v68, v40, v41
	v_cvt_pk_bf16_f32 v69, v42, v43
	v_cvt_pk_bf16_f32 v70, v44, v45
	v_cvt_pk_bf16_f32 v71, v46, v47
	v_pk_add_f32 v[232:233], v[232:233], v[32:33]
	v_pk_add_f32 v[232:233], v[232:233], v[34:35]
	v_pk_add_f32 v[232:233], v[232:233], v[36:37]
	v_pk_add_f32 v[232:233], v[232:233], v[38:39]
	v_pk_add_f32 v[232:233], v[232:233], v[40:41]
	v_pk_add_f32 v[232:233], v[232:233], v[42:43]
	v_pk_add_f32 v[232:233], v[232:233], v[44:45]
	v_pk_add_f32 v[232:233], v[232:233], v[46:47]
	s_waitcnt lgkmcnt(0)
	v_mfma_f32_32x32x16_bf16 v[0:15], v[64:67], v[72:75], v[0:15]
	v_mfma_f32_32x32x16_bf16 v[16:31], v[64:67], v[76:79], v[16:31]
	v_mfma_f32_32x32x16_bf16 v[0:15], v[68:71], v[220:223], v[0:15]
	v_mfma_f32_32x32x16_bf16 v[16:31], v[68:71], v[224:227], v[16:31]
	global_load_dwordx4 v[156:159], v239, s[86:87]
	global_load_dwordx4 v[160:163], v240, s[86:87]
	global_load_dwordx4 v[164:167], v241, s[86:87]
	global_load_dwordx4 v[168:171], v242, s[86:87]
	global_load_dwordx4 v[172:175], v101, s[86:87] offset:768
	global_load_dwordx4 v[176:179], v150, s[86:87] offset:768
	global_load_dwordx4 v[180:183], v101, s[86:87] offset:832
	global_load_dwordx4 v[184:187], v150, s[86:87] offset:832
	s_add_u32 s86, s86, 0xc0000
	s_addc_u32 s87, s87, 0
	s_waitcnt vmcnt(16)
	ds_write_b128 v247, v[188:191]
	ds_write_b128 v247, v[192:195] offset:1024
	ds_write_b128 v247, v[196:199] offset:2048
	ds_write_b128 v247, v[200:203] offset:3072
	ds_read_b128 v[188:191], v248
	ds_read_b128 v[192:195], v249
	ds_read_b128 v[196:199], v250
	ds_read_b128 v[200:203], v251
	ds_write_b128 v112, v[204:207]
	ds_write_b128 v112, v[208:211] offset:1024
	ds_write_b128 v112, v[212:215] offset:2048
	ds_write_b128 v112, v[216:219] offset:3072
	ds_read2_b32 v[32:33], v115 offset0:96 offset1:97
	ds_read2_b32 v[34:35], v115 offset0:98 offset1:99
	ds_read2_b32 v[36:37], v115 offset0:104 offset1:105
	ds_read2_b32 v[38:39], v115 offset0:106 offset1:107
	ds_read2_b32 v[40:41], v115 offset0:112 offset1:113
	ds_read2_b32 v[42:43], v115 offset0:114 offset1:115
	ds_read2_b32 v[44:45], v115 offset0:120 offset1:121
	ds_read2_b32 v[46:47], v115 offset0:122 offset1:123
	s_waitcnt lgkmcnt(0)
	v_mfma_f32_32x32x16_bf16 v[32:47], v[188:191], v[48:51], v[32:47]
	ds_read_b64_tr_b16 v[72:73], v231
	ds_read_b64_tr_b16 v[74:75], v231 offset:512
	ds_read_b64_tr_b16 v[76:77], v231 offset:2048
	ds_read_b64_tr_b16 v[78:79], v231 offset:2560
	ds_read_b64_tr_b16 v[220:221], v231 offset:1024
	ds_read_b64_tr_b16 v[222:223], v231 offset:1536
	ds_read_b64_tr_b16 v[224:225], v231 offset:3072
	ds_read_b64_tr_b16 v[226:227], v231 offset:3584
	v_mfma_f32_32x32x16_bf16 v[32:47], v[192:195], v[52:55], v[32:47]
	v_mfma_f32_32x32x16_bf16 v[32:47], v[196:199], v[56:59], v[32:47]
	v_mfma_f32_32x32x16_bf16 v[32:47], v[200:203], v[60:63], v[32:47]
	s_nop 11
	v_exp_f32_e32 v32, v32
	v_exp_f32_e32 v33, v33
	v_exp_f32_e32 v34, v34
	v_exp_f32_e32 v35, v35
	v_exp_f32_e32 v36, v36
	v_exp_f32_e32 v37, v37
	v_exp_f32_e32 v38, v38
	v_exp_f32_e32 v39, v39
	v_exp_f32_e32 v40, v40
	v_exp_f32_e32 v41, v41
	v_exp_f32_e32 v42, v42
	v_exp_f32_e32 v43, v43
	v_exp_f32_e32 v44, v44
	v_exp_f32_e32 v45, v45
	v_exp_f32_e32 v46, v46
	v_exp_f32_e32 v47, v47
	v_cvt_pk_bf16_f32 v64, v32, v33
	v_cvt_pk_bf16_f32 v65, v34, v35
	v_cvt_pk_bf16_f32 v66, v36, v37
	v_cvt_pk_bf16_f32 v67, v38, v39
	v_cvt_pk_bf16_f32 v68, v40, v41
	v_cvt_pk_bf16_f32 v69, v42, v43
	v_cvt_pk_bf16_f32 v70, v44, v45
	v_cvt_pk_bf16_f32 v71, v46, v47
	v_pk_add_f32 v[232:233], v[232:233], v[32:33]
	v_pk_add_f32 v[232:233], v[232:233], v[34:35]
	v_pk_add_f32 v[232:233], v[232:233], v[36:37]
	v_pk_add_f32 v[232:233], v[232:233], v[38:39]
	v_pk_add_f32 v[232:233], v[232:233], v[40:41]
	v_pk_add_f32 v[232:233], v[232:233], v[42:43]
	v_pk_add_f32 v[232:233], v[232:233], v[44:45]
	v_pk_add_f32 v[232:233], v[232:233], v[46:47]
	s_waitcnt lgkmcnt(0)
	v_mfma_f32_32x32x16_bf16 v[0:15], v[64:67], v[72:75], v[0:15]
	v_mfma_f32_32x32x16_bf16 v[16:31], v[64:67], v[76:79], v[16:31]
	v_mfma_f32_32x32x16_bf16 v[0:15], v[68:71], v[220:223], v[0:15]
	v_mfma_f32_32x32x16_bf16 v[16:31], v[68:71], v[224:227], v[16:31]
	global_load_dwordx4 v[188:191], v239, s[86:87]
	global_load_dwordx4 v[192:195], v240, s[86:87]
	global_load_dwordx4 v[196:199], v241, s[86:87]
	global_load_dwordx4 v[200:203], v242, s[86:87]
	global_load_dwordx4 v[204:207], v101, s[86:87] offset:768
	global_load_dwordx4 v[208:211], v150, s[86:87] offset:768
	global_load_dwordx4 v[212:215], v101, s[86:87] offset:832
	global_load_dwordx4 v[216:219], v150, s[86:87] offset:832
	s_add_u32 s86, s86, 0xc0000
	s_addc_u32 s87, s87, 0
	s_waitcnt vmcnt(16)
	ds_write_b128 v247, v[116:119]
	ds_write_b128 v247, v[120:123] offset:1024
	ds_write_b128 v247, v[124:127] offset:2048
	ds_write_b128 v247, v[128:131] offset:3072
	ds_read_b128 v[116:119], v248
	ds_read_b128 v[120:123], v249
	ds_read_b128 v[124:127], v250
	ds_read_b128 v[128:131], v251
	ds_write_b128 v112, v[132:135]
	ds_write_b128 v112, v[136:139] offset:1024
	ds_write_b128 v112, v[140:143] offset:2048
	ds_write_b128 v112, v[144:147] offset:3072
	ds_read2_b32 v[32:33], v115 offset0:128 offset1:129
	ds_read2_b32 v[34:35], v115 offset0:130 offset1:131
	ds_read2_b32 v[36:37], v115 offset0:136 offset1:137
	ds_read2_b32 v[38:39], v115 offset0:138 offset1:139
	ds_read2_b32 v[40:41], v115 offset0:144 offset1:145
	ds_read2_b32 v[42:43], v115 offset0:146 offset1:147
	ds_read2_b32 v[44:45], v115 offset0:152 offset1:153
	ds_read2_b32 v[46:47], v115 offset0:154 offset1:155
	s_waitcnt lgkmcnt(0)
	v_mfma_f32_32x32x16_bf16 v[32:47], v[116:119], v[48:51], v[32:47]
	ds_read_b64_tr_b16 v[72:73], v231
	ds_read_b64_tr_b16 v[74:75], v231 offset:512
	ds_read_b64_tr_b16 v[76:77], v231 offset:2048
	ds_read_b64_tr_b16 v[78:79], v231 offset:2560
	ds_read_b64_tr_b16 v[220:221], v231 offset:1024
	ds_read_b64_tr_b16 v[222:223], v231 offset:1536
	ds_read_b64_tr_b16 v[224:225], v231 offset:3072
	ds_read_b64_tr_b16 v[226:227], v231 offset:3584
	v_mfma_f32_32x32x16_bf16 v[32:47], v[120:123], v[52:55], v[32:47]
	v_mfma_f32_32x32x16_bf16 v[32:47], v[124:127], v[56:59], v[32:47]
	v_mfma_f32_32x32x16_bf16 v[32:47], v[128:131], v[60:63], v[32:47]
	s_nop 11
	v_exp_f32_e32 v32, v32
	v_exp_f32_e32 v33, v33
	v_exp_f32_e32 v34, v34
	v_exp_f32_e32 v35, v35
	v_exp_f32_e32 v36, v36
	v_exp_f32_e32 v37, v37
	v_exp_f32_e32 v38, v38
	v_exp_f32_e32 v39, v39
	v_exp_f32_e32 v40, v40
	v_exp_f32_e32 v41, v41
	v_exp_f32_e32 v42, v42
	v_exp_f32_e32 v43, v43
	v_exp_f32_e32 v44, v44
	v_exp_f32_e32 v45, v45
	v_exp_f32_e32 v46, v46
	v_exp_f32_e32 v47, v47
	v_cvt_pk_bf16_f32 v64, v32, v33
	v_cvt_pk_bf16_f32 v65, v34, v35
	v_cvt_pk_bf16_f32 v66, v36, v37
	v_cvt_pk_bf16_f32 v67, v38, v39
	v_cvt_pk_bf16_f32 v68, v40, v41
	v_cvt_pk_bf16_f32 v69, v42, v43
	v_cvt_pk_bf16_f32 v70, v44, v45
	v_cvt_pk_bf16_f32 v71, v46, v47
	v_pk_add_f32 v[232:233], v[232:233], v[32:33]
	v_pk_add_f32 v[232:233], v[232:233], v[34:35]
	v_pk_add_f32 v[232:233], v[232:233], v[36:37]
	v_pk_add_f32 v[232:233], v[232:233], v[38:39]
	v_pk_add_f32 v[232:233], v[232:233], v[40:41]
	v_pk_add_f32 v[232:233], v[232:233], v[42:43]
	v_pk_add_f32 v[232:233], v[232:233], v[44:45]
	v_pk_add_f32 v[232:233], v[232:233], v[46:47]
	s_waitcnt lgkmcnt(0)
	v_mfma_f32_32x32x16_bf16 v[0:15], v[64:67], v[72:75], v[0:15]
	v_mfma_f32_32x32x16_bf16 v[16:31], v[64:67], v[76:79], v[16:31]
	v_mfma_f32_32x32x16_bf16 v[0:15], v[68:71], v[220:223], v[0:15]
	v_mfma_f32_32x32x16_bf16 v[16:31], v[68:71], v[224:227], v[16:31]
	global_load_dwordx4 v[116:119], v239, s[86:87]
	global_load_dwordx4 v[120:123], v240, s[86:87]
	global_load_dwordx4 v[124:127], v241, s[86:87]
	global_load_dwordx4 v[128:131], v242, s[86:87]
	global_load_dwordx4 v[132:135], v101, s[86:87] offset:768
	global_load_dwordx4 v[136:139], v150, s[86:87] offset:768
	global_load_dwordx4 v[140:143], v101, s[86:87] offset:832
	global_load_dwordx4 v[144:147], v150, s[86:87] offset:832
	s_waitcnt vmcnt(16)
	ds_write_b128 v247, v[156:159]
	ds_write_b128 v247, v[160:163] offset:1024
	ds_write_b128 v247, v[164:167] offset:2048
	ds_write_b128 v247, v[168:171] offset:3072
	ds_read_b128 v[156:159], v248
	ds_read_b128 v[160:163], v249
	ds_read_b128 v[164:167], v250
	ds_read_b128 v[168:171], v251
	ds_write_b128 v112, v[172:175]
	ds_write_b128 v112, v[176:179] offset:1024
	ds_write_b128 v112, v[180:183] offset:2048
	ds_write_b128 v112, v[184:187] offset:3072
	ds_read2_b32 v[32:33], v115 offset0:160 offset1:161
	ds_read2_b32 v[34:35], v115 offset0:162 offset1:163
	ds_read2_b32 v[36:37], v115 offset0:168 offset1:169
	ds_read2_b32 v[38:39], v115 offset0:170 offset1:171
	ds_read2_b32 v[40:41], v115 offset0:176 offset1:177
	ds_read2_b32 v[42:43], v115 offset0:178 offset1:179
	ds_read2_b32 v[44:45], v115 offset0:184 offset1:185
	ds_read2_b32 v[46:47], v115 offset0:186 offset1:187
	s_waitcnt lgkmcnt(0)
	v_mfma_f32_32x32x16_bf16 v[32:47], v[156:159], v[48:51], v[32:47]
	ds_read_b64_tr_b16 v[72:73], v231
	ds_read_b64_tr_b16 v[74:75], v231 offset:512
	ds_read_b64_tr_b16 v[76:77], v231 offset:2048
	ds_read_b64_tr_b16 v[78:79], v231 offset:2560
	ds_read_b64_tr_b16 v[220:221], v231 offset:1024
	ds_read_b64_tr_b16 v[222:223], v231 offset:1536
	ds_read_b64_tr_b16 v[224:225], v231 offset:3072
	ds_read_b64_tr_b16 v[226:227], v231 offset:3584
	v_mfma_f32_32x32x16_bf16 v[32:47], v[160:163], v[52:55], v[32:47]
	v_mfma_f32_32x32x16_bf16 v[32:47], v[164:167], v[56:59], v[32:47]
	v_mfma_f32_32x32x16_bf16 v[32:47], v[168:171], v[60:63], v[32:47]
	s_nop 11
	v_exp_f32_e32 v32, v32
	v_exp_f32_e32 v33, v33
	v_exp_f32_e32 v34, v34
	v_exp_f32_e32 v35, v35
	v_exp_f32_e32 v36, v36
	v_exp_f32_e32 v37, v37
	v_exp_f32_e32 v38, v38
	v_exp_f32_e32 v39, v39
	v_exp_f32_e32 v40, v40
	v_exp_f32_e32 v41, v41
	v_exp_f32_e32 v42, v42
	v_exp_f32_e32 v43, v43
	v_exp_f32_e32 v44, v44
	v_exp_f32_e32 v45, v45
	v_exp_f32_e32 v46, v46
	v_exp_f32_e32 v47, v47
	v_cvt_pk_bf16_f32 v64, v32, v33
	v_cvt_pk_bf16_f32 v65, v34, v35
	v_cvt_pk_bf16_f32 v66, v36, v37
	v_cvt_pk_bf16_f32 v67, v38, v39
	v_cvt_pk_bf16_f32 v68, v40, v41
	v_cvt_pk_bf16_f32 v69, v42, v43
	v_cvt_pk_bf16_f32 v70, v44, v45
	v_cvt_pk_bf16_f32 v71, v46, v47
	v_pk_add_f32 v[232:233], v[232:233], v[32:33]
	v_pk_add_f32 v[232:233], v[232:233], v[34:35]
	v_pk_add_f32 v[232:233], v[232:233], v[36:37]
	v_pk_add_f32 v[232:233], v[232:233], v[38:39]
	v_pk_add_f32 v[232:233], v[232:233], v[40:41]
	v_pk_add_f32 v[232:233], v[232:233], v[42:43]
	v_pk_add_f32 v[232:233], v[232:233], v[44:45]
	v_pk_add_f32 v[232:233], v[232:233], v[46:47]
	s_waitcnt lgkmcnt(0)
	v_mfma_f32_32x32x16_bf16 v[0:15], v[64:67], v[72:75], v[0:15]
	v_mfma_f32_32x32x16_bf16 v[16:31], v[64:67], v[76:79], v[16:31]
	v_mfma_f32_32x32x16_bf16 v[0:15], v[68:71], v[220:223], v[0:15]
	v_mfma_f32_32x32x16_bf16 v[16:31], v[68:71], v[224:227], v[16:31]
	global_load_dwordx4 v[156:159], v243, s[88:89]
	global_load_dwordx4 v[160:163], v244, s[88:89]
	global_load_dwordx4 v[164:167], v245, s[88:89]
	global_load_dwordx4 v[168:171], v246, s[88:89]
	global_load_dwordx4 v[172:175], v148, s[88:89] offset:768
	global_load_dwordx4 v[176:179], v151, s[88:89] offset:768
	global_load_dwordx4 v[180:183], v148, s[88:89] offset:832
	global_load_dwordx4 v[184:187], v151, s[88:89] offset:832
	s_add_u32 s88, s88, 0x300000
	s_addc_u32 s89, s89, 0
	s_waitcnt vmcnt(16)
	ds_write_b128 v247, v[188:191]
	ds_write_b128 v247, v[192:195] offset:1024
	ds_write_b128 v247, v[196:199] offset:2048
	ds_write_b128 v247, v[200:203] offset:3072
	ds_read_b128 v[188:191], v248
	ds_read_b128 v[192:195], v249
	ds_read_b128 v[196:199], v250
	ds_read_b128 v[200:203], v251
	ds_write_b128 v112, v[204:207]
	ds_write_b128 v112, v[208:211] offset:1024
	ds_write_b128 v112, v[212:215] offset:2048
	ds_write_b128 v112, v[216:219] offset:3072
	ds_read2_b32 v[32:33], v115 offset0:192 offset1:193
	ds_read2_b32 v[34:35], v115 offset0:194 offset1:195
	ds_read2_b32 v[36:37], v115 offset0:200 offset1:201
	ds_read2_b32 v[38:39], v115 offset0:202 offset1:203
	ds_read2_b32 v[40:41], v115 offset0:208 offset1:209
	ds_read2_b32 v[42:43], v115 offset0:210 offset1:211
	ds_read2_b32 v[44:45], v115 offset0:216 offset1:217
	ds_read2_b32 v[46:47], v115 offset0:218 offset1:219
	s_waitcnt lgkmcnt(0)
	v_mfma_f32_32x32x16_bf16 v[32:47], v[188:191], v[48:51], v[32:47]
	ds_read_b64_tr_b16 v[72:73], v231
	ds_read_b64_tr_b16 v[74:75], v231 offset:512
	ds_read_b64_tr_b16 v[76:77], v231 offset:2048
	ds_read_b64_tr_b16 v[78:79], v231 offset:2560
	ds_read_b64_tr_b16 v[220:221], v231 offset:1024
	ds_read_b64_tr_b16 v[222:223], v231 offset:1536
	ds_read_b64_tr_b16 v[224:225], v231 offset:3072
	ds_read_b64_tr_b16 v[226:227], v231 offset:3584
	v_mfma_f32_32x32x16_bf16 v[32:47], v[192:195], v[52:55], v[32:47]
	v_mfma_f32_32x32x16_bf16 v[32:47], v[196:199], v[56:59], v[32:47]
	v_mfma_f32_32x32x16_bf16 v[32:47], v[200:203], v[60:63], v[32:47]
	s_nop 11
	v_exp_f32_e32 v32, v32
	v_exp_f32_e32 v33, v33
	v_exp_f32_e32 v34, v34
	v_exp_f32_e32 v35, v35
	v_exp_f32_e32 v36, v36
	v_exp_f32_e32 v37, v37
	v_exp_f32_e32 v38, v38
	v_exp_f32_e32 v39, v39
	v_exp_f32_e32 v40, v40
	v_exp_f32_e32 v41, v41
	v_exp_f32_e32 v42, v42
	v_exp_f32_e32 v43, v43
	v_exp_f32_e32 v44, v44
	v_exp_f32_e32 v45, v45
	v_exp_f32_e32 v46, v46
	v_exp_f32_e32 v47, v47
	v_cvt_pk_bf16_f32 v64, v32, v33
	v_cvt_pk_bf16_f32 v65, v34, v35
	v_cvt_pk_bf16_f32 v66, v36, v37
	v_cvt_pk_bf16_f32 v67, v38, v39
	v_cvt_pk_bf16_f32 v68, v40, v41
	v_cvt_pk_bf16_f32 v69, v42, v43
	v_cvt_pk_bf16_f32 v70, v44, v45
	v_cvt_pk_bf16_f32 v71, v46, v47
	v_pk_add_f32 v[232:233], v[232:233], v[32:33]
	v_pk_add_f32 v[232:233], v[232:233], v[34:35]
	v_pk_add_f32 v[232:233], v[232:233], v[36:37]
	v_pk_add_f32 v[232:233], v[232:233], v[38:39]
	v_pk_add_f32 v[232:233], v[232:233], v[40:41]
	v_pk_add_f32 v[232:233], v[232:233], v[42:43]
	v_pk_add_f32 v[232:233], v[232:233], v[44:45]
	v_pk_add_f32 v[232:233], v[232:233], v[46:47]
	s_waitcnt lgkmcnt(0)
	v_mfma_f32_32x32x16_bf16 v[0:15], v[64:67], v[72:75], v[0:15]
	v_mfma_f32_32x32x16_bf16 v[16:31], v[64:67], v[76:79], v[16:31]
	v_mfma_f32_32x32x16_bf16 v[0:15], v[68:71], v[220:223], v[0:15]
	v_mfma_f32_32x32x16_bf16 v[16:31], v[68:71], v[224:227], v[16:31]
	global_load_dwordx4 v[188:191], v243, s[88:89]
	global_load_dwordx4 v[192:195], v244, s[88:89]
	global_load_dwordx4 v[196:199], v245, s[88:89]
	global_load_dwordx4 v[200:203], v246, s[88:89]
	global_load_dwordx4 v[204:207], v148, s[88:89] offset:768
	global_load_dwordx4 v[208:211], v151, s[88:89] offset:768
	global_load_dwordx4 v[212:215], v148, s[88:89] offset:832
	global_load_dwordx4 v[216:219], v151, s[88:89] offset:832
	s_add_u32 s88, s88, 0x300000
	s_addc_u32 s89, s89, 0
	s_waitcnt vmcnt(16)
	ds_write_b128 v247, v[116:119]
	ds_write_b128 v247, v[120:123] offset:1024
	ds_write_b128 v247, v[124:127] offset:2048
	ds_write_b128 v247, v[128:131] offset:3072
	ds_read_b128 v[116:119], v248
	ds_read_b128 v[120:123], v249
	ds_read_b128 v[124:127], v250
	ds_read_b128 v[128:131], v251
	ds_write_b128 v112, v[132:135]
	ds_write_b128 v112, v[136:139] offset:1024
	ds_write_b128 v112, v[140:143] offset:2048
	ds_write_b128 v112, v[144:147] offset:3072
	ds_read2_b32 v[32:33], v115 offset0:224 offset1:225
	ds_read2_b32 v[34:35], v115 offset0:226 offset1:227
	ds_read2_b32 v[36:37], v115 offset0:232 offset1:233
	ds_read2_b32 v[38:39], v115 offset0:234 offset1:235
	ds_read2_b32 v[40:41], v115 offset0:240 offset1:241
	ds_read2_b32 v[42:43], v115 offset0:242 offset1:243
	ds_read2_b32 v[44:45], v115 offset0:248 offset1:249
	ds_read2_b32 v[46:47], v115 offset0:250 offset1:251
	s_waitcnt lgkmcnt(0)
	v_mfma_f32_32x32x16_bf16 v[32:47], v[116:119], v[48:51], v[32:47]
	ds_read_b64_tr_b16 v[72:73], v231
	ds_read_b64_tr_b16 v[74:75], v231 offset:512
	ds_read_b64_tr_b16 v[76:77], v231 offset:2048
	ds_read_b64_tr_b16 v[78:79], v231 offset:2560
	ds_read_b64_tr_b16 v[220:221], v231 offset:1024
	ds_read_b64_tr_b16 v[222:223], v231 offset:1536
	ds_read_b64_tr_b16 v[224:225], v231 offset:3072
	ds_read_b64_tr_b16 v[226:227], v231 offset:3584
	v_mfma_f32_32x32x16_bf16 v[32:47], v[120:123], v[52:55], v[32:47]
	v_mfma_f32_32x32x16_bf16 v[32:47], v[124:127], v[56:59], v[32:47]
	v_mfma_f32_32x32x16_bf16 v[32:47], v[128:131], v[60:63], v[32:47]
	s_nop 11
	v_exp_f32_e32 v32, v32
	v_exp_f32_e32 v33, v33
	v_exp_f32_e32 v34, v34
	v_exp_f32_e32 v35, v35
	v_exp_f32_e32 v36, v36
	v_exp_f32_e32 v37, v37
	v_exp_f32_e32 v38, v38
	v_exp_f32_e32 v39, v39
	v_exp_f32_e32 v40, v40
	v_exp_f32_e32 v41, v41
	v_exp_f32_e32 v42, v42
	v_exp_f32_e32 v43, v43
	v_exp_f32_e32 v44, v44
	v_exp_f32_e32 v45, v45
	v_exp_f32_e32 v46, v46
	v_exp_f32_e32 v47, v47
	v_cvt_pk_bf16_f32 v64, v32, v33
	v_cvt_pk_bf16_f32 v65, v34, v35
	v_cvt_pk_bf16_f32 v66, v36, v37
	v_cvt_pk_bf16_f32 v67, v38, v39
	v_cvt_pk_bf16_f32 v68, v40, v41
	v_cvt_pk_bf16_f32 v69, v42, v43
	v_cvt_pk_bf16_f32 v70, v44, v45
	v_cvt_pk_bf16_f32 v71, v46, v47
	v_pk_add_f32 v[232:233], v[232:233], v[32:33]
	v_pk_add_f32 v[232:233], v[232:233], v[34:35]
	v_pk_add_f32 v[232:233], v[232:233], v[36:37]
	v_pk_add_f32 v[232:233], v[232:233], v[38:39]
	v_pk_add_f32 v[232:233], v[232:233], v[40:41]
	v_pk_add_f32 v[232:233], v[232:233], v[42:43]
	v_pk_add_f32 v[232:233], v[232:233], v[44:45]
	v_pk_add_f32 v[232:233], v[232:233], v[46:47]
	s_waitcnt lgkmcnt(0)
	v_mfma_f32_32x32x16_bf16 v[0:15], v[64:67], v[72:75], v[0:15]
	v_mfma_f32_32x32x16_bf16 v[16:31], v[64:67], v[76:79], v[16:31]
	v_mfma_f32_32x32x16_bf16 v[0:15], v[68:71], v[220:223], v[0:15]
	v_mfma_f32_32x32x16_bf16 v[16:31], v[68:71], v[224:227], v[16:31]
	global_load_dwordx4 v[116:119], v243, s[88:89]
	global_load_dwordx4 v[120:123], v244, s[88:89]
	global_load_dwordx4 v[124:127], v245, s[88:89]
	global_load_dwordx4 v[128:131], v246, s[88:89]
	global_load_dwordx4 v[132:135], v148, s[88:89] offset:768
	global_load_dwordx4 v[136:139], v151, s[88:89] offset:768
	global_load_dwordx4 v[140:143], v148, s[88:89] offset:832
	global_load_dwordx4 v[144:147], v151, s[88:89] offset:832
	s_add_u32 s88, s88, 0x300000
	s_addc_u32 s89, s89, 0
	s_waitcnt vmcnt(16)
	ds_write_b128 v247, v[156:159]
	ds_write_b128 v247, v[160:163] offset:1024
	ds_write_b128 v247, v[164:167] offset:2048
	ds_write_b128 v247, v[168:171] offset:3072
	ds_read_b128 v[156:159], v248
	ds_read_b128 v[160:163], v249
	ds_read_b128 v[164:167], v250
	ds_read_b128 v[168:171], v251
	ds_write_b128 v112, v[172:175]
	ds_write_b128 v112, v[176:179] offset:1024
	ds_write_b128 v112, v[180:183] offset:2048
	ds_write_b128 v112, v[184:187] offset:3072
	v_mov_b32_e32 v115, v230
	ds_read2_b32 v[32:33], v115 offset0:0 offset1:1
	ds_read2_b32 v[34:35], v115 offset0:2 offset1:3
	ds_read2_b32 v[36:37], v115 offset0:8 offset1:9
	ds_read2_b32 v[38:39], v115 offset0:10 offset1:11
	ds_read2_b32 v[40:41], v115 offset0:16 offset1:17
	ds_read2_b32 v[42:43], v115 offset0:18 offset1:19
	ds_read2_b32 v[44:45], v115 offset0:24 offset1:25
	ds_read2_b32 v[46:47], v115 offset0:26 offset1:27
	s_waitcnt lgkmcnt(0)
	v_mfma_f32_32x32x16_bf16 v[32:47], v[156:159], v[48:51], v[32:47]
	ds_read_b64_tr_b16 v[72:73], v231
	ds_read_b64_tr_b16 v[74:75], v231 offset:512
	ds_read_b64_tr_b16 v[76:77], v231 offset:2048
	ds_read_b64_tr_b16 v[78:79], v231 offset:2560
	ds_read_b64_tr_b16 v[220:221], v231 offset:1024
	ds_read_b64_tr_b16 v[222:223], v231 offset:1536
	ds_read_b64_tr_b16 v[224:225], v231 offset:3072
	ds_read_b64_tr_b16 v[226:227], v231 offset:3584
	v_mfma_f32_32x32x16_bf16 v[32:47], v[160:163], v[52:55], v[32:47]
	v_mfma_f32_32x32x16_bf16 v[32:47], v[164:167], v[56:59], v[32:47]
	v_mfma_f32_32x32x16_bf16 v[32:47], v[168:171], v[60:63], v[32:47]
	s_nop 11
	v_exp_f32_e32 v32, v32
	v_exp_f32_e32 v33, v33
	v_exp_f32_e32 v34, v34
	v_exp_f32_e32 v35, v35
	v_exp_f32_e32 v36, v36
	v_exp_f32_e32 v37, v37
	v_exp_f32_e32 v38, v38
	v_exp_f32_e32 v39, v39
	v_exp_f32_e32 v40, v40
	v_exp_f32_e32 v41, v41
	v_exp_f32_e32 v42, v42
	v_exp_f32_e32 v43, v43
	v_exp_f32_e32 v44, v44
	v_exp_f32_e32 v45, v45
	v_exp_f32_e32 v46, v46
	v_exp_f32_e32 v47, v47
	v_cvt_pk_bf16_f32 v64, v32, v33
	v_cvt_pk_bf16_f32 v65, v34, v35
	v_cvt_pk_bf16_f32 v66, v36, v37
	v_cvt_pk_bf16_f32 v67, v38, v39
	v_cvt_pk_bf16_f32 v68, v40, v41
	v_cvt_pk_bf16_f32 v69, v42, v43
	v_cvt_pk_bf16_f32 v70, v44, v45
	v_cvt_pk_bf16_f32 v71, v46, v47
	v_pk_add_f32 v[232:233], v[232:233], v[32:33]
	v_pk_add_f32 v[232:233], v[232:233], v[34:35]
	v_pk_add_f32 v[232:233], v[232:233], v[36:37]
	v_pk_add_f32 v[232:233], v[232:233], v[38:39]
	v_pk_add_f32 v[232:233], v[232:233], v[40:41]
	v_pk_add_f32 v[232:233], v[232:233], v[42:43]
	v_pk_add_f32 v[232:233], v[232:233], v[44:45]
	v_pk_add_f32 v[232:233], v[232:233], v[46:47]
	s_waitcnt lgkmcnt(0)
	v_mfma_f32_32x32x16_bf16 v[0:15], v[64:67], v[72:75], v[0:15]
	v_mfma_f32_32x32x16_bf16 v[16:31], v[64:67], v[76:79], v[16:31]
	v_mfma_f32_32x32x16_bf16 v[0:15], v[68:71], v[220:223], v[0:15]
	v_mfma_f32_32x32x16_bf16 v[16:31], v[68:71], v[224:227], v[16:31]
	global_load_dwordx4 v[156:159], v243, s[88:89]
	global_load_dwordx4 v[160:163], v244, s[88:89]
	global_load_dwordx4 v[164:167], v245, s[88:89]
	global_load_dwordx4 v[168:171], v246, s[88:89]
	global_load_dwordx4 v[172:175], v148, s[88:89] offset:768
	global_load_dwordx4 v[176:179], v151, s[88:89] offset:768
	global_load_dwordx4 v[180:183], v148, s[88:89] offset:832
	global_load_dwordx4 v[184:187], v151, s[88:89] offset:832
	s_add_u32 s88, s88, 0x300000
	s_addc_u32 s89, s89, 0
	s_waitcnt vmcnt(16)
	ds_write_b128 v247, v[188:191]
	ds_write_b128 v247, v[192:195] offset:1024
	ds_write_b128 v247, v[196:199] offset:2048
	ds_write_b128 v247, v[200:203] offset:3072
	ds_read_b128 v[188:191], v248
	ds_read_b128 v[192:195], v249
	ds_read_b128 v[196:199], v250
	ds_read_b128 v[200:203], v251
	ds_write_b128 v112, v[204:207]
	ds_write_b128 v112, v[208:211] offset:1024
	ds_write_b128 v112, v[212:215] offset:2048
	ds_write_b128 v112, v[216:219] offset:3072
	ds_read2_b32 v[32:33], v115 offset0:32 offset1:33
	ds_read2_b32 v[34:35], v115 offset0:34 offset1:35
	ds_read2_b32 v[36:37], v115 offset0:40 offset1:41
	ds_read2_b32 v[38:39], v115 offset0:42 offset1:43
	ds_read2_b32 v[40:41], v115 offset0:48 offset1:49
	ds_read2_b32 v[42:43], v115 offset0:50 offset1:51
	ds_read2_b32 v[44:45], v115 offset0:56 offset1:57
	ds_read2_b32 v[46:47], v115 offset0:58 offset1:59
	s_waitcnt lgkmcnt(0)
	v_mfma_f32_32x32x16_bf16 v[32:47], v[188:191], v[48:51], v[32:47]
	ds_read_b64_tr_b16 v[72:73], v231
	ds_read_b64_tr_b16 v[74:75], v231 offset:512
	ds_read_b64_tr_b16 v[76:77], v231 offset:2048
	ds_read_b64_tr_b16 v[78:79], v231 offset:2560
	ds_read_b64_tr_b16 v[220:221], v231 offset:1024
	ds_read_b64_tr_b16 v[222:223], v231 offset:1536
	ds_read_b64_tr_b16 v[224:225], v231 offset:3072
	ds_read_b64_tr_b16 v[226:227], v231 offset:3584
	v_mfma_f32_32x32x16_bf16 v[32:47], v[192:195], v[52:55], v[32:47]
	v_mfma_f32_32x32x16_bf16 v[32:47], v[196:199], v[56:59], v[32:47]
	v_mfma_f32_32x32x16_bf16 v[32:47], v[200:203], v[60:63], v[32:47]
	s_nop 11
	v_exp_f32_e32 v32, v32
	v_exp_f32_e32 v33, v33
	v_exp_f32_e32 v34, v34
	v_exp_f32_e32 v35, v35
	v_exp_f32_e32 v36, v36
	v_exp_f32_e32 v37, v37
	v_exp_f32_e32 v38, v38
	v_exp_f32_e32 v39, v39
	v_exp_f32_e32 v40, v40
	v_exp_f32_e32 v41, v41
	v_exp_f32_e32 v42, v42
	v_exp_f32_e32 v43, v43
	v_exp_f32_e32 v44, v44
	v_exp_f32_e32 v45, v45
	v_exp_f32_e32 v46, v46
	v_exp_f32_e32 v47, v47
	v_cvt_pk_bf16_f32 v64, v32, v33
	v_cvt_pk_bf16_f32 v65, v34, v35
	v_cvt_pk_bf16_f32 v66, v36, v37
	v_cvt_pk_bf16_f32 v67, v38, v39
	v_cvt_pk_bf16_f32 v68, v40, v41
	v_cvt_pk_bf16_f32 v69, v42, v43
	v_cvt_pk_bf16_f32 v70, v44, v45
	v_cvt_pk_bf16_f32 v71, v46, v47
	v_pk_add_f32 v[232:233], v[232:233], v[32:33]
	v_pk_add_f32 v[232:233], v[232:233], v[34:35]
	v_pk_add_f32 v[232:233], v[232:233], v[36:37]
	v_pk_add_f32 v[232:233], v[232:233], v[38:39]
	v_pk_add_f32 v[232:233], v[232:233], v[40:41]
	v_pk_add_f32 v[232:233], v[232:233], v[42:43]
	v_pk_add_f32 v[232:233], v[232:233], v[44:45]
	v_pk_add_f32 v[232:233], v[232:233], v[46:47]
	s_waitcnt lgkmcnt(0)
	v_mfma_f32_32x32x16_bf16 v[0:15], v[64:67], v[72:75], v[0:15]
	v_mfma_f32_32x32x16_bf16 v[16:31], v[64:67], v[76:79], v[16:31]
	v_mfma_f32_32x32x16_bf16 v[0:15], v[68:71], v[220:223], v[0:15]
	v_mfma_f32_32x32x16_bf16 v[16:31], v[68:71], v[224:227], v[16:31]
	global_load_dwordx4 v[188:191], v243, s[88:89]
	global_load_dwordx4 v[192:195], v244, s[88:89]
	global_load_dwordx4 v[196:199], v245, s[88:89]
	global_load_dwordx4 v[200:203], v246, s[88:89]
	global_load_dwordx4 v[204:207], v148, s[88:89] offset:768
	global_load_dwordx4 v[208:211], v151, s[88:89] offset:768
	global_load_dwordx4 v[212:215], v148, s[88:89] offset:832
	global_load_dwordx4 v[216:219], v151, s[88:89] offset:832
	s_waitcnt vmcnt(16)
	ds_write_b128 v247, v[116:119]
	ds_write_b128 v247, v[120:123] offset:1024
	ds_write_b128 v247, v[124:127] offset:2048
	ds_write_b128 v247, v[128:131] offset:3072
	ds_read_b128 v[116:119], v248
	ds_read_b128 v[120:123], v249
	ds_read_b128 v[124:127], v250
	ds_read_b128 v[128:131], v251
	ds_write_b128 v112, v[132:135]
	ds_write_b128 v112, v[136:139] offset:1024
	ds_write_b128 v112, v[140:143] offset:2048
	ds_write_b128 v112, v[144:147] offset:3072
	ds_read2_b32 v[32:33], v115 offset0:64 offset1:65
	ds_read2_b32 v[34:35], v115 offset0:66 offset1:67
	ds_read2_b32 v[36:37], v115 offset0:72 offset1:73
	ds_read2_b32 v[38:39], v115 offset0:74 offset1:75
	ds_read2_b32 v[40:41], v115 offset0:80 offset1:81
	ds_read2_b32 v[42:43], v115 offset0:82 offset1:83
	ds_read2_b32 v[44:45], v115 offset0:88 offset1:89
	ds_read2_b32 v[46:47], v115 offset0:90 offset1:91
	s_waitcnt lgkmcnt(0)
	v_mfma_f32_32x32x16_bf16 v[32:47], v[116:119], v[48:51], v[32:47]
	ds_read_b64_tr_b16 v[72:73], v231
	ds_read_b64_tr_b16 v[74:75], v231 offset:512
	ds_read_b64_tr_b16 v[76:77], v231 offset:2048
	ds_read_b64_tr_b16 v[78:79], v231 offset:2560
	ds_read_b64_tr_b16 v[220:221], v231 offset:1024
	ds_read_b64_tr_b16 v[222:223], v231 offset:1536
	ds_read_b64_tr_b16 v[224:225], v231 offset:3072
	ds_read_b64_tr_b16 v[226:227], v231 offset:3584
	v_mfma_f32_32x32x16_bf16 v[32:47], v[120:123], v[52:55], v[32:47]
	v_mfma_f32_32x32x16_bf16 v[32:47], v[124:127], v[56:59], v[32:47]
	v_mfma_f32_32x32x16_bf16 v[32:47], v[128:131], v[60:63], v[32:47]
	s_nop 11
	v_exp_f32_e32 v32, v32
	v_exp_f32_e32 v33, v33
	v_exp_f32_e32 v34, v34
	v_exp_f32_e32 v35, v35
	v_exp_f32_e32 v36, v36
	v_exp_f32_e32 v37, v37
	v_exp_f32_e32 v38, v38
	v_exp_f32_e32 v39, v39
	v_exp_f32_e32 v40, v40
	v_exp_f32_e32 v41, v41
	v_exp_f32_e32 v42, v42
	v_exp_f32_e32 v43, v43
	v_exp_f32_e32 v44, v44
	v_exp_f32_e32 v45, v45
	v_exp_f32_e32 v46, v46
	v_exp_f32_e32 v47, v47
	v_cvt_pk_bf16_f32 v64, v32, v33
	v_cvt_pk_bf16_f32 v65, v34, v35
	v_cvt_pk_bf16_f32 v66, v36, v37
	v_cvt_pk_bf16_f32 v67, v38, v39
	v_cvt_pk_bf16_f32 v68, v40, v41
	v_cvt_pk_bf16_f32 v69, v42, v43
	v_cvt_pk_bf16_f32 v70, v44, v45
	v_cvt_pk_bf16_f32 v71, v46, v47
	v_pk_add_f32 v[232:233], v[232:233], v[32:33]
	v_pk_add_f32 v[232:233], v[232:233], v[34:35]
	v_pk_add_f32 v[232:233], v[232:233], v[36:37]
	v_pk_add_f32 v[232:233], v[232:233], v[38:39]
	v_pk_add_f32 v[232:233], v[232:233], v[40:41]
	v_pk_add_f32 v[232:233], v[232:233], v[42:43]
	v_pk_add_f32 v[232:233], v[232:233], v[44:45]
	v_pk_add_f32 v[232:233], v[232:233], v[46:47]
	s_waitcnt lgkmcnt(0)
	v_mfma_f32_32x32x16_bf16 v[0:15], v[64:67], v[72:75], v[0:15]
	v_mfma_f32_32x32x16_bf16 v[16:31], v[64:67], v[76:79], v[16:31]
	v_mfma_f32_32x32x16_bf16 v[0:15], v[68:71], v[220:223], v[0:15]
	v_mfma_f32_32x32x16_bf16 v[16:31], v[68:71], v[224:227], v[16:31]
	s_waitcnt vmcnt(8)
	ds_write_b128 v247, v[156:159]
	ds_write_b128 v247, v[160:163] offset:1024
	ds_write_b128 v247, v[164:167] offset:2048
	ds_write_b128 v247, v[168:171] offset:3072
	ds_read_b128 v[156:159], v248
	ds_read_b128 v[160:163], v249
	ds_read_b128 v[164:167], v250
	ds_read_b128 v[168:171], v251
	ds_write_b128 v112, v[172:175]
	ds_write_b128 v112, v[176:179] offset:1024
	ds_write_b128 v112, v[180:183] offset:2048
	ds_write_b128 v112, v[184:187] offset:3072
	ds_read2_b32 v[32:33], v115 offset0:96 offset1:97
	ds_read2_b32 v[34:35], v115 offset0:98 offset1:99
	ds_read2_b32 v[36:37], v115 offset0:104 offset1:105
	ds_read2_b32 v[38:39], v115 offset0:106 offset1:107
	ds_read2_b32 v[40:41], v115 offset0:112 offset1:113
	ds_read2_b32 v[42:43], v115 offset0:114 offset1:115
	ds_read2_b32 v[44:45], v115 offset0:120 offset1:121
	ds_read2_b32 v[46:47], v115 offset0:122 offset1:123
	s_waitcnt lgkmcnt(0)
; __device__ __forceinline__ int crow(int r, int hi) { return (r & 3) + 8 * (r >> 2) + 4 * hi; }
; __device__ __forceinline__ void dil_unit(LAS unsigned char* lds, bf16_t* proj, int seq, int hd, int T0, int rho) {
;     ...
;     l += __shfl_xor(l, 32);
; #pragma unroll
;     for (int rr = 0; rr < 16; ++rr) {
;         const int j = crow(rr, hi);
	v_mfma_f32_32x32x16_bf16 v[32:47], v[156:159], v[48:51], v[32:47]
	ds_read_b64_tr_b16 v[72:73], v231
	ds_read_b64_tr_b16 v[74:75], v231 offset:512
	ds_read_b64_tr_b16 v[76:77], v231 offset:2048
	ds_read_b64_tr_b16 v[78:79], v231 offset:2560
	ds_read_b64_tr_b16 v[220:221], v231 offset:1024
	ds_read_b64_tr_b16 v[222:223], v231 offset:1536
	ds_read_b64_tr_b16 v[224:225], v231 offset:3072
	ds_read_b64_tr_b16 v[226:227], v231 offset:3584
	v_mfma_f32_32x32x16_bf16 v[32:47], v[160:163], v[52:55], v[32:47]
	v_mfma_f32_32x32x16_bf16 v[32:47], v[164:167], v[56:59], v[32:47]
	v_mfma_f32_32x32x16_bf16 v[32:47], v[168:171], v[60:63], v[32:47]
	s_nop 11
	v_exp_f32_e32 v32, v32
	v_exp_f32_e32 v33, v33
	v_exp_f32_e32 v34, v34
	v_exp_f32_e32 v35, v35
	v_exp_f32_e32 v36, v36
	v_exp_f32_e32 v37, v37
	v_exp_f32_e32 v38, v38
	v_exp_f32_e32 v39, v39
	v_exp_f32_e32 v40, v40
	v_exp_f32_e32 v41, v41
	v_exp_f32_e32 v42, v42
	v_exp_f32_e32 v43, v43
	v_exp_f32_e32 v44, v44
	v_exp_f32_e32 v45, v45
	v_exp_f32_e32 v46, v46
	v_exp_f32_e32 v47, v47
	v_cvt_pk_bf16_f32 v64, v32, v33
	v_cvt_pk_bf16_f32 v65, v34, v35
	v_cvt_pk_bf16_f32 v66, v36, v37
	v_cvt_pk_bf16_f32 v67, v38, v39
	v_cvt_pk_bf16_f32 v68, v40, v41
	v_cvt_pk_bf16_f32 v69, v42, v43
	v_cvt_pk_bf16_f32 v70, v44, v45
	v_cvt_pk_bf16_f32 v71, v46, v47
	v_pk_add_f32 v[232:233], v[232:233], v[32:33]
	v_pk_add_f32 v[232:233], v[232:233], v[34:35]
	v_pk_add_f32 v[232:233], v[232:233], v[36:37]
	v_pk_add_f32 v[232:233], v[232:233], v[38:39]
	v_pk_add_f32 v[232:233], v[232:233], v[40:41]
	v_pk_add_f32 v[232:233], v[232:233], v[42:43]
	v_pk_add_f32 v[232:233], v[232:233], v[44:45]
	v_pk_add_f32 v[232:233], v[232:233], v[46:47]
	s_waitcnt lgkmcnt(0)
	v_mfma_f32_32x32x16_bf16 v[0:15], v[64:67], v[72:75], v[0:15]
	v_mfma_f32_32x32x16_bf16 v[16:31], v[64:67], v[76:79], v[16:31]
	v_mfma_f32_32x32x16_bf16 v[0:15], v[68:71], v[220:223], v[0:15]
	v_mfma_f32_32x32x16_bf16 v[16:31], v[68:71], v[224:227], v[16:31]
	s_waitcnt vmcnt(0)
	ds_write_b128 v247, v[188:191]
	ds_write_b128 v247, v[192:195] offset:1024
	ds_write_b128 v247, v[196:199] offset:2048
	ds_write_b128 v247, v[200:203] offset:3072
	ds_read_b128 v[188:191], v248
	ds_read_b128 v[192:195], v249
	ds_read_b128 v[196:199], v250
	ds_read_b128 v[200:203], v251
	ds_write_b128 v112, v[204:207]
	ds_write_b128 v112, v[208:211] offset:1024
	ds_write_b128 v112, v[212:215] offset:2048
	ds_write_b128 v112, v[216:219] offset:3072
	ds_read2_b32 v[32:33], v115 offset0:128 offset1:129
	ds_read2_b32 v[34:35], v115 offset0:130 offset1:131
	ds_read2_b32 v[36:37], v115 offset0:136 offset1:137
	ds_read2_b32 v[38:39], v115 offset0:138 offset1:139
	ds_read2_b32 v[40:41], v115 offset0:144 offset1:145
	ds_read2_b32 v[42:43], v115 offset0:146 offset1:147
	ds_read2_b32 v[44:45], v115 offset0:152 offset1:153
	ds_read2_b32 v[46:47], v115 offset0:154 offset1:155
	s_waitcnt lgkmcnt(0)
	v_mfma_f32_32x32x16_bf16 v[32:47], v[188:191], v[48:51], v[32:47]
	ds_read_b64_tr_b16 v[72:73], v231
	ds_read_b64_tr_b16 v[74:75], v231 offset:512
	ds_read_b64_tr_b16 v[76:77], v231 offset:2048
	ds_read_b64_tr_b16 v[78:79], v231 offset:2560
	ds_read_b64_tr_b16 v[220:221], v231 offset:1024
	ds_read_b64_tr_b16 v[222:223], v231 offset:1536
	ds_read_b64_tr_b16 v[224:225], v231 offset:3072
	ds_read_b64_tr_b16 v[226:227], v231 offset:3584
	v_mfma_f32_32x32x16_bf16 v[32:47], v[192:195], v[52:55], v[32:47]
	v_mfma_f32_32x32x16_bf16 v[32:47], v[196:199], v[56:59], v[32:47]
	v_mfma_f32_32x32x16_bf16 v[32:47], v[200:203], v[60:63], v[32:47]
	s_nop 11
	v_exp_f32_e32 v32, v32
	v_exp_f32_e32 v33, v33
	v_exp_f32_e32 v34, v34
	v_exp_f32_e32 v35, v35
	v_exp_f32_e32 v36, v36
	v_exp_f32_e32 v37, v37
	v_exp_f32_e32 v38, v38
	v_exp_f32_e32 v39, v39
	v_exp_f32_e32 v40, v40
	v_exp_f32_e32 v41, v41
	v_exp_f32_e32 v42, v42
	v_exp_f32_e32 v43, v43
	v_exp_f32_e32 v44, v44
	v_exp_f32_e32 v45, v45
	v_exp_f32_e32 v46, v46
	v_exp_f32_e32 v47, v47
	v_cvt_pk_bf16_f32 v64, v32, v33
	v_cvt_pk_bf16_f32 v65, v34, v35
	v_cvt_pk_bf16_f32 v66, v36, v37
	v_cvt_pk_bf16_f32 v67, v38, v39
	v_cvt_pk_bf16_f32 v68, v40, v41
	v_cvt_pk_bf16_f32 v69, v42, v43
	v_cvt_pk_bf16_f32 v70, v44, v45
	v_cvt_pk_bf16_f32 v71, v46, v47
	v_pk_add_f32 v[232:233], v[232:233], v[32:33]
	v_pk_add_f32 v[232:233], v[232:233], v[34:35]
	v_pk_add_f32 v[232:233], v[232:233], v[36:37]
	v_pk_add_f32 v[232:233], v[232:233], v[38:39]
	v_pk_add_f32 v[232:233], v[232:233], v[40:41]
	v_pk_add_f32 v[232:233], v[232:233], v[42:43]
	v_pk_add_f32 v[232:233], v[232:233], v[44:45]
	v_pk_add_f32 v[232:233], v[232:233], v[46:47]
	s_waitcnt lgkmcnt(0)
	v_mfma_f32_32x32x16_bf16 v[0:15], v[64:67], v[72:75], v[0:15]
	v_mfma_f32_32x32x16_bf16 v[16:31], v[64:67], v[76:79], v[16:31]
	v_mfma_f32_32x32x16_bf16 v[0:15], v[68:71], v[220:223], v[0:15]
	v_mfma_f32_32x32x16_bf16 v[16:31], v[68:71], v[224:227], v[16:31]
	v_add_f32_e32 v113, v232, v233
	v_or_b32_e32 v114, 1, v107
	v_or_b32_e32 v97, 2, v107
	v_or_b32_e32 v96, 3, v107
	v_or_b32_e32 v95, 8, v107
	v_or_b32_e32 v94, 9, v107
	v_or_b32_e32 v93, 10, v107
	v_or_b32_e32 v92, 11, v107
	v_or_b32_e32 v91, 16, v107
	v_or_b32_e32 v90, 17, v107
	v_or_b32_e32 v89, 18, v107
	v_or_b32_e32 v88, 19, v107
	v_or_b32_e32 v87, 24, v107
	v_or_b32_e32 v86, 25, v107
	v_or_b32_e32 v85, 26, v107
	v_or_b32_e32 v84, 27, v107
	s_nop 11
	s_branch .LBB0_1265
